# delete the 32 redundant s_waitcnt lgkmcnt(0) that follow s_barrier; s_setprio 1 at the head of every MFMA segment (counter already 0: the same wait precedes the barrier); on top of v63
# speedup vs baseline: 1.0147x; 1.0097x over previous
;     __host__ __device__ __forceinline__ bool next(int i, Unit& u) const { const int vv = vid + (i / 5) * G; if (vv >= 256) return false; u.pm = vv >> 2; u.pn = (vv & 3) + 4 * (i % 5); return true; }
; #define PG8_STAGE(bufoff, gbase, voff) do { _Pragma("unroll") for (int _i = 0; _i < 2; ++_i) \
;         __builtin_amdgcn_global_load_lds((const unsigned*)((const char*)(gbase) + (voff)[_i]), (PG8_LAS unsigned*)(lds + (bufoff) + ldsw + _i * 8192), 16, 0, 0); } while (0)
; #define PG8_LDA(dst, b, h) do { _Pragma("unroll") for (int m = 0; m < 4; ++m) _Pragma("unroll") for (int k = 0; k < 2; ++k) dst[m][k] = *(const PG8_LAS bf16x8*)(lds + PG8_SA(b, h) + aoff + m * 2048 + k * 1024); } while (0)
; #define PG8_LDB(dst, b, h) do { _Pragma("unroll") for (int n = 0; n < 2; ++n) _Pragma("unroll") for (int k = 0; k < 2; ++k) dst[n][k] = *(const PG8_LAS bf16x8*)(lds + PG8_SB(b, h) + boff + n * 2048 + k * 1024); } while (0)
; #define PG8_WAIT_V(n) asm volatile("s_waitcnt vmcnt(" #n ")" ::: "memory")
;     ...
;         const bool has_next = S.next(ui + 1, nxt);
;         const char* nA = has_next ? (const char*)g.A + (size_t)nxt.pm * tstepA + (size_t)nxt.pn * APN + kofA : cA; const char* nB = has_next ? (const char*)g.Bt + (size_t)nxt.pn * tstepB + S.b_off(nxt) + kofB : cB;
;         for (int t = 0; t < nt; t += 2) {
;             const bool last = (t == nt - 2);
;             const char* a1 = cA + (ptrdiff_t)(t + 1) * kstepA;
;             const char* a2 = last ? nA : cA + (ptrdiff_t)(t + 2) * kstepA; const char* b2 = last ? nB : cB + (ptrdiff_t)(t + 2) * kstep;
;             const char* a3 = a2 + kstepA; const char* b3 = b2 + kstep;
;             if (last && has_next) S.a_ready(nxt);
;             if constexpr (SP2) {
;             PG8_LDB(B0, 0, 0); PG8_LDB(B1, 0, 1); PG8_SCHED; PG8_LDA(At, 0, 0); PG8_STAGE(PG8_SA(1, 1), a1 + hstepA, voffA);
;             PG8_WAIT_V(8); PG8_WAIT_L(0); PG8_BAR; PG8_MMA(0, 0, At, B0); PG8_MMA(0, 1, At, B1); PG8_BAR; PG8_SCHED;
;             PG8_LDA(At, 0, 1); PG8_STAGE(PG8_SB(0, 0), b2, voffB); PG8_STAGE(PG8_SB(0, 1), b2 + hstepB, voffB); PG8_STAGE(PG8_SA(0, 0), a2, voffA);
;             PG8_WAIT_V(8); PG8_WAIT_L(0); PG8_BAR; PG8_MMA(1, 0, At, B0); PG8_MMA(1, 1, At, B1); PG8_BAR; PG8_SCHED;
;     __device__ __forceinline__ size_t b_off(const pg8::Unit& u) const { return (size_t)(u.pm >> 3) * 4 * 131072; }
.LBB0_97:
	s_mov_b64 s[30:31], s[6:7]
	s_ashr_i32 s6, s14, 2
	s_and_b32 s6, s6, -8
	s_and_b32 s7, s14, 7
	s_mov_b32 s20, s58
	s_mov_b32 s21, s57
	v_cmp_lt_i64_e64 s[4:5], s[14:15], v[138:139]
	s_bfe_u32 s57, s14, 0x20003
	s_or_b32 s58, s6, s7
	s_and_b64 s[6:7], s[4:5], exec
	s_cselect_b32 s24, s58, s20
	s_cselect_b32 s6, s57, s21
	s_ashr_i32 s25, s24, 31
	s_lshl_b64 s[20:21], s[24:25], 20
	s_add_u32 s20, s2, s20
	s_addc_u32 s21, s3, s21
	s_ashr_i32 s7, s6, 31
	s_lshl_b64 s[6:7], s[6:7], 17
	s_add_u32 s20, s20, s6
	s_addc_u32 s21, s21, s7
	s_and_b64 s[28:29], s[4:5], exec
	ds_read_b128 v[0:3], v141
	ds_read_b128 v[4:7], v141 offset:1024
	ds_read_b128 v[8:11], v141 offset:2048
	ds_read_b128 v[12:15], v141 offset:3072
	ds_read_b128 v[16:19], v142
	ds_read_b128 v[20:23], v142 offset:1024
	ds_read_b128 v[24:27], v142 offset:2048
	ds_read_b128 v[28:31], v142 offset:3072
	s_cselect_b32 s29, s21, s27
	s_cselect_b32 s28, s20, s26
	s_add_u32 s25, s33, s6
	s_addc_u32 s34, s36, s7
	s_ashr_i32 s6, s24, 3
	s_ashr_i32 s7, s6, 31
	s_lshl_b64 s[6:7], s[6:7], 19
	s_add_u32 s6, s25, s6
	s_addc_u32 s7, s34, s7
	s_and_b64 s[24:25], s[4:5], exec
	s_cselect_b32 s25, s7, s31
	s_cselect_b32 s24, s6, s30
	s_add_u32 s60, s26, 0x10000
	s_addc_u32 s61, s27, 0
	s_add_u32 s34, s26, 0x18000
	s_addc_u32 s35, s27, 0
	s_add_u32 s62, s26, 0xc000
	s_addc_u32 s63, s27, 0
	s_mov_b32 m0, s46
	ds_read_b128 v[32:35], v143
	ds_read_b128 v[36:39], v143 offset:1024
	ds_read_b128 v[40:43], v143 offset:2048
	ds_read_b128 v[44:47], v143 offset:3072
	ds_read_b128 v[48:51], v143 offset:4096
	ds_read_b128 v[52:55], v143 offset:5120
	ds_read_b128 v[56:59], v143 offset:6144
	ds_read_b128 v[60:63], v143 offset:7168
	global_load_lds_dwordx4 v134, s[62:63]
	v_lshl_add_u64 v[64:65], s[62:63], 0, v[130:131]
	s_mov_b32 m0, s47
	s_nop 0
	global_load_lds_dwordx4 v[64:65], off
	s_waitcnt vmcnt(8)
	s_waitcnt lgkmcnt(0)
	s_barrier
	s_setprio 1
	v_mfma_f32_16x16x32_bf16 v[64:67], v[0:3], v[32:35], 0
	v_mfma_f32_16x16x32_bf16 v[64:67], v[4:7], v[36:39], v[64:67]
	v_mfma_f32_16x16x32_bf16 v[68:71], v[8:11], v[32:35], 0
	v_mfma_f32_16x16x32_bf16 v[68:71], v[12:15], v[36:39], v[68:71]
	v_mfma_f32_16x16x32_bf16 v[72:75], v[0:3], v[40:43], 0
	v_mfma_f32_16x16x32_bf16 v[72:75], v[4:7], v[44:47], v[72:75]
	v_mfma_f32_16x16x32_bf16 v[76:79], v[8:11], v[40:43], 0
	v_mfma_f32_16x16x32_bf16 v[76:79], v[12:15], v[44:47], v[76:79]
	v_mfma_f32_16x16x32_bf16 v[80:83], v[0:3], v[48:51], 0
	v_mfma_f32_16x16x32_bf16 v[80:83], v[4:7], v[52:55], v[80:83]
	v_mfma_f32_16x16x32_bf16 v[84:87], v[8:11], v[48:51], 0
	v_mfma_f32_16x16x32_bf16 v[84:87], v[12:15], v[52:55], v[84:87]
	v_mfma_f32_16x16x32_bf16 v[88:91], v[0:3], v[56:59], 0
	v_mfma_f32_16x16x32_bf16 v[88:91], v[4:7], v[60:63], v[88:91]
	v_mfma_f32_16x16x32_bf16 v[92:95], v[8:11], v[56:59], 0
	v_mfma_f32_16x16x32_bf16 v[92:95], v[12:15], v[60:63], v[92:95]
	s_setprio 0
	s_setprio 1
	v_mfma_f32_16x16x32_bf16 v[96:99], v[16:19], v[32:35], 0
	v_mfma_f32_16x16x32_bf16 v[96:99], v[20:23], v[36:39], v[96:99]
	v_mfma_f32_16x16x32_bf16 v[32:35], v[24:27], v[32:35], 0
	v_mfma_f32_16x16x32_bf16 v[32:35], v[28:31], v[36:39], v[32:35]
	v_mfma_f32_16x16x32_bf16 v[36:39], v[16:19], v[40:43], 0
	v_mfma_f32_16x16x32_bf16 v[36:39], v[20:23], v[44:47], v[36:39]
	v_mfma_f32_16x16x32_bf16 v[40:43], v[24:27], v[40:43], 0
	v_mfma_f32_16x16x32_bf16 v[40:43], v[28:31], v[44:47], v[40:43]
	v_mfma_f32_16x16x32_bf16 v[44:47], v[16:19], v[48:51], 0
	v_mfma_f32_16x16x32_bf16 v[44:47], v[20:23], v[52:55], v[44:47]
	v_mfma_f32_16x16x32_bf16 v[48:51], v[24:27], v[48:51], 0
	v_mfma_f32_16x16x32_bf16 v[48:51], v[28:31], v[52:55], v[48:51]
	v_mfma_f32_16x16x32_bf16 v[52:55], v[16:19], v[56:59], 0
	v_mfma_f32_16x16x32_bf16 v[52:55], v[20:23], v[60:63], v[52:55]
	v_mfma_f32_16x16x32_bf16 v[56:59], v[24:27], v[56:59], 0
	v_mfma_f32_16x16x32_bf16 v[56:59], v[28:31], v[60:63], v[56:59]
	s_setprio 0
	s_barrier
	v_lshl_add_u64 v[210:211], s[30:31], 0, v[132:133]
	s_mov_b32 m0, s48
	v_lshl_add_u64 v[146:147], v[210:211], 0, s[16:17]
	v_lshl_add_u64 v[212:213], s[30:31], 0, v[128:129]
	s_add_u32 s62, s30, 0x10100
	ds_read_b128 v[60:63], v143 offset:16384
	ds_read_b128 v[100:103], v143 offset:17408
	ds_read_b128 v[104:107], v143 offset:18432
	ds_read_b128 v[108:111], v143 offset:19456
	ds_read_b128 v[112:115], v143 offset:20480
	ds_read_b128 v[116:119], v143 offset:21504
	ds_read_b128 v[120:123], v143 offset:22528
	ds_read_b128 v[124:127], v143 offset:23552
	global_load_lds_dwordx4 v[146:147], off
	v_lshl_add_u64 v[146:147], v[212:213], 0, s[16:17]
	s_mov_b32 m0, s50
	s_addc_u32 s63, s31, 0
	global_load_lds_dwordx4 v[146:147], off
	s_mov_b32 m0, s51
	s_nop 0
	global_load_lds_dwordx4 v132, s[62:63]
	s_mov_b32 m0, s52
	s_nop 0
	global_load_lds_dwordx4 v128, s[62:63]
	s_mov_b32 m0, s23
	s_nop 0
	global_load_lds_dwordx4 v134, s[60:61]
	v_lshl_add_u64 v[146:147], s[60:61], 0, v[130:131]
	s_mov_b32 m0, s37
	s_nop 0
	global_load_lds_dwordx4 v[146:147], off
	s_waitcnt vmcnt(8)
	s_waitcnt lgkmcnt(0)
	s_barrier
; #define PG8_STAGE(bufoff, gbase, voff) do { _Pragma("unroll") for (int _i = 0; _i < 2; ++_i) \
;         __builtin_amdgcn_global_load_lds((const unsigned*)((const char*)(gbase) + (voff)[_i]), (PG8_LAS unsigned*)(lds + (bufoff) + ldsw + _i * 8192), 16, 0, 0); } while (0)
; #define PG8_LDA(dst, b, h) do { _Pragma("unroll") for (int m = 0; m < 4; ++m) _Pragma("unroll") for (int k = 0; k < 2; ++k) dst[m][k] = *(const PG8_LAS bf16x8*)(lds + PG8_SA(b, h) + aoff + m * 2048 + k * 1024); } while (0)
; #define PG8_LDB(dst, b, h) do { _Pragma("unroll") for (int n = 0; n < 2; ++n) _Pragma("unroll") for (int k = 0; k < 2; ++k) dst[n][k] = *(const PG8_LAS bf16x8*)(lds + PG8_SB(b, h) + boff + n * 2048 + k * 1024); } while (0)
; #define PG8_MMA(ai, bj, At, Bt) do { __builtin_amdgcn_s_setprio(1); _Pragma("unroll") for (int m = 0; m < 4; ++m) _Pragma("unroll") for (int n = 0; n < 2; ++n) _Pragma("unroll") for (int k = 0; k < 2; ++k) \
;         acc[ai][bj][m][n] = __builtin_amdgcn_mfma_f32_16x16x32_bf16(Bt[n][k], At[m][k], acc[ai][bj][m][n], 0, 0, 0); __builtin_amdgcn_s_setprio(0); } while (0)
; #define PG8_WAIT_V(n) asm volatile("s_waitcnt vmcnt(" #n ")" ::: "memory")
; #define PG8_WAIT_L(n) asm volatile("s_waitcnt lgkmcnt(" #n ")" ::: "memory")
; #define PG8_BAR __builtin_amdgcn_s_barrier()
;     ...
;             if constexpr (SP2) {
;             PG8_LDB(B0, 0, 0); PG8_LDB(B1, 0, 1); PG8_SCHED; PG8_LDA(At, 0, 0); PG8_STAGE(PG8_SA(1, 1), a1 + hstepA, voffA);
;             PG8_WAIT_V(8); PG8_WAIT_L(0); PG8_BAR; PG8_MMA(0, 0, At, B0); PG8_MMA(0, 1, At, B1); PG8_BAR; PG8_SCHED;
;             PG8_LDA(At, 0, 1); PG8_STAGE(PG8_SB(0, 0), b2, voffB); PG8_STAGE(PG8_SB(0, 1), b2 + hstepB, voffB); PG8_STAGE(PG8_SA(0, 0), a2, voffA);
;             PG8_WAIT_V(8); PG8_WAIT_L(0); PG8_BAR; PG8_MMA(1, 0, At, B0); PG8_MMA(1, 1, At, B1); PG8_BAR; PG8_SCHED;
;             PG8_LDB(B0, 1, 0); PG8_LDB(B1, 1, 1); PG8_SCHED; PG8_LDA(At, 1, 0); PG8_STAGE(PG8_SA(0, 1), a2 + hstepA, voffA);
;             PG8_WAIT_V(8); PG8_WAIT_L(0); PG8_BAR; PG8_MMA(0, 0, At, B0); PG8_MMA(0, 1, At, B1); PG8_BAR; PG8_SCHED;
;             PG8_LDA(At, 1, 1); PG8_STAGE(PG8_SB(1, 0), b3, voffB); PG8_STAGE(PG8_SB(1, 1), b3 + hstepB, voffB); PG8_STAGE(PG8_SA(1, 0), a3, voffA);
;             PG8_WAIT_V(8); PG8_WAIT_L(0); PG8_BAR; PG8_MMA(1, 0, At, B0); PG8_MMA(1, 1, At, B1); PG8_BAR; PG8_SCHED;
	s_setprio 1
	v_mfma_f32_16x16x32_bf16 v[146:149], v[0:3], v[60:63], 0
	v_mfma_f32_16x16x32_bf16 v[146:149], v[4:7], v[100:103], v[146:149]
	v_mfma_f32_16x16x32_bf16 v[154:157], v[0:3], v[104:107], 0
	v_mfma_f32_16x16x32_bf16 v[154:157], v[4:7], v[108:111], v[154:157]
	v_mfma_f32_16x16x32_bf16 v[162:165], v[0:3], v[112:115], 0
	v_mfma_f32_16x16x32_bf16 v[162:165], v[4:7], v[116:119], v[162:165]
	v_mfma_f32_16x16x32_bf16 v[0:3], v[0:3], v[120:123], 0
	v_mfma_f32_16x16x32_bf16 v[0:3], v[4:7], v[124:127], v[0:3]
	v_mfma_f32_16x16x32_bf16 v[4:7], v[8:11], v[120:123], 0
	v_mfma_f32_16x16x32_bf16 v[4:7], v[12:15], v[124:127], v[4:7]
	v_mfma_f32_16x16x32_bf16 v[150:153], v[8:11], v[60:63], 0
	v_mfma_f32_16x16x32_bf16 v[150:153], v[12:15], v[100:103], v[150:153]
	v_mfma_f32_16x16x32_bf16 v[158:161], v[8:11], v[104:107], 0
	v_mfma_f32_16x16x32_bf16 v[158:161], v[12:15], v[108:111], v[158:161]
	v_mfma_f32_16x16x32_bf16 v[166:169], v[8:11], v[112:115], 0
	v_mfma_f32_16x16x32_bf16 v[166:169], v[12:15], v[116:119], v[166:169]
	s_setprio 0
	s_setprio 1
	v_mfma_f32_16x16x32_bf16 v[8:11], v[16:19], v[60:63], 0
	v_mfma_f32_16x16x32_bf16 v[8:11], v[20:23], v[100:103], v[8:11]
	v_mfma_f32_16x16x32_bf16 v[12:15], v[24:27], v[60:63], 0
	v_mfma_f32_16x16x32_bf16 v[12:15], v[28:31], v[100:103], v[12:15]
	v_mfma_f32_16x16x32_bf16 v[60:63], v[16:19], v[104:107], 0
	v_mfma_f32_16x16x32_bf16 v[60:63], v[20:23], v[108:111], v[60:63]
	v_mfma_f32_16x16x32_bf16 v[100:103], v[24:27], v[104:107], 0
	v_mfma_f32_16x16x32_bf16 v[100:103], v[28:31], v[108:111], v[100:103]
	v_mfma_f32_16x16x32_bf16 v[104:107], v[16:19], v[112:115], 0
	v_mfma_f32_16x16x32_bf16 v[104:107], v[20:23], v[116:119], v[104:107]
	v_mfma_f32_16x16x32_bf16 v[16:19], v[16:19], v[120:123], 0
	v_mfma_f32_16x16x32_bf16 v[16:19], v[20:23], v[124:127], v[16:19]
	v_mfma_f32_16x16x32_bf16 v[108:111], v[24:27], v[112:115], 0
	v_mfma_f32_16x16x32_bf16 v[108:111], v[28:31], v[116:119], v[108:111]
	v_mfma_f32_16x16x32_bf16 v[20:23], v[24:27], v[120:123], 0
	v_mfma_f32_16x16x32_bf16 v[20:23], v[28:31], v[124:127], v[20:23]
	s_setprio 0
	s_barrier
	ds_read_b128 v[24:27], v144
	ds_read_b128 v[28:31], v144 offset:1024
	ds_read_b128 v[112:115], v144 offset:2048
	ds_read_b128 v[116:119], v144 offset:3072
	ds_read_b128 v[120:123], v145
	ds_read_b128 v[124:127], v145 offset:1024
	ds_read_b128 v[170:173], v145 offset:2048
	ds_read_b128 v[174:177], v145 offset:3072
	s_add_u32 s60, s26, 0x14000
	s_addc_u32 s61, s27, 0
	s_mov_b32 m0, s39
	ds_read_b128 v[178:181], v143 offset:32768
	ds_read_b128 v[182:185], v143 offset:33792
	ds_read_b128 v[186:189], v143 offset:34816
	ds_read_b128 v[190:193], v143 offset:35840
	ds_read_b128 v[194:197], v143 offset:36864
	ds_read_b128 v[198:201], v143 offset:37888
	ds_read_b128 v[202:205], v143 offset:38912
	ds_read_b128 v[206:209], v143 offset:39936
	global_load_lds_dwordx4 v134, s[60:61]
	v_lshl_add_u64 v[214:215], s[60:61], 0, v[130:131]
	s_mov_b32 m0, s40
	s_nop 0
	global_load_lds_dwordx4 v[214:215], off
	s_waitcnt vmcnt(8)
	s_waitcnt lgkmcnt(0)
	s_barrier
	s_setprio 1
	v_mfma_f32_16x16x32_bf16 v[64:67], v[24:27], v[178:181], v[64:67]
	v_mfma_f32_16x16x32_bf16 v[64:67], v[28:31], v[182:185], v[64:67]
	v_mfma_f32_16x16x32_bf16 v[68:71], v[116:119], v[182:185], v[68:71]
	v_mfma_f32_16x16x32_bf16 v[68:71], v[112:115], v[178:181], v[68:71]
	v_mfma_f32_16x16x32_bf16 v[76:79], v[112:115], v[186:189], v[76:79]
	v_mfma_f32_16x16x32_bf16 v[76:79], v[116:119], v[190:193], v[76:79]
	v_mfma_f32_16x16x32_bf16 v[72:75], v[28:31], v[190:193], v[72:75]
	v_mfma_f32_16x16x32_bf16 v[72:75], v[24:27], v[186:189], v[72:75]
	v_mfma_f32_16x16x32_bf16 v[80:83], v[24:27], v[194:197], v[80:83]
	v_mfma_f32_16x16x32_bf16 v[80:83], v[28:31], v[198:201], v[80:83]
	v_mfma_f32_16x16x32_bf16 v[84:87], v[116:119], v[198:201], v[84:87]
	v_mfma_f32_16x16x32_bf16 v[84:87], v[112:115], v[194:197], v[84:87]
	v_mfma_f32_16x16x32_bf16 v[92:95], v[112:115], v[202:205], v[92:95]
	v_mfma_f32_16x16x32_bf16 v[92:95], v[116:119], v[206:209], v[92:95]
	v_mfma_f32_16x16x32_bf16 v[88:91], v[28:31], v[206:209], v[88:91]
	v_mfma_f32_16x16x32_bf16 v[88:91], v[24:27], v[202:205], v[88:91]
	s_setprio 0
	s_setprio 1
	v_mfma_f32_16x16x32_bf16 v[96:99], v[120:123], v[178:181], v[96:99]
	v_mfma_f32_16x16x32_bf16 v[96:99], v[124:127], v[182:185], v[96:99]
	v_mfma_f32_16x16x32_bf16 v[32:35], v[174:177], v[182:185], v[32:35]
	v_mfma_f32_16x16x32_bf16 v[32:35], v[170:173], v[178:181], v[32:35]
	v_mfma_f32_16x16x32_bf16 v[40:43], v[170:173], v[186:189], v[40:43]
	v_mfma_f32_16x16x32_bf16 v[40:43], v[174:177], v[190:193], v[40:43]
	v_mfma_f32_16x16x32_bf16 v[36:39], v[124:127], v[190:193], v[36:39]
	v_mfma_f32_16x16x32_bf16 v[36:39], v[120:123], v[186:189], v[36:39]
	v_mfma_f32_16x16x32_bf16 v[44:47], v[120:123], v[194:197], v[44:47]
	v_mfma_f32_16x16x32_bf16 v[44:47], v[124:127], v[198:201], v[44:47]
	v_mfma_f32_16x16x32_bf16 v[48:51], v[174:177], v[198:201], v[48:51]
	v_mfma_f32_16x16x32_bf16 v[48:51], v[170:173], v[194:197], v[48:51]
	v_mfma_f32_16x16x32_bf16 v[56:59], v[170:173], v[202:205], v[56:59]
	v_mfma_f32_16x16x32_bf16 v[56:59], v[174:177], v[206:209], v[56:59]
	v_mfma_f32_16x16x32_bf16 v[52:55], v[124:127], v[206:209], v[52:55]
	v_mfma_f32_16x16x32_bf16 v[52:55], v[120:123], v[202:205], v[52:55]
	s_setprio 0
	s_barrier
; #define PG8_STAGE(bufoff, gbase, voff) do { _Pragma("unroll") for (int _i = 0; _i < 2; ++_i) \
;         __builtin_amdgcn_global_load_lds((const unsigned*)((const char*)(gbase) + (voff)[_i]), (PG8_LAS unsigned*)(lds + (bufoff) + ldsw + _i * 8192), 16, 0, 0); } while (0)
; #define PG8_LDA(dst, b, h) do { _Pragma("unroll") for (int m = 0; m < 4; ++m) _Pragma("unroll") for (int k = 0; k < 2; ++k) dst[m][k] = *(const PG8_LAS bf16x8*)(lds + PG8_SA(b, h) + aoff + m * 2048 + k * 1024); } while (0)
; #define PG8_LDB(dst, b, h) do { _Pragma("unroll") for (int n = 0; n < 2; ++n) _Pragma("unroll") for (int k = 0; k < 2; ++k) dst[n][k] = *(const PG8_LAS bf16x8*)(lds + PG8_SB(b, h) + boff + n * 2048 + k * 1024); } while (0)
; #define PG8_MMA(ai, bj, At, Bt) do { __builtin_amdgcn_s_setprio(1); _Pragma("unroll") for (int m = 0; m < 4; ++m) _Pragma("unroll") for (int n = 0; n < 2; ++n) _Pragma("unroll") for (int k = 0; k < 2; ++k) \
;         acc[ai][bj][m][n] = __builtin_amdgcn_mfma_f32_16x16x32_bf16(Bt[n][k], At[m][k], acc[ai][bj][m][n], 0, 0, 0); __builtin_amdgcn_s_setprio(0); } while (0)
; #define PG8_WAIT_V(n) asm volatile("s_waitcnt vmcnt(" #n ")" ::: "memory")
; #define PG8_WAIT_L(n) asm volatile("s_waitcnt lgkmcnt(" #n ")" ::: "memory")
; #define PG8_BAR __builtin_amdgcn_s_barrier()
;     ...
;             if constexpr (SP2) {
;             PG8_LDB(B0, 0, 0); PG8_LDB(B1, 0, 1); PG8_SCHED; PG8_LDA(At, 0, 0); PG8_STAGE(PG8_SA(1, 1), a1 + hstepA, voffA);
;             PG8_WAIT_V(8); PG8_WAIT_L(0); PG8_BAR; PG8_MMA(0, 0, At, B0); PG8_MMA(0, 1, At, B1); PG8_BAR; PG8_SCHED;
;             PG8_LDA(At, 0, 1); PG8_STAGE(PG8_SB(0, 0), b2, voffB); PG8_STAGE(PG8_SB(0, 1), b2 + hstepB, voffB); PG8_STAGE(PG8_SA(0, 0), a2, voffA);
;             PG8_WAIT_V(8); PG8_WAIT_L(0); PG8_BAR; PG8_MMA(1, 0, At, B0); PG8_MMA(1, 1, At, B1); PG8_BAR; PG8_SCHED;
;             PG8_LDB(B0, 1, 0); PG8_LDB(B1, 1, 1); PG8_SCHED; PG8_LDA(At, 1, 0); PG8_STAGE(PG8_SA(0, 1), a2 + hstepA, voffA);
;             PG8_WAIT_V(8); PG8_WAIT_L(0); PG8_BAR; PG8_MMA(0, 0, At, B0); PG8_MMA(0, 1, At, B1); PG8_BAR; PG8_SCHED;
;             PG8_LDA(At, 1, 1); PG8_STAGE(PG8_SB(1, 0), b3, voffB); PG8_STAGE(PG8_SB(1, 1), b3 + hstepB, voffB); PG8_STAGE(PG8_SA(1, 0), a3, voffA);
;             PG8_WAIT_V(8); PG8_WAIT_L(0); PG8_BAR; PG8_MMA(1, 0, At, B0); PG8_MMA(1, 1, At, B1); PG8_BAR; PG8_SCHED;
	s_mov_b32 m0, s53
	v_lshl_add_u64 v[210:211], v[210:211], 0, s[18:19]
	s_add_u32 s30, s30, 0x10180
	ds_read_b128 v[178:181], v143 offset:49152
	ds_read_b128 v[182:185], v143 offset:50176
	ds_read_b128 v[186:189], v143 offset:51200
	ds_read_b128 v[190:193], v143 offset:52224
	ds_read_b128 v[194:197], v143 offset:53248
	ds_read_b128 v[198:201], v143 offset:54272
	ds_read_b128 v[202:205], v143 offset:55296
	ds_read_b128 v[206:209], v143 offset:56320
	global_load_lds_dwordx4 v[210:211], off
	v_lshl_add_u64 v[210:211], v[212:213], 0, s[18:19]
	s_mov_b32 m0, s54
	s_addc_u32 s31, s31, 0
	global_load_lds_dwordx4 v[210:211], off
	s_mov_b32 m0, s55
	s_nop 0
	global_load_lds_dwordx4 v132, s[30:31]
	s_mov_b32 m0, s56
	s_nop 0
	global_load_lds_dwordx4 v128, s[30:31]
	s_mov_b32 m0, s42
	s_nop 0
	global_load_lds_dwordx4 v134, s[34:35]
	s_mov_b32 m0, s43
	s_nop 0
	global_load_lds_dwordx4 v130, s[34:35]
	s_waitcnt vmcnt(8)
	s_waitcnt lgkmcnt(0)
	s_barrier
	s_setprio 1
	v_mfma_f32_16x16x32_bf16 v[0:3], v[24:27], v[202:205], v[0:3]
	v_mfma_f32_16x16x32_bf16 v[0:3], v[28:31], v[206:209], v[0:3]
	v_mfma_f32_16x16x32_bf16 v[4:7], v[116:119], v[206:209], v[4:7]
	v_mfma_f32_16x16x32_bf16 v[4:7], v[112:115], v[202:205], v[4:7]
	v_mfma_f32_16x16x32_bf16 v[150:153], v[112:115], v[178:181], v[150:153]
	v_mfma_f32_16x16x32_bf16 v[150:153], v[116:119], v[182:185], v[150:153]
	v_mfma_f32_16x16x32_bf16 v[146:149], v[28:31], v[182:185], v[146:149]
	v_mfma_f32_16x16x32_bf16 v[146:149], v[24:27], v[178:181], v[146:149]
	v_mfma_f32_16x16x32_bf16 v[154:157], v[24:27], v[186:189], v[154:157]
	v_mfma_f32_16x16x32_bf16 v[154:157], v[28:31], v[190:193], v[154:157]
	v_mfma_f32_16x16x32_bf16 v[158:161], v[116:119], v[190:193], v[158:161]
	v_mfma_f32_16x16x32_bf16 v[158:161], v[112:115], v[186:189], v[158:161]
	v_mfma_f32_16x16x32_bf16 v[166:169], v[112:115], v[194:197], v[166:169]
	v_mfma_f32_16x16x32_bf16 v[166:169], v[116:119], v[198:201], v[166:169]
	v_mfma_f32_16x16x32_bf16 v[162:165], v[28:31], v[198:201], v[162:165]
	v_mfma_f32_16x16x32_bf16 v[162:165], v[24:27], v[194:197], v[162:165]
	s_setprio 0
	s_setprio 1
	v_mfma_f32_16x16x32_bf16 v[8:11], v[120:123], v[178:181], v[8:11]
	v_mfma_f32_16x16x32_bf16 v[8:11], v[124:127], v[182:185], v[8:11]
	v_mfma_f32_16x16x32_bf16 v[12:15], v[170:173], v[178:181], v[12:15]
	v_mfma_f32_16x16x32_bf16 v[12:15], v[174:177], v[182:185], v[12:15]
	v_mfma_f32_16x16x32_bf16 v[24:27], v[120:123], v[186:189], v[60:63]
	v_mfma_f32_16x16x32_bf16 v[24:27], v[124:127], v[190:193], v[24:27]
	v_mfma_f32_16x16x32_bf16 v[28:31], v[170:173], v[186:189], v[100:103]
	v_mfma_f32_16x16x32_bf16 v[28:31], v[174:177], v[190:193], v[28:31]
	v_mfma_f32_16x16x32_bf16 v[60:63], v[120:123], v[194:197], v[104:107]
	v_mfma_f32_16x16x32_bf16 v[60:63], v[124:127], v[198:201], v[60:63]
	v_mfma_f32_16x16x32_bf16 v[100:103], v[170:173], v[194:197], v[108:111]
	v_mfma_f32_16x16x32_bf16 v[100:103], v[174:177], v[198:201], v[100:103]
	v_mfma_f32_16x16x32_bf16 v[16:19], v[120:123], v[202:205], v[16:19]
	v_mfma_f32_16x16x32_bf16 v[16:19], v[124:127], v[206:209], v[16:19]
	v_mfma_f32_16x16x32_bf16 v[20:23], v[170:173], v[202:205], v[20:23]
	v_mfma_f32_16x16x32_bf16 v[20:23], v[174:177], v[206:209], v[20:23]
	s_setprio 0
	s_barrier
	ds_read_b128 v[104:107], v141
	ds_read_b128 v[108:111], v141 offset:1024
	ds_read_b128 v[112:115], v141 offset:2048
	ds_read_b128 v[116:119], v141 offset:3072
	ds_read_b128 v[120:123], v142
	ds_read_b128 v[124:127], v142 offset:1024
	ds_read_b128 v[170:173], v142 offset:2048
	ds_read_b128 v[174:177], v142 offset:3072
	s_add_u32 s30, s28, 0x8000
	s_addc_u32 s31, s29, 0
	s_add_u32 s26, s26, 0x1c000
	s_addc_u32 s27, s27, 0
	s_mov_b32 m0, s46
	ds_read_b128 v[178:181], v143
	ds_read_b128 v[182:185], v143 offset:1024
	ds_read_b128 v[186:189], v143 offset:2048
	ds_read_b128 v[190:193], v143 offset:3072
	ds_read_b128 v[194:197], v143 offset:4096
	ds_read_b128 v[198:201], v143 offset:5120
	ds_read_b128 v[202:205], v143 offset:6144
	ds_read_b128 v[206:209], v143 offset:7168
	global_load_lds_dwordx4 v134, s[26:27]
	v_lshl_add_u64 v[210:211], s[26:27], 0, v[130:131]
	s_mov_b32 m0, s47
	s_nop 0
	global_load_lds_dwordx4 v[210:211], off
	s_waitcnt vmcnt(8)
	s_waitcnt lgkmcnt(0)
	s_barrier
	s_setprio 1
	v_mfma_f32_16x16x32_bf16 v[64:67], v[104:107], v[178:181], v[64:67]
	v_mfma_f32_16x16x32_bf16 v[64:67], v[108:111], v[182:185], v[64:67]
	v_mfma_f32_16x16x32_bf16 v[68:71], v[112:115], v[178:181], v[68:71]
	v_mfma_f32_16x16x32_bf16 v[68:71], v[116:119], v[182:185], v[68:71]
	v_mfma_f32_16x16x32_bf16 v[72:75], v[104:107], v[186:189], v[72:75]
	v_mfma_f32_16x16x32_bf16 v[72:75], v[108:111], v[190:193], v[72:75]
	v_mfma_f32_16x16x32_bf16 v[76:79], v[112:115], v[186:189], v[76:79]
	v_mfma_f32_16x16x32_bf16 v[76:79], v[116:119], v[190:193], v[76:79]
	v_mfma_f32_16x16x32_bf16 v[80:83], v[104:107], v[194:197], v[80:83]
	v_mfma_f32_16x16x32_bf16 v[80:83], v[108:111], v[198:201], v[80:83]
	v_mfma_f32_16x16x32_bf16 v[84:87], v[112:115], v[194:197], v[84:87]
	v_mfma_f32_16x16x32_bf16 v[84:87], v[116:119], v[198:201], v[84:87]
	v_mfma_f32_16x16x32_bf16 v[88:91], v[104:107], v[202:205], v[88:91]
	v_mfma_f32_16x16x32_bf16 v[210:213], v[108:111], v[206:209], v[88:91]
	v_mfma_f32_16x16x32_bf16 v[88:91], v[112:115], v[202:205], v[92:95]
	v_mfma_f32_16x16x32_bf16 v[214:217], v[116:119], v[206:209], v[88:91]
	s_setprio 0
	s_setprio 1
	v_mfma_f32_16x16x32_bf16 v[88:91], v[120:123], v[178:181], v[96:99]
	v_mfma_f32_16x16x32_bf16 v[96:99], v[124:127], v[182:185], v[88:91]
	v_mfma_f32_16x16x32_bf16 v[32:35], v[170:173], v[178:181], v[32:35]
	v_mfma_f32_16x16x32_bf16 v[32:35], v[174:177], v[182:185], v[32:35]
	v_mfma_f32_16x16x32_bf16 v[36:39], v[120:123], v[186:189], v[36:39]
	v_mfma_f32_16x16x32_bf16 v[36:39], v[124:127], v[190:193], v[36:39]
	v_mfma_f32_16x16x32_bf16 v[40:43], v[170:173], v[186:189], v[40:43]
	v_mfma_f32_16x16x32_bf16 v[40:43], v[174:177], v[190:193], v[40:43]
	v_mfma_f32_16x16x32_bf16 v[44:47], v[120:123], v[194:197], v[44:47]
	v_mfma_f32_16x16x32_bf16 v[44:47], v[124:127], v[198:201], v[44:47]
	v_mfma_f32_16x16x32_bf16 v[48:51], v[170:173], v[194:197], v[48:51]
	v_mfma_f32_16x16x32_bf16 v[48:51], v[174:177], v[198:201], v[48:51]
	v_mfma_f32_16x16x32_bf16 v[52:55], v[120:123], v[202:205], v[52:55]
	v_mfma_f32_16x16x32_bf16 v[52:55], v[124:127], v[206:209], v[52:55]
	v_mfma_f32_16x16x32_bf16 v[56:59], v[170:173], v[202:205], v[56:59]
	v_mfma_f32_16x16x32_bf16 v[56:59], v[174:177], v[206:209], v[56:59]
	s_setprio 0
	s_barrier
; #define PG8_STAGE(bufoff, gbase, voff) do { _Pragma("unroll") for (int _i = 0; _i < 2; ++_i) \
;         __builtin_amdgcn_global_load_lds((const unsigned*)((const char*)(gbase) + (voff)[_i]), (PG8_LAS unsigned*)(lds + (bufoff) + ldsw + _i * 8192), 16, 0, 0); } while (0)
; #define PG8_LDA(dst, b, h) do { _Pragma("unroll") for (int m = 0; m < 4; ++m) _Pragma("unroll") for (int k = 0; k < 2; ++k) dst[m][k] = *(const PG8_LAS bf16x8*)(lds + PG8_SA(b, h) + aoff + m * 2048 + k * 1024); } while (0)
; #define PG8_LDB(dst, b, h) do { _Pragma("unroll") for (int n = 0; n < 2; ++n) _Pragma("unroll") for (int k = 0; k < 2; ++k) dst[n][k] = *(const PG8_LAS bf16x8*)(lds + PG8_SB(b, h) + boff + n * 2048 + k * 1024); } while (0)
; #define PG8_MMA(ai, bj, At, Bt) do { __builtin_amdgcn_s_setprio(1); _Pragma("unroll") for (int m = 0; m < 4; ++m) _Pragma("unroll") for (int n = 0; n < 2; ++n) _Pragma("unroll") for (int k = 0; k < 2; ++k) \
;         acc[ai][bj][m][n] = __builtin_amdgcn_mfma_f32_16x16x32_bf16(Bt[n][k], At[m][k], acc[ai][bj][m][n], 0, 0, 0); __builtin_amdgcn_s_setprio(0); } while (0)
; #define PG8_WAIT_V(n) asm volatile("s_waitcnt vmcnt(" #n ")" ::: "memory")
; #define PG8_WAIT_L(n) asm volatile("s_waitcnt lgkmcnt(" #n ")" ::: "memory")
; #define PG8_BAR __builtin_amdgcn_s_barrier()
;     ...
;             if constexpr (SP2) {
;             PG8_LDB(B0, 0, 0); PG8_LDB(B1, 0, 1); PG8_SCHED; PG8_LDA(At, 0, 0); PG8_STAGE(PG8_SA(1, 1), a1 + hstepA, voffA);
;             PG8_WAIT_V(8); PG8_WAIT_L(0); PG8_BAR; PG8_MMA(0, 0, At, B0); PG8_MMA(0, 1, At, B1); PG8_BAR; PG8_SCHED;
;             PG8_LDA(At, 0, 1); PG8_STAGE(PG8_SB(0, 0), b2, voffB); PG8_STAGE(PG8_SB(0, 1), b2 + hstepB, voffB); PG8_STAGE(PG8_SA(0, 0), a2, voffA);
;             PG8_WAIT_V(8); PG8_WAIT_L(0); PG8_BAR; PG8_MMA(1, 0, At, B0); PG8_MMA(1, 1, At, B1); PG8_BAR; PG8_SCHED;
;             PG8_LDB(B0, 1, 0); PG8_LDB(B1, 1, 1); PG8_SCHED; PG8_LDA(At, 1, 0); PG8_STAGE(PG8_SA(0, 1), a2 + hstepA, voffA);
;             PG8_WAIT_V(8); PG8_WAIT_L(0); PG8_BAR; PG8_MMA(0, 0, At, B0); PG8_MMA(0, 1, At, B1); PG8_BAR; PG8_SCHED;
;             PG8_LDA(At, 1, 1); PG8_STAGE(PG8_SB(1, 0), b3, voffB); PG8_STAGE(PG8_SB(1, 1), b3 + hstepB, voffB); PG8_STAGE(PG8_SA(1, 0), a3, voffA);
;             PG8_WAIT_V(8); PG8_WAIT_L(0); PG8_BAR; PG8_MMA(1, 0, At, B0); PG8_MMA(1, 1, At, B1); PG8_BAR; PG8_SCHED;
	s_mov_b32 m0, s48
	v_lshl_add_u64 v[246:247], s[24:25], 0, v[132:133]
	s_add_u32 s26, s24, 0x10000
	ds_read_b128 v[88:91], v143 offset:16384
	ds_read_b128 v[92:95], v143 offset:17408
	ds_read_b128 v[178:181], v143 offset:18432
	ds_read_b128 v[182:185], v143 offset:19456
	ds_read_b128 v[186:189], v143 offset:20480
	ds_read_b128 v[190:193], v143 offset:21504
	ds_read_b128 v[194:197], v143 offset:22528
	ds_read_b128 v[198:201], v143 offset:23552
	global_load_lds_dwordx4 v[246:247], off
	v_lshl_add_u64 v[248:249], s[24:25], 0, v[128:129]
	s_mov_b32 m0, s50
	s_addc_u32 s27, s25, 0
	global_load_lds_dwordx4 v[248:249], off
	s_mov_b32 m0, s51
	s_nop 0
	global_load_lds_dwordx4 v132, s[26:27]
	s_mov_b32 m0, s52
	s_nop 0
	global_load_lds_dwordx4 v128, s[26:27]
	s_mov_b32 m0, s23
	s_nop 0
	global_load_lds_dwordx4 v134, s[28:29]
	v_lshl_add_u64 v[202:203], s[28:29], 0, v[130:131]
	s_mov_b32 m0, s37
	s_nop 0
	global_load_lds_dwordx4 v[202:203], off
	s_waitcnt vmcnt(8)
	s_waitcnt lgkmcnt(0)
	s_barrier
	s_setprio 1
	v_mfma_f32_16x16x32_bf16 v[0:3], v[104:107], v[194:197], v[0:3]
	v_mfma_f32_16x16x32_bf16 v[0:3], v[108:111], v[198:201], v[0:3]
	v_mfma_f32_16x16x32_bf16 v[4:7], v[116:119], v[198:201], v[4:7]
	v_mfma_f32_16x16x32_bf16 v[4:7], v[112:115], v[194:197], v[4:7]
	v_mfma_f32_16x16x32_bf16 v[150:153], v[112:115], v[88:91], v[150:153]
	v_mfma_f32_16x16x32_bf16 v[150:153], v[116:119], v[92:95], v[150:153]
	v_mfma_f32_16x16x32_bf16 v[146:149], v[108:111], v[92:95], v[146:149]
	v_mfma_f32_16x16x32_bf16 v[146:149], v[104:107], v[88:91], v[146:149]
	v_mfma_f32_16x16x32_bf16 v[154:157], v[104:107], v[178:181], v[154:157]
	v_mfma_f32_16x16x32_bf16 v[154:157], v[108:111], v[182:185], v[154:157]
	v_mfma_f32_16x16x32_bf16 v[158:161], v[116:119], v[182:185], v[158:161]
	v_mfma_f32_16x16x32_bf16 v[158:161], v[112:115], v[178:181], v[158:161]
	v_mfma_f32_16x16x32_bf16 v[166:169], v[112:115], v[186:189], v[166:169]
	v_mfma_f32_16x16x32_bf16 v[166:169], v[116:119], v[190:193], v[166:169]
	v_mfma_f32_16x16x32_bf16 v[162:165], v[108:111], v[190:193], v[162:165]
	v_mfma_f32_16x16x32_bf16 v[162:165], v[104:107], v[186:189], v[162:165]
	s_setprio 0
	s_setprio 1
	v_mfma_f32_16x16x32_bf16 v[8:11], v[120:123], v[88:91], v[8:11]
	v_mfma_f32_16x16x32_bf16 v[202:205], v[124:127], v[92:95], v[8:11]
	v_mfma_f32_16x16x32_bf16 v[8:11], v[170:173], v[88:91], v[12:15]
	v_mfma_f32_16x16x32_bf16 v[206:209], v[174:177], v[92:95], v[8:11]
	v_mfma_f32_16x16x32_bf16 v[8:11], v[120:123], v[178:181], v[24:27]
	v_mfma_f32_16x16x32_bf16 v[218:221], v[124:127], v[182:185], v[8:11]
	v_mfma_f32_16x16x32_bf16 v[8:11], v[170:173], v[178:181], v[28:31]
	v_mfma_f32_16x16x32_bf16 v[178:181], v[174:177], v[182:185], v[8:11]
	v_mfma_f32_16x16x32_bf16 v[8:11], v[120:123], v[186:189], v[60:63]
	v_mfma_f32_16x16x32_bf16 v[182:185], v[124:127], v[190:193], v[8:11]
	v_mfma_f32_16x16x32_bf16 v[8:11], v[170:173], v[186:189], v[100:103]
	v_mfma_f32_16x16x32_bf16 v[186:189], v[174:177], v[190:193], v[8:11]
	v_mfma_f32_16x16x32_bf16 v[8:11], v[120:123], v[194:197], v[16:19]
	v_mfma_f32_16x16x32_bf16 v[190:193], v[124:127], v[198:201], v[8:11]
	v_mfma_f32_16x16x32_bf16 v[8:11], v[170:173], v[194:197], v[20:23]
	v_mfma_f32_16x16x32_bf16 v[170:173], v[174:177], v[198:201], v[8:11]
	s_setprio 0
	s_barrier
	s_nop 4
	ds_read_b128 v[8:11], v144
	ds_read_b128 v[12:15], v144 offset:1024
	ds_read_b128 v[16:19], v144 offset:2048
	ds_read_b128 v[20:23], v144 offset:3072
	ds_read_b128 v[174:177], v145
	ds_read_b128 v[194:197], v145 offset:1024
	ds_read_b128 v[198:201], v145 offset:2048
	ds_read_b128 v[222:225], v145 offset:3072
	s_add_u32 s26, s28, 0x4000
	s_addc_u32 s27, s29, 0
	s_mov_b32 m0, s39
	ds_read_b128 v[24:27], v143 offset:32768
	ds_read_b128 v[28:31], v143 offset:33792
	ds_read_b128 v[60:63], v143 offset:34816
	ds_read_b128 v[226:229], v143 offset:35840
	ds_read_b128 v[230:233], v143 offset:36864
	ds_read_b128 v[234:237], v143 offset:37888
	ds_read_b128 v[238:241], v143 offset:38912
	ds_read_b128 v[242:245], v143 offset:39936
	global_load_lds_dwordx4 v134, s[26:27]
	v_lshl_add_u64 v[88:89], s[26:27], 0, v[130:131]
	s_mov_b32 m0, s40
	s_nop 0
	global_load_lds_dwordx4 v[88:89], off
	s_waitcnt vmcnt(8)
	s_waitcnt lgkmcnt(0)
	s_barrier
; #define PG8_STAGE(bufoff, gbase, voff) do { _Pragma("unroll") for (int _i = 0; _i < 2; ++_i) \
;         __builtin_amdgcn_global_load_lds((const unsigned*)((const char*)(gbase) + (voff)[_i]), (PG8_LAS unsigned*)(lds + (bufoff) + ldsw + _i * 8192), 16, 0, 0); } while (0)
; #define PG8_LDA(dst, b, h) do { _Pragma("unroll") for (int m = 0; m < 4; ++m) _Pragma("unroll") for (int k = 0; k < 2; ++k) dst[m][k] = *(const PG8_LAS bf16x8*)(lds + PG8_SA(b, h) + aoff + m * 2048 + k * 1024); } while (0)
; #define PG8_LDB(dst, b, h) do { _Pragma("unroll") for (int n = 0; n < 2; ++n) _Pragma("unroll") for (int k = 0; k < 2; ++k) dst[n][k] = *(const PG8_LAS bf16x8*)(lds + PG8_SB(b, h) + boff + n * 2048 + k * 1024); } while (0)
; #define PG8_MMA(ai, bj, At, Bt) do { __builtin_amdgcn_s_setprio(1); _Pragma("unroll") for (int m = 0; m < 4; ++m) _Pragma("unroll") for (int n = 0; n < 2; ++n) _Pragma("unroll") for (int k = 0; k < 2; ++k) \
;         acc[ai][bj][m][n] = __builtin_amdgcn_mfma_f32_16x16x32_bf16(Bt[n][k], At[m][k], acc[ai][bj][m][n], 0, 0, 0); __builtin_amdgcn_s_setprio(0); } while (0)
; #define PG8_WAIT_V(n) asm volatile("s_waitcnt vmcnt(" #n ")" ::: "memory")
; #define PG8_WAIT_L(n) asm volatile("s_waitcnt lgkmcnt(" #n ")" ::: "memory")
;     ...
;             if constexpr (SP2) {
;             PG8_LDB(B0, 0, 0); PG8_LDB(B1, 0, 1); PG8_SCHED; PG8_LDA(At, 0, 0); PG8_STAGE(PG8_SA(1, 1), a1 + hstepA, voffA);
;             PG8_WAIT_V(8); PG8_WAIT_L(0); PG8_BAR; PG8_MMA(0, 0, At, B0); PG8_MMA(0, 1, At, B1); PG8_BAR; PG8_SCHED;
;             PG8_LDA(At, 0, 1); PG8_STAGE(PG8_SB(0, 0), b2, voffB); PG8_STAGE(PG8_SB(0, 1), b2 + hstepB, voffB); PG8_STAGE(PG8_SA(0, 0), a2, voffA);
;             PG8_WAIT_V(8); PG8_WAIT_L(0); PG8_BAR; PG8_MMA(1, 0, At, B0); PG8_MMA(1, 1, At, B1); PG8_BAR; PG8_SCHED;
;             PG8_LDB(B0, 1, 0); PG8_LDB(B1, 1, 1); PG8_SCHED; PG8_LDA(At, 1, 0); PG8_STAGE(PG8_SA(0, 1), a2 + hstepA, voffA);
;             PG8_WAIT_V(8); PG8_WAIT_L(0); PG8_BAR; PG8_MMA(0, 0, At, B0); PG8_MMA(0, 1, At, B1); PG8_BAR; PG8_SCHED;
;             PG8_LDA(At, 1, 1); PG8_STAGE(PG8_SB(1, 0), b3, voffB); PG8_STAGE(PG8_SB(1, 1), b3 + hstepB, voffB); PG8_STAGE(PG8_SA(1, 0), a3, voffA);
;             PG8_WAIT_V(8); PG8_WAIT_L(0); PG8_BAR; PG8_MMA(1, 0, At, B0); PG8_MMA(1, 1, At, B1); PG8_BAR; PG8_SCHED;
;     ...
;         if constexpr (ALIGN_EPI) { if (wr == 0) PG8_BAR; }
	s_setprio 1
	v_mfma_f32_16x16x32_bf16 v[64:67], v[8:11], v[24:27], v[64:67]
	v_mfma_f32_16x16x32_bf16 v[124:127], v[12:15], v[28:31], v[64:67]
	v_mfma_f32_16x16x32_bf16 v[64:67], v[16:19], v[24:27], v[68:71]
	v_mfma_f32_16x16x32_bf16 v[120:123], v[20:23], v[28:31], v[64:67]
	v_mfma_f32_16x16x32_bf16 v[64:67], v[8:11], v[60:63], v[72:75]
	v_mfma_f32_16x16x32_bf16 v[108:111], v[12:15], v[226:229], v[64:67]
	v_mfma_f32_16x16x32_bf16 v[64:67], v[16:19], v[60:63], v[76:79]
	v_mfma_f32_16x16x32_bf16 v[104:107], v[20:23], v[226:229], v[64:67]
	v_mfma_f32_16x16x32_bf16 v[64:67], v[8:11], v[230:233], v[80:83]
	v_mfma_f32_16x16x32_bf16 v[92:95], v[12:15], v[234:237], v[64:67]
	v_mfma_f32_16x16x32_bf16 v[64:67], v[16:19], v[230:233], v[84:87]
	v_mfma_f32_16x16x32_bf16 v[88:91], v[20:23], v[234:237], v[64:67]
	v_mfma_f32_16x16x32_bf16 v[64:67], v[8:11], v[238:241], v[210:213]
	v_mfma_f32_16x16x32_bf16 v[76:79], v[12:15], v[242:245], v[64:67]
	v_mfma_f32_16x16x32_bf16 v[64:67], v[16:19], v[238:241], v[214:217]
	v_mfma_f32_16x16x32_bf16 v[72:75], v[20:23], v[242:245], v[64:67]
	s_setprio 0
	s_setprio 1
	v_mfma_f32_16x16x32_bf16 v[64:67], v[174:177], v[24:27], v[96:99]
	v_mfma_f32_16x16x32_bf16 v[24:27], v[198:201], v[24:27], v[32:35]
	v_mfma_f32_16x16x32_bf16 v[112:115], v[222:225], v[28:31], v[24:27]
	v_mfma_f32_16x16x32_bf16 v[24:27], v[174:177], v[60:63], v[36:39]
	v_mfma_f32_16x16x32_bf16 v[100:103], v[194:197], v[226:229], v[24:27]
	v_mfma_f32_16x16x32_bf16 v[24:27], v[198:201], v[60:63], v[40:43]
	v_mfma_f32_16x16x32_bf16 v[96:99], v[222:225], v[226:229], v[24:27]
	v_mfma_f32_16x16x32_bf16 v[24:27], v[174:177], v[230:233], v[44:47]
	v_mfma_f32_16x16x32_bf16 v[84:87], v[194:197], v[234:237], v[24:27]
	v_mfma_f32_16x16x32_bf16 v[24:27], v[198:201], v[230:233], v[48:51]
	v_mfma_f32_16x16x32_bf16 v[80:83], v[222:225], v[234:237], v[24:27]
	v_mfma_f32_16x16x32_bf16 v[24:27], v[174:177], v[238:241], v[52:55]
	v_mfma_f32_16x16x32_bf16 v[60:63], v[194:197], v[242:245], v[24:27]
	v_mfma_f32_16x16x32_bf16 v[24:27], v[198:201], v[238:241], v[56:59]
	v_mfma_f32_16x16x32_bf16 v[116:119], v[194:197], v[28:31], v[64:67]
	v_mfma_f32_16x16x32_bf16 v[56:59], v[222:225], v[242:245], v[24:27]
	s_setprio 0
	s_barrier
	s_mov_b32 m0, s53
	s_nop 2
	v_lshl_add_u64 v[24:25], v[246:247], 0, s[12:13]
	s_add_u32 s24, s24, 0x10080
	ds_read_b128 v[32:35], v143 offset:49152
	ds_read_b128 v[36:39], v143 offset:50176
	ds_read_b128 v[210:213], v143 offset:51200
	ds_read_b128 v[214:217], v143 offset:52224
	ds_read_b128 v[226:229], v143 offset:53248
	ds_read_b128 v[230:233], v143 offset:54272
	ds_read_b128 v[234:237], v143 offset:55296
	ds_read_b128 v[238:241], v143 offset:56320
	global_load_lds_dwordx4 v[24:25], off
	v_lshl_add_u64 v[24:25], v[248:249], 0, s[12:13]
	s_mov_b32 m0, s54
	s_addc_u32 s25, s25, 0
	global_load_lds_dwordx4 v[24:25], off
	s_mov_b32 m0, s55
	s_nop 0
	global_load_lds_dwordx4 v132, s[24:25]
	s_mov_b32 m0, s56
	s_nop 0
	global_load_lds_dwordx4 v128, s[24:25]
	s_mov_b32 m0, s42
	s_nop 0
	global_load_lds_dwordx4 v134, s[30:31]
	v_lshl_add_u64 v[24:25], s[30:31], 0, v[130:131]
	s_mov_b32 m0, s43
	s_nop 0
	global_load_lds_dwordx4 v[24:25], off
	s_waitcnt vmcnt(8)
	s_waitcnt lgkmcnt(0)
	s_barrier
	s_setprio 1
	v_mfma_f32_16x16x32_bf16 v[24:27], v[8:11], v[32:35], v[146:149]
	v_mfma_f32_16x16x32_bf16 v[68:71], v[12:15], v[36:39], v[24:27]
	v_mfma_f32_16x16x32_bf16 v[24:27], v[16:19], v[32:35], v[150:153]
	v_mfma_f32_16x16x32_bf16 v[64:67], v[20:23], v[36:39], v[24:27]
	v_mfma_f32_16x16x32_bf16 v[24:27], v[8:11], v[210:213], v[154:157]
	v_mfma_f32_16x16x32_bf16 v[44:47], v[12:15], v[214:217], v[24:27]
	v_mfma_f32_16x16x32_bf16 v[24:27], v[16:19], v[210:213], v[158:161]
	v_mfma_f32_16x16x32_bf16 v[40:43], v[20:23], v[214:217], v[24:27]
	v_mfma_f32_16x16x32_bf16 v[24:27], v[8:11], v[226:229], v[162:165]
	v_mfma_f32_16x16x32_bf16 v[28:31], v[12:15], v[230:233], v[24:27]
	v_mfma_f32_16x16x32_bf16 v[0:3], v[8:11], v[234:237], v[0:3]
	v_mfma_f32_16x16x32_bf16 v[12:15], v[12:15], v[238:241], v[0:3]
	v_mfma_f32_16x16x32_bf16 v[24:27], v[16:19], v[226:229], v[166:169]
	v_mfma_f32_16x16x32_bf16 v[24:27], v[20:23], v[230:233], v[24:27]
	v_mfma_f32_16x16x32_bf16 v[0:3], v[16:19], v[234:237], v[4:7]
	v_mfma_f32_16x16x32_bf16 v[8:11], v[20:23], v[238:241], v[0:3]
	s_setprio 0
	s_setprio 1
	v_mfma_f32_16x16x32_bf16 v[0:3], v[174:177], v[32:35], v[202:205]
	v_mfma_f32_16x16x32_bf16 v[52:55], v[194:197], v[36:39], v[0:3]
	v_mfma_f32_16x16x32_bf16 v[0:3], v[198:201], v[32:35], v[206:209]
	v_mfma_f32_16x16x32_bf16 v[48:51], v[222:225], v[36:39], v[0:3]
	v_mfma_f32_16x16x32_bf16 v[0:3], v[174:177], v[210:213], v[218:221]
	v_mfma_f32_16x16x32_bf16 v[36:39], v[194:197], v[214:217], v[0:3]
	v_mfma_f32_16x16x32_bf16 v[0:3], v[198:201], v[210:213], v[178:181]
	v_mfma_f32_16x16x32_bf16 v[32:35], v[222:225], v[214:217], v[0:3]
	v_mfma_f32_16x16x32_bf16 v[0:3], v[174:177], v[226:229], v[182:185]
	v_mfma_f32_16x16x32_bf16 v[20:23], v[194:197], v[230:233], v[0:3]
	v_mfma_f32_16x16x32_bf16 v[0:3], v[198:201], v[226:229], v[186:189]
	v_mfma_f32_16x16x32_bf16 v[16:19], v[222:225], v[230:233], v[0:3]
	v_mfma_f32_16x16x32_bf16 v[0:3], v[174:177], v[234:237], v[190:193]
	v_mfma_f32_16x16x32_bf16 v[4:7], v[194:197], v[238:241], v[0:3]
	v_mfma_f32_16x16x32_bf16 v[0:3], v[198:201], v[234:237], v[170:173]
	v_mfma_f32_16x16x32_bf16 v[0:3], v[222:225], v[238:241], v[0:3]
	s_setprio 0
	s_barrier
	s_and_b64 vcc, exec, s[0:1]
	s_cbranch_vccnz .LBB0_99
	s_barrier

; #define PG8_STAGE(bufoff, gbase, voff) do { _Pragma("unroll") for (int _i = 0; _i < 2; ++_i) \
;         __builtin_amdgcn_global_load_lds((const unsigned*)((const char*)(gbase) + (voff)[_i]), (PG8_LAS unsigned*)(lds + (bufoff) + ldsw + _i * 8192), 16, 0, 0); } while (0)
; #define PG8_LDA(dst, b, h) do { _Pragma("unroll") for (int m = 0; m < 4; ++m) _Pragma("unroll") for (int k = 0; k < 2; ++k) dst[m][k] = *(const PG8_LAS bf16x8*)(lds + PG8_SA(b, h) + aoff + m * 2048 + k * 1024); } while (0)
; #define PG8_LDB(dst, b, h) do { _Pragma("unroll") for (int n = 0; n < 2; ++n) _Pragma("unroll") for (int k = 0; k < 2; ++k) dst[n][k] = *(const PG8_LAS bf16x8*)(lds + PG8_SB(b, h) + boff + n * 2048 + k * 1024); } while (0)
; #define PG8_WAIT_V(n) asm volatile("s_waitcnt vmcnt(" #n ")" ::: "memory")
; #define PG8_WAIT_L(n) asm volatile("s_waitcnt lgkmcnt(" #n ")" ::: "memory")
;     ...
;         for (int t = 0; t < nt; t += 2) {
;             const bool last = (t == nt - 2);
;             const char* a1 = cA + (ptrdiff_t)(t + 1) * kstepA;
;             const char* a2 = last ? nA : cA + (ptrdiff_t)(t + 2) * kstepA; const char* b2 = last ? nB : cB + (ptrdiff_t)(t + 2) * kstep;
;             const char* a3 = a2 + kstepA; const char* b3 = b2 + kstep;
;             if (last && has_next) S.a_ready(nxt);
;             if constexpr (SP2) {
;             PG8_LDB(B0, 0, 0); PG8_LDB(B1, 0, 1); PG8_SCHED; PG8_LDA(At, 0, 0); PG8_STAGE(PG8_SA(1, 1), a1 + hstepA, voffA);
;             PG8_WAIT_V(8); PG8_WAIT_L(0); PG8_BAR; PG8_MMA(0, 0, At, B0); PG8_MMA(0, 1, At, B1); PG8_BAR; PG8_SCHED;
;             PG8_LDA(At, 0, 1); PG8_STAGE(PG8_SB(0, 0), b2, voffB); PG8_STAGE(PG8_SB(0, 1), b2 + hstepB, voffB); PG8_STAGE(PG8_SA(0, 0), a2, voffA);
;             PG8_WAIT_V(8); PG8_WAIT_L(0); PG8_BAR; PG8_MMA(1, 0, At, B0); PG8_MMA(1, 1, At, B1); PG8_BAR; PG8_SCHED;
;             PG8_LDB(B0, 1, 0); PG8_LDB(B1, 1, 1); PG8_SCHED; PG8_LDA(At, 1, 0); PG8_STAGE(PG8_SA(0, 1), a2 + hstepA, voffA);
;             PG8_WAIT_V(8); PG8_WAIT_L(0); PG8_BAR; PG8_MMA(0, 0, At, B0); PG8_MMA(0, 1, At, B1); PG8_BAR; PG8_SCHED;
;             PG8_LDA(At, 1, 1); PG8_STAGE(PG8_SB(1, 0), b3, voffB); PG8_STAGE(PG8_SB(1, 1), b3 + hstepB, voffB); PG8_STAGE(PG8_SA(1, 0), a3, voffA);
;             PG8_WAIT_V(8); PG8_WAIT_L(0); PG8_BAR; PG8_MMA(1, 0, At, B0); PG8_MMA(1, 1, At, B1); PG8_BAR; PG8_SCHED;
.Lin_nostg:
	s_add_u32 s65, s6, 0x4000
	s_addc_u32 s66, s7, 0
	s_cmp_eq_u32 vcc_lo, 28
	s_cselect_b32 s90, s54, s65
	s_cselect_b32 s91, s29, s66
	s_cselect_b32 s88, s55, s56
	s_cselect_b32 s89, s31, s57
	s_add_u32 s86, s90, 0x8000
	s_addc_u32 s87, s91, 0
	s_add_i32 s65, 0, 0x10000
	s_add_i32 s66, 0, 0x14000
	v_add_u32_e32 v22, s65, v182
	v_add_u32_e32 v54, s66, v182
	ds_read_b128 v[10:13], v22
	ds_read_b128 v[14:17], v22 offset:1024
	ds_read_b128 v[18:21], v22 offset:2048
	ds_read_b128 v[22:25], v22 offset:3072
	ds_read_b128 v[26:29], v54
	ds_read_b128 v[38:41], v54 offset:1024
	ds_read_b128 v[50:53], v54 offset:2048
	ds_read_b128 v[54:57], v54 offset:3072
	s_add_i32 m0, s51, 0xc000
	ds_read_b128 v[172:175], v183
	ds_read_b128 v[176:179], v183 offset:1024
	ds_read_b128 v[184:187], v183 offset:2048
	ds_read_b128 v[188:191], v183 offset:3072
	ds_read_b128 v[192:195], v183 offset:4096
	ds_read_b128 v[196:199], v183 offset:5120
	ds_read_b128 v[200:203], v183 offset:6144
	ds_read_b128 v[204:207], v183 offset:7168
	global_load_lds_dwordx4 v168, s[6:7]
	s_add_i32 m0, s51, 0xe000
	s_nop 0
	global_load_lds_dwordx4 v170, s[6:7]
	s_waitcnt vmcnt(8)
	s_waitcnt lgkmcnt(0)
	s_barrier
	s_setprio 1
	v_mfma_f32_16x16x32_bf16 v[158:161], v[10:13], v[172:175], 0
	v_mfma_f32_16x16x32_bf16 v[158:161], v[14:17], v[176:179], v[158:161]
	v_mfma_f32_16x16x32_bf16 v[154:157], v[22:25], v[176:179], 0
	v_mfma_f32_16x16x32_bf16 v[154:157], v[18:21], v[172:175], v[154:157]
	v_mfma_f32_16x16x32_bf16 v[138:141], v[18:21], v[184:187], 0
	v_mfma_f32_16x16x32_bf16 v[138:141], v[22:25], v[188:191], v[138:141]
	v_mfma_f32_16x16x32_bf16 v[142:145], v[14:17], v[188:191], 0
	v_mfma_f32_16x16x32_bf16 v[142:145], v[10:13], v[184:187], v[142:145]
	v_mfma_f32_16x16x32_bf16 v[126:129], v[10:13], v[192:195], 0
	v_mfma_f32_16x16x32_bf16 v[126:129], v[14:17], v[196:199], v[126:129]
	v_mfma_f32_16x16x32_bf16 v[122:125], v[22:25], v[196:199], 0
	v_mfma_f32_16x16x32_bf16 v[122:125], v[18:21], v[192:195], v[122:125]
	v_mfma_f32_16x16x32_bf16 v[106:109], v[18:21], v[200:203], 0
	v_mfma_f32_16x16x32_bf16 v[106:109], v[22:25], v[204:207], v[106:109]
	v_mfma_f32_16x16x32_bf16 v[110:113], v[14:17], v[204:207], 0
	v_mfma_f32_16x16x32_bf16 v[110:113], v[10:13], v[200:203], v[110:113]
	s_setprio 0
	s_setprio 1
	v_mfma_f32_16x16x32_bf16 v[150:153], v[26:29], v[172:175], 0
	v_mfma_f32_16x16x32_bf16 v[150:153], v[38:41], v[176:179], v[150:153]
	v_mfma_f32_16x16x32_bf16 v[146:149], v[54:57], v[176:179], 0
	v_mfma_f32_16x16x32_bf16 v[146:149], v[50:53], v[172:175], v[146:149]
	v_mfma_f32_16x16x32_bf16 v[130:133], v[50:53], v[184:187], 0
	v_mfma_f32_16x16x32_bf16 v[130:133], v[54:57], v[188:191], v[130:133]
	v_mfma_f32_16x16x32_bf16 v[134:137], v[38:41], v[188:191], 0
	v_mfma_f32_16x16x32_bf16 v[134:137], v[26:29], v[184:187], v[134:137]
	v_mfma_f32_16x16x32_bf16 v[118:121], v[26:29], v[192:195], 0
	v_mfma_f32_16x16x32_bf16 v[118:121], v[38:41], v[196:199], v[118:121]
	v_mfma_f32_16x16x32_bf16 v[114:117], v[54:57], v[196:199], 0
	v_mfma_f32_16x16x32_bf16 v[114:117], v[50:53], v[192:195], v[114:117]
	v_mfma_f32_16x16x32_bf16 v[98:101], v[50:53], v[200:203], 0
	v_mfma_f32_16x16x32_bf16 v[98:101], v[54:57], v[204:207], v[98:101]
	v_mfma_f32_16x16x32_bf16 v[102:105], v[38:41], v[204:207], 0
	v_mfma_f32_16x16x32_bf16 v[102:105], v[26:29], v[200:203], v[102:105]
	s_setprio 0
	s_barrier
	s_add_i32 s65, s65, s2
	s_mov_b32 m0, s65
	ds_read_b128 v[172:175], v183 offset:16384
	ds_read_b128 v[176:179], v183 offset:17408
	ds_read_b128 v[184:187], v183 offset:18432
	ds_read_b128 v[188:191], v183 offset:19456
	ds_read_b128 v[192:195], v183 offset:20480
	ds_read_b128 v[196:199], v183 offset:21504
	ds_read_b128 v[200:203], v183 offset:22528
	ds_read_b128 v[204:207], v183 offset:23552
	global_load_lds_dwordx4 v0, s[88:89]
	s_add_i32 m0, s65, 0x2000
	s_add_u32 s96, s88, 0x4000
	s_addc_u32 s97, s89, 0
	s_add_i32 s65, s66, s2
	global_load_lds_dwordx4 v162, s[88:89]
	s_mov_b32 m0, s65
	s_nop 0
	global_load_lds_dwordx4 v0, s[96:97]
	s_add_i32 m0, s65, 0x2000
	s_nop 0
	global_load_lds_dwordx4 v162, s[96:97]
	s_mov_b32 m0, s51
	s_nop 0
	global_load_lds_dwordx4 v166, s[90:91]
	s_mov_b32 m0, s92
	s_nop 0
	global_load_lds_dwordx4 v164, s[90:91]
	s_waitcnt vmcnt(8)
	s_waitcnt lgkmcnt(0)
	s_barrier
	s_setprio 1
	v_mfma_f32_16x16x32_bf16 v[94:97], v[10:13], v[172:175], 0
	v_mfma_f32_16x16x32_bf16 v[94:97], v[14:17], v[176:179], v[94:97]
	v_mfma_f32_16x16x32_bf16 v[90:93], v[18:21], v[172:175], 0
	v_mfma_f32_16x16x32_bf16 v[90:93], v[22:25], v[176:179], v[90:93]
	v_mfma_f32_16x16x32_bf16 v[78:81], v[10:13], v[184:187], 0
	v_mfma_f32_16x16x32_bf16 v[78:81], v[14:17], v[188:191], v[78:81]
	v_mfma_f32_16x16x32_bf16 v[74:77], v[18:21], v[184:187], 0
	v_mfma_f32_16x16x32_bf16 v[74:77], v[22:25], v[188:191], v[74:77]
	v_mfma_f32_16x16x32_bf16 v[62:65], v[10:13], v[192:195], 0
	v_mfma_f32_16x16x32_bf16 v[62:65], v[14:17], v[196:199], v[62:65]
	v_mfma_f32_16x16x32_bf16 v[58:61], v[18:21], v[192:195], 0
	v_mfma_f32_16x16x32_bf16 v[58:61], v[22:25], v[196:199], v[58:61]
	v_mfma_f32_16x16x32_bf16 v[10:13], v[10:13], v[200:203], 0
	v_mfma_f32_16x16x32_bf16 v[10:13], v[14:17], v[204:207], v[10:13]
	v_mfma_f32_16x16x32_bf16 v[14:17], v[18:21], v[200:203], 0
	v_mfma_f32_16x16x32_bf16 v[14:17], v[22:25], v[204:207], v[14:17]
	s_setprio 0
	s_setprio 1
	v_mfma_f32_16x16x32_bf16 v[30:33], v[26:29], v[184:187], 0
	v_mfma_f32_16x16x32_bf16 v[70:73], v[38:41], v[188:191], v[30:33]
	v_mfma_f32_16x16x32_bf16 v[30:33], v[50:53], v[184:187], 0
	v_mfma_f32_16x16x32_bf16 v[66:69], v[54:57], v[188:191], v[30:33]
	v_mfma_f32_16x16x32_bf16 v[30:33], v[26:29], v[192:195], 0
	v_mfma_f32_16x16x32_bf16 v[46:49], v[38:41], v[196:199], v[30:33]
	v_mfma_f32_16x16x32_bf16 v[30:33], v[50:53], v[192:195], 0
	v_mfma_f32_16x16x32_bf16 v[42:45], v[54:57], v[196:199], v[30:33]
	v_mfma_f32_16x16x32_bf16 v[6:9], v[26:29], v[200:203], 0
	v_mfma_f32_16x16x32_bf16 v[6:9], v[38:41], v[204:207], v[6:9]
	v_mfma_f32_16x16x32_bf16 v[2:5], v[50:53], v[200:203], 0
	v_mfma_f32_16x16x32_bf16 v[2:5], v[54:57], v[204:207], v[2:5]
	v_mfma_f32_16x16x32_bf16 v[18:21], v[26:29], v[172:175], 0
	v_mfma_f32_16x16x32_bf16 v[18:21], v[38:41], v[176:179], v[18:21]
	v_mfma_f32_16x16x32_bf16 v[22:25], v[50:53], v[172:175], 0
	v_mfma_f32_16x16x32_bf16 v[22:25], v[54:57], v[176:179], v[22:25]
	s_setprio 0
	s_barrier
	s_branch .Lin_mid

; #define PG8_STAGE(bufoff, gbase, voff) do { _Pragma("unroll") for (int _i = 0; _i < 2; ++_i) \
;         __builtin_amdgcn_global_load_lds((const unsigned*)((const char*)(gbase) + (voff)[_i]), (PG8_LAS unsigned*)(lds + (bufoff) + ldsw + _i * 8192), 16, 0, 0); } while (0)
; #define PG8_LDA(dst, b, h) do { _Pragma("unroll") for (int m = 0; m < 4; ++m) _Pragma("unroll") for (int k = 0; k < 2; ++k) dst[m][k] = *(const PG8_LAS bf16x8*)(lds + PG8_SA(b, h) + aoff + m * 2048 + k * 1024); } while (0)
; #define PG8_LDB(dst, b, h) do { _Pragma("unroll") for (int n = 0; n < 2; ++n) _Pragma("unroll") for (int k = 0; k < 2; ++k) dst[n][k] = *(const PG8_LAS bf16x8*)(lds + PG8_SB(b, h) + boff + n * 2048 + k * 1024); } while (0)
; #define PG8_WAIT_V(n) asm volatile("s_waitcnt vmcnt(" #n ")" ::: "memory")
; #define PG8_WAIT_L(n) asm volatile("s_waitcnt lgkmcnt(" #n ")" ::: "memory")
;     ...
;         for (int t = 0; t < nt; t += 2) {
;             const bool last = (t == nt - 2);
;             const char* a1 = cA + (ptrdiff_t)(t + 1) * kstepA;
;             const char* a2 = last ? nA : cA + (ptrdiff_t)(t + 2) * kstepA; const char* b2 = last ? nB : cB + (ptrdiff_t)(t + 2) * kstep;
;             const char* a3 = a2 + kstepA; const char* b3 = b2 + kstep;
;             if (last && has_next) S.a_ready(nxt);
;             if constexpr (SP2) {
;             PG8_LDB(B0, 0, 0); PG8_LDB(B1, 0, 1); PG8_SCHED; PG8_LDA(At, 0, 0); PG8_STAGE(PG8_SA(1, 1), a1 + hstepA, voffA);
;             PG8_WAIT_V(8); PG8_WAIT_L(0); PG8_BAR; PG8_MMA(0, 0, At, B0); PG8_MMA(0, 1, At, B1); PG8_BAR; PG8_SCHED;
;             PG8_LDA(At, 0, 1); PG8_STAGE(PG8_SB(0, 0), b2, voffB); PG8_STAGE(PG8_SB(0, 1), b2 + hstepB, voffB); PG8_STAGE(PG8_SA(0, 0), a2, voffA);
;             PG8_WAIT_V(8); PG8_WAIT_L(0); PG8_BAR; PG8_MMA(1, 0, At, B0); PG8_MMA(1, 1, At, B1); PG8_BAR; PG8_SCHED;
;             PG8_LDB(B0, 1, 0); PG8_LDB(B1, 1, 1); PG8_SCHED; PG8_LDA(At, 1, 0); PG8_STAGE(PG8_SA(0, 1), a2 + hstepA, voffA);
;             PG8_WAIT_V(8); PG8_WAIT_L(0); PG8_BAR; PG8_MMA(0, 0, At, B0); PG8_MMA(0, 1, At, B1); PG8_BAR; PG8_SCHED;
;             PG8_LDA(At, 1, 1); PG8_STAGE(PG8_SB(1, 0), b3, voffB); PG8_STAGE(PG8_SB(1, 1), b3 + hstepB, voffB); PG8_STAGE(PG8_SA(1, 0), a3, voffA);
;             PG8_WAIT_V(8); PG8_WAIT_L(0); PG8_BAR; PG8_MMA(1, 0, At, B0); PG8_MMA(1, 1, At, B1); PG8_BAR; PG8_SCHED;
.LBB0_328:
	s_add_u32 s65, s6, 0x4000
	s_addc_u32 s66, s7, 0
	s_cmp_eq_u32 vcc_lo, 28
	s_cselect_b32 s90, s54, s65
	s_cselect_b32 s91, s29, s66
	s_cselect_b32 s88, s55, s56
	s_cselect_b32 s89, s31, s57
	s_add_u32 s86, s90, 0x8000
	s_addc_u32 s87, s91, 0
	s_add_i32 s65, 0, 0x10000
	s_add_i32 s66, 0, 0x14000
	v_add_u32_e32 v22, s65, v182
	v_add_u32_e32 v54, s66, v182
	ds_read_b128 v[10:13], v22
	ds_read_b128 v[14:17], v22 offset:1024
	ds_read_b128 v[18:21], v22 offset:2048
	ds_read_b128 v[22:25], v22 offset:3072
	ds_read_b128 v[26:29], v54
	ds_read_b128 v[38:41], v54 offset:1024
	ds_read_b128 v[50:53], v54 offset:2048
	ds_read_b128 v[54:57], v54 offset:3072
	s_add_i32 m0, s51, 0xc000
	ds_read_b128 v[172:175], v183
	ds_read_b128 v[176:179], v183 offset:1024
	ds_read_b128 v[184:187], v183 offset:2048
	ds_read_b128 v[188:191], v183 offset:3072
	ds_read_b128 v[192:195], v183 offset:4096
	ds_read_b128 v[196:199], v183 offset:5120
	ds_read_b128 v[200:203], v183 offset:6144
	ds_read_b128 v[204:207], v183 offset:7168
	global_load_lds_dwordx4 v168, s[6:7]
	s_add_i32 m0, s51, 0xe000
	s_nop 0
	global_load_lds_dwordx4 v170, s[6:7]
	s_waitcnt vmcnt(8)
	s_waitcnt lgkmcnt(0)
	s_barrier
	s_setprio 1
	v_mfma_f32_16x16x32_bf16 v[158:161], v[10:13], v[172:175], v[158:161]
	v_mfma_f32_16x16x32_bf16 v[158:161], v[14:17], v[176:179], v[158:161]
	v_mfma_f32_16x16x32_bf16 v[154:157], v[22:25], v[176:179], v[154:157]
	v_mfma_f32_16x16x32_bf16 v[154:157], v[18:21], v[172:175], v[154:157]
	v_mfma_f32_16x16x32_bf16 v[138:141], v[18:21], v[184:187], v[138:141]
	v_mfma_f32_16x16x32_bf16 v[138:141], v[22:25], v[188:191], v[138:141]
	v_mfma_f32_16x16x32_bf16 v[142:145], v[14:17], v[188:191], v[142:145]
	v_mfma_f32_16x16x32_bf16 v[142:145], v[10:13], v[184:187], v[142:145]
	v_mfma_f32_16x16x32_bf16 v[126:129], v[10:13], v[192:195], v[126:129]
	v_mfma_f32_16x16x32_bf16 v[126:129], v[14:17], v[196:199], v[126:129]
	v_mfma_f32_16x16x32_bf16 v[122:125], v[22:25], v[196:199], v[122:125]
	v_mfma_f32_16x16x32_bf16 v[122:125], v[18:21], v[192:195], v[122:125]
	v_mfma_f32_16x16x32_bf16 v[106:109], v[18:21], v[200:203], v[106:109]
	v_mfma_f32_16x16x32_bf16 v[106:109], v[22:25], v[204:207], v[106:109]
	v_mfma_f32_16x16x32_bf16 v[110:113], v[14:17], v[204:207], v[110:113]
	v_mfma_f32_16x16x32_bf16 v[110:113], v[10:13], v[200:203], v[110:113]
	s_setprio 0
	s_setprio 1
	v_mfma_f32_16x16x32_bf16 v[150:153], v[26:29], v[172:175], v[150:153]
	v_mfma_f32_16x16x32_bf16 v[150:153], v[38:41], v[176:179], v[150:153]
	v_mfma_f32_16x16x32_bf16 v[146:149], v[54:57], v[176:179], v[146:149]
	v_mfma_f32_16x16x32_bf16 v[146:149], v[50:53], v[172:175], v[146:149]
	v_mfma_f32_16x16x32_bf16 v[130:133], v[50:53], v[184:187], v[130:133]
	v_mfma_f32_16x16x32_bf16 v[130:133], v[54:57], v[188:191], v[130:133]
	v_mfma_f32_16x16x32_bf16 v[134:137], v[38:41], v[188:191], v[134:137]
	v_mfma_f32_16x16x32_bf16 v[134:137], v[26:29], v[184:187], v[134:137]
	v_mfma_f32_16x16x32_bf16 v[118:121], v[26:29], v[192:195], v[118:121]
	v_mfma_f32_16x16x32_bf16 v[118:121], v[38:41], v[196:199], v[118:121]
	v_mfma_f32_16x16x32_bf16 v[114:117], v[54:57], v[196:199], v[114:117]
	v_mfma_f32_16x16x32_bf16 v[114:117], v[50:53], v[192:195], v[114:117]
	v_mfma_f32_16x16x32_bf16 v[98:101], v[50:53], v[200:203], v[98:101]
	v_mfma_f32_16x16x32_bf16 v[98:101], v[54:57], v[204:207], v[98:101]
	v_mfma_f32_16x16x32_bf16 v[102:105], v[38:41], v[204:207], v[102:105]
	v_mfma_f32_16x16x32_bf16 v[102:105], v[26:29], v[200:203], v[102:105]
	s_setprio 0
	s_barrier
	s_add_i32 s65, s65, s2
	s_mov_b32 m0, s65
	ds_read_b128 v[172:175], v183 offset:16384
	ds_read_b128 v[176:179], v183 offset:17408
	ds_read_b128 v[184:187], v183 offset:18432
	ds_read_b128 v[188:191], v183 offset:19456
	ds_read_b128 v[192:195], v183 offset:20480
	ds_read_b128 v[196:199], v183 offset:21504
	ds_read_b128 v[200:203], v183 offset:22528
	ds_read_b128 v[204:207], v183 offset:23552
	global_load_lds_dwordx4 v0, s[88:89]
	s_add_i32 m0, s65, 0x2000
	s_add_u32 s96, s88, 0x4000
	s_addc_u32 s97, s89, 0
	s_add_i32 s65, s66, s2
	global_load_lds_dwordx4 v162, s[88:89]
	s_mov_b32 m0, s65
	s_nop 0
	global_load_lds_dwordx4 v0, s[96:97]
	s_add_i32 m0, s65, 0x2000
	s_nop 0
	global_load_lds_dwordx4 v162, s[96:97]
	s_mov_b32 m0, s51
	s_nop 0
	global_load_lds_dwordx4 v166, s[90:91]
	s_mov_b32 m0, s92
	s_nop 0
	global_load_lds_dwordx4 v164, s[90:91]
	s_waitcnt vmcnt(8)
	s_waitcnt lgkmcnt(0)
	s_barrier
	s_setprio 1
	v_mfma_f32_16x16x32_bf16 v[94:97], v[10:13], v[172:175], v[94:97]
	v_mfma_f32_16x16x32_bf16 v[94:97], v[14:17], v[176:179], v[94:97]
	v_mfma_f32_16x16x32_bf16 v[90:93], v[18:21], v[172:175], v[90:93]
	v_mfma_f32_16x16x32_bf16 v[90:93], v[22:25], v[176:179], v[90:93]
	v_mfma_f32_16x16x32_bf16 v[78:81], v[10:13], v[184:187], v[78:81]
	v_mfma_f32_16x16x32_bf16 v[78:81], v[14:17], v[188:191], v[78:81]
	v_mfma_f32_16x16x32_bf16 v[74:77], v[18:21], v[184:187], v[74:77]
	v_mfma_f32_16x16x32_bf16 v[74:77], v[22:25], v[188:191], v[74:77]
	v_mfma_f32_16x16x32_bf16 v[62:65], v[10:13], v[192:195], v[62:65]
	v_mfma_f32_16x16x32_bf16 v[62:65], v[14:17], v[196:199], v[62:65]
	v_mfma_f32_16x16x32_bf16 v[58:61], v[18:21], v[192:195], v[58:61]
	v_mfma_f32_16x16x32_bf16 v[58:61], v[22:25], v[196:199], v[58:61]
	v_mfma_f32_16x16x32_bf16 v[10:13], v[10:13], v[200:203], v[34:37]
	v_mfma_f32_16x16x32_bf16 v[10:13], v[14:17], v[204:207], v[10:13]
	v_mfma_f32_16x16x32_bf16 v[14:17], v[18:21], v[200:203], v[30:33]
	v_mfma_f32_16x16x32_bf16 v[14:17], v[22:25], v[204:207], v[14:17]
	s_setprio 0
	s_setprio 1
	v_mfma_f32_16x16x32_bf16 v[30:33], v[26:29], v[184:187], v[70:73]
	v_mfma_f32_16x16x32_bf16 v[70:73], v[38:41], v[188:191], v[30:33]
	v_mfma_f32_16x16x32_bf16 v[30:33], v[50:53], v[184:187], v[66:69]
	v_mfma_f32_16x16x32_bf16 v[66:69], v[54:57], v[188:191], v[30:33]
	v_mfma_f32_16x16x32_bf16 v[30:33], v[26:29], v[192:195], v[46:49]
	v_mfma_f32_16x16x32_bf16 v[46:49], v[38:41], v[196:199], v[30:33]
	v_mfma_f32_16x16x32_bf16 v[30:33], v[50:53], v[192:195], v[42:45]
	v_mfma_f32_16x16x32_bf16 v[42:45], v[54:57], v[196:199], v[30:33]
	v_mfma_f32_16x16x32_bf16 v[6:9], v[26:29], v[200:203], v[6:9]
	v_mfma_f32_16x16x32_bf16 v[6:9], v[38:41], v[204:207], v[6:9]
	v_mfma_f32_16x16x32_bf16 v[2:5], v[50:53], v[200:203], v[2:5]
	v_mfma_f32_16x16x32_bf16 v[2:5], v[54:57], v[204:207], v[2:5]
	v_mfma_f32_16x16x32_bf16 v[18:21], v[26:29], v[172:175], v[86:89]
	v_mfma_f32_16x16x32_bf16 v[18:21], v[38:41], v[176:179], v[18:21]
	v_mfma_f32_16x16x32_bf16 v[22:25], v[50:53], v[172:175], v[82:85]
	v_mfma_f32_16x16x32_bf16 v[22:25], v[54:57], v[176:179], v[22:25]
	s_setprio 0
	s_barrier
; #define PG8_STAGE(bufoff, gbase, voff) do { _Pragma("unroll") for (int _i = 0; _i < 2; ++_i) \
;         __builtin_amdgcn_global_load_lds((const unsigned*)((const char*)(gbase) + (voff)[_i]), (PG8_LAS unsigned*)(lds + (bufoff) + ldsw + _i * 8192), 16, 0, 0); } while (0)
; #define PG8_LDA(dst, b, h) do { _Pragma("unroll") for (int m = 0; m < 4; ++m) _Pragma("unroll") for (int k = 0; k < 2; ++k) dst[m][k] = *(const PG8_LAS bf16x8*)(lds + PG8_SA(b, h) + aoff + m * 2048 + k * 1024); } while (0)
; #define PG8_LDB(dst, b, h) do { _Pragma("unroll") for (int n = 0; n < 2; ++n) _Pragma("unroll") for (int k = 0; k < 2; ++k) dst[n][k] = *(const PG8_LAS bf16x8*)(lds + PG8_SB(b, h) + boff + n * 2048 + k * 1024); } while (0)
; #define PG8_WAIT_V(n) asm volatile("s_waitcnt vmcnt(" #n ")" ::: "memory")
; #define PG8_WAIT_L(n) asm volatile("s_waitcnt lgkmcnt(" #n ")" ::: "memory")
;     ...
;         for (int t = 0; t < nt; t += 2) {
;             const bool last = (t == nt - 2);
;             const char* a1 = cA + (ptrdiff_t)(t + 1) * kstepA;
;             const char* a2 = last ? nA : cA + (ptrdiff_t)(t + 2) * kstepA; const char* b2 = last ? nB : cB + (ptrdiff_t)(t + 2) * kstep;
;             const char* a3 = a2 + kstepA; const char* b3 = b2 + kstep;
;             if (last && has_next) S.a_ready(nxt);
;             if constexpr (SP2) {
;             PG8_LDB(B0, 0, 0); PG8_LDB(B1, 0, 1); PG8_SCHED; PG8_LDA(At, 0, 0); PG8_STAGE(PG8_SA(1, 1), a1 + hstepA, voffA);
;             PG8_WAIT_V(8); PG8_WAIT_L(0); PG8_BAR; PG8_MMA(0, 0, At, B0); PG8_MMA(0, 1, At, B1); PG8_BAR; PG8_SCHED;
;             PG8_LDA(At, 0, 1); PG8_STAGE(PG8_SB(0, 0), b2, voffB); PG8_STAGE(PG8_SB(0, 1), b2 + hstepB, voffB); PG8_STAGE(PG8_SA(0, 0), a2, voffA);
;             PG8_WAIT_V(8); PG8_WAIT_L(0); PG8_BAR; PG8_MMA(1, 0, At, B0); PG8_MMA(1, 1, At, B1); PG8_BAR; PG8_SCHED;
;             PG8_LDB(B0, 1, 0); PG8_LDB(B1, 1, 1); PG8_SCHED; PG8_LDA(At, 1, 0); PG8_STAGE(PG8_SA(0, 1), a2 + hstepA, voffA);
;             PG8_WAIT_V(8); PG8_WAIT_L(0); PG8_BAR; PG8_MMA(0, 0, At, B0); PG8_MMA(0, 1, At, B1); PG8_BAR; PG8_SCHED;
;             PG8_LDA(At, 1, 1); PG8_STAGE(PG8_SB(1, 0), b3, voffB); PG8_STAGE(PG8_SB(1, 1), b3 + hstepB, voffB); PG8_STAGE(PG8_SA(1, 0), a3, voffA);
;             PG8_WAIT_V(8); PG8_WAIT_L(0); PG8_BAR; PG8_MMA(1, 0, At, B0); PG8_MMA(1, 1, At, B1); PG8_BAR; PG8_SCHED;
.Lin_mid:
	s_add_i32 s65, 0, 0x18000
	v_add_u32_e32 v34, s65, v182
	s_add_i32 s66, 0, 0x1c000
	ds_read_b128 v[26:29], v34
	ds_read_b128 v[30:33], v34 offset:1024
	ds_read_b128 v[38:41], v34 offset:2048
	ds_read_b128 v[50:53], v34 offset:3072
	v_add_u32_e32 v34, s66, v182
	ds_read_b128 v[54:57], v34
	ds_read_b128 v[172:175], v34 offset:1024
	ds_read_b128 v[176:179], v34 offset:2048
	ds_read_b128 v[184:187], v34 offset:3072
	s_add_u32 s90, s90, 0x4000
	s_addc_u32 s91, s91, 0
	s_mov_b32 m0, s14
	ds_read_b128 v[34:37], v183 offset:32768
	ds_read_b128 v[82:85], v183 offset:33792
	ds_read_b128 v[86:89], v183 offset:34816
	ds_read_b128 v[188:191], v183 offset:35840
	ds_read_b128 v[192:195], v183 offset:36864
	ds_read_b128 v[196:199], v183 offset:37888
	ds_read_b128 v[200:203], v183 offset:38912
	ds_read_b128 v[204:207], v183 offset:39936
	global_load_lds_dwordx4 v166, s[90:91]
	v_lshl_add_u64 v[208:209], s[90:91], 0, v[164:165]
	s_mov_b32 m0, s15
	s_nop 0
	global_load_lds_dwordx4 v[208:209], off
	s_waitcnt vmcnt(8)
	s_waitcnt lgkmcnt(0)
	s_barrier
	s_setprio 1
	v_mfma_f32_16x16x32_bf16 v[158:161], v[26:29], v[34:37], v[158:161]
	v_mfma_f32_16x16x32_bf16 v[158:161], v[30:33], v[82:85], v[158:161]
	v_mfma_f32_16x16x32_bf16 v[154:157], v[50:53], v[82:85], v[154:157]
	v_mfma_f32_16x16x32_bf16 v[154:157], v[38:41], v[34:37], v[154:157]
	v_mfma_f32_16x16x32_bf16 v[138:141], v[38:41], v[86:89], v[138:141]
	v_mfma_f32_16x16x32_bf16 v[138:141], v[50:53], v[188:191], v[138:141]
	v_mfma_f32_16x16x32_bf16 v[142:145], v[30:33], v[188:191], v[142:145]
	v_mfma_f32_16x16x32_bf16 v[142:145], v[26:29], v[86:89], v[142:145]
	v_mfma_f32_16x16x32_bf16 v[126:129], v[26:29], v[192:195], v[126:129]
	v_mfma_f32_16x16x32_bf16 v[126:129], v[30:33], v[196:199], v[126:129]
	v_mfma_f32_16x16x32_bf16 v[122:125], v[50:53], v[196:199], v[122:125]
	v_mfma_f32_16x16x32_bf16 v[122:125], v[38:41], v[192:195], v[122:125]
	v_mfma_f32_16x16x32_bf16 v[106:109], v[38:41], v[200:203], v[106:109]
	v_mfma_f32_16x16x32_bf16 v[106:109], v[50:53], v[204:207], v[106:109]
	v_mfma_f32_16x16x32_bf16 v[110:113], v[30:33], v[204:207], v[110:113]
	v_mfma_f32_16x16x32_bf16 v[110:113], v[26:29], v[200:203], v[110:113]
	s_setprio 0
	s_setprio 1
	v_mfma_f32_16x16x32_bf16 v[150:153], v[54:57], v[34:37], v[150:153]
	v_mfma_f32_16x16x32_bf16 v[150:153], v[172:175], v[82:85], v[150:153]
	v_mfma_f32_16x16x32_bf16 v[34:37], v[176:179], v[34:37], v[146:149]
	v_mfma_f32_16x16x32_bf16 v[146:149], v[184:187], v[82:85], v[34:37]
	v_mfma_f32_16x16x32_bf16 v[34:37], v[54:57], v[86:89], v[134:137]
	v_mfma_f32_16x16x32_bf16 v[134:137], v[172:175], v[188:191], v[34:37]
	v_mfma_f32_16x16x32_bf16 v[34:37], v[176:179], v[86:89], v[130:133]
	v_mfma_f32_16x16x32_bf16 v[130:133], v[184:187], v[188:191], v[34:37]
	v_mfma_f32_16x16x32_bf16 v[34:37], v[54:57], v[192:195], v[118:121]
	v_mfma_f32_16x16x32_bf16 v[118:121], v[172:175], v[196:199], v[34:37]
	v_mfma_f32_16x16x32_bf16 v[34:37], v[176:179], v[192:195], v[114:117]
	v_mfma_f32_16x16x32_bf16 v[114:117], v[184:187], v[196:199], v[34:37]
	v_mfma_f32_16x16x32_bf16 v[34:37], v[54:57], v[200:203], v[102:105]
	v_mfma_f32_16x16x32_bf16 v[102:105], v[172:175], v[204:207], v[34:37]
	v_mfma_f32_16x16x32_bf16 v[34:37], v[176:179], v[200:203], v[98:101]
	v_mfma_f32_16x16x32_bf16 v[98:101], v[184:187], v[204:207], v[34:37]
	s_setprio 0
	s_barrier
	s_add_u32 s90, s88, 0x8000
	s_addc_u32 s91, s89, 0
	s_add_i32 s65, s65, s2
	s_nop 0
	s_mov_b32 m0, s65
	ds_read_b128 v[82:85], v183 offset:49152
	ds_read_b128 v[188:191], v183 offset:50176
	ds_read_b128 v[192:195], v183 offset:51200
	ds_read_b128 v[196:199], v183 offset:52224
	ds_read_b128 v[200:203], v183 offset:53248
	ds_read_b128 v[204:207], v183 offset:54272
	ds_read_b128 v[208:211], v183 offset:55296
	ds_read_b128 v[216:219], v183 offset:56320
	global_load_lds_dwordx4 v0, s[90:91]
	s_add_i32 m0, s65, 0x2000
	s_add_u32 s88, s88, 0xc000
	s_addc_u32 s89, s89, 0
	s_add_i32 s65, s66, s2
	global_load_lds_dwordx4 v162, s[90:91]
	s_mov_b32 m0, s65
	s_nop 0
	global_load_lds_dwordx4 v0, s[88:89]
	s_add_i32 m0, s65, 0x2000
	s_nop 0
	global_load_lds_dwordx4 v162, s[88:89]
	s_mov_b32 m0, s71
	s_nop 0
	global_load_lds_dwordx4 v166, s[86:87]
	v_lshl_add_u64 v[34:35], s[86:87], 0, v[164:165]
	s_mov_b32 m0, s80
	s_nop 0
	global_load_lds_dwordx4 v[34:35], off
	s_waitcnt vmcnt(8)
	s_waitcnt lgkmcnt(0)
	s_barrier
	s_setprio 1
	v_mfma_f32_16x16x32_bf16 v[34:37], v[26:29], v[82:85], v[94:97]
	v_mfma_f32_16x16x32_bf16 v[94:97], v[30:33], v[188:191], v[34:37]
	v_mfma_f32_16x16x32_bf16 v[34:37], v[38:41], v[82:85], v[90:93]
	v_mfma_f32_16x16x32_bf16 v[90:93], v[50:53], v[188:191], v[34:37]
	v_mfma_f32_16x16x32_bf16 v[34:37], v[26:29], v[192:195], v[78:81]
	v_mfma_f32_16x16x32_bf16 v[78:81], v[30:33], v[196:199], v[34:37]
	v_mfma_f32_16x16x32_bf16 v[34:37], v[38:41], v[192:195], v[74:77]
	v_mfma_f32_16x16x32_bf16 v[74:77], v[50:53], v[196:199], v[34:37]
	v_mfma_f32_16x16x32_bf16 v[34:37], v[26:29], v[200:203], v[62:65]
	v_mfma_f32_16x16x32_bf16 v[62:65], v[30:33], v[204:207], v[34:37]
	v_mfma_f32_16x16x32_bf16 v[34:37], v[38:41], v[200:203], v[58:61]
	v_mfma_f32_16x16x32_bf16 v[58:61], v[50:53], v[204:207], v[34:37]
	v_mfma_f32_16x16x32_bf16 v[10:13], v[26:29], v[208:211], v[10:13]
	v_mfma_f32_16x16x32_bf16 v[34:37], v[30:33], v[216:219], v[10:13]
	v_mfma_f32_16x16x32_bf16 v[10:13], v[38:41], v[208:211], v[14:17]
	v_mfma_f32_16x16x32_bf16 v[30:33], v[50:53], v[216:219], v[10:13]
	s_setprio 0
	s_setprio 1
	v_mfma_f32_16x16x32_bf16 v[10:13], v[54:57], v[82:85], v[18:21]
	v_mfma_f32_16x16x32_bf16 v[86:89], v[172:175], v[188:191], v[10:13]
	v_mfma_f32_16x16x32_bf16 v[10:13], v[176:179], v[82:85], v[22:25]
	v_mfma_f32_16x16x32_bf16 v[82:85], v[184:187], v[188:191], v[10:13]
	v_mfma_f32_16x16x32_bf16 v[10:13], v[54:57], v[192:195], v[70:73]
	v_mfma_f32_16x16x32_bf16 v[70:73], v[172:175], v[196:199], v[10:13]
	v_mfma_f32_16x16x32_bf16 v[10:13], v[176:179], v[192:195], v[66:69]
	v_mfma_f32_16x16x32_bf16 v[66:69], v[184:187], v[196:199], v[10:13]
	v_mfma_f32_16x16x32_bf16 v[10:13], v[54:57], v[200:203], v[46:49]
	v_mfma_f32_16x16x32_bf16 v[46:49], v[172:175], v[204:207], v[10:13]
	v_mfma_f32_16x16x32_bf16 v[10:13], v[176:179], v[200:203], v[42:45]
	v_mfma_f32_16x16x32_bf16 v[42:45], v[184:187], v[204:207], v[10:13]
	v_mfma_f32_16x16x32_bf16 v[6:9], v[54:57], v[208:211], v[6:9]
	v_mfma_f32_16x16x32_bf16 v[6:9], v[172:175], v[216:219], v[6:9]
	v_mfma_f32_16x16x32_bf16 v[2:5], v[176:179], v[208:211], v[2:5]
	v_mfma_f32_16x16x32_bf16 v[2:5], v[184:187], v[216:219], v[2:5]
	s_setprio 0
	s_barrier
	s_add_i32 vcc_lo, vcc_lo, 2
	s_add_u32 s6, s6, 0x10000
	s_addc_u32 s7, s7, 0
	s_add_u32 s56, s56, 0x10000
	s_addc_u32 s57, s57, 0
	s_cmp_gt_u32 vcc_lo, 29
	s_cbranch_scc0 .LBB0_328
	s_and_b64 vcc, exec, s[26:27]
	s_cbranch_vccz .LBB0_331
	s_barrier

; #define PG8_STAGE(bufoff, gbase, voff) do { _Pragma("unroll") for (int _i = 0; _i < 2; ++_i) \
;         __builtin_amdgcn_global_load_lds((const unsigned*)((const char*)(gbase) + (voff)[_i]), (PG8_LAS unsigned*)(lds + (bufoff) + ldsw + _i * 8192), 16, 0, 0); } while (0)
; #define PG8_LDA(dst, b, h) do { _Pragma("unroll") for (int m = 0; m < 4; ++m) _Pragma("unroll") for (int k = 0; k < 2; ++k) dst[m][k] = *(const PG8_LAS bf16x8*)(lds + PG8_SA(b, h) + aoff + m * 2048 + k * 1024); } while (0)
; #define PG8_LDB(dst, b, h) do { _Pragma("unroll") for (int n = 0; n < 2; ++n) _Pragma("unroll") for (int k = 0; k < 2; ++k) dst[n][k] = *(const PG8_LAS bf16x8*)(lds + PG8_SB(b, h) + boff + n * 2048 + k * 1024); } while (0)
; #define PG8_WAIT_V(n) asm volatile("s_waitcnt vmcnt(" #n ")" ::: "memory")
; #define PG8_WAIT_L(n) asm volatile("s_waitcnt lgkmcnt(" #n ")" ::: "memory")
;     ...
;         for (int t = 0; t < nt; t += 2) {
;             const bool last = (t == nt - 2);
;             const char* a1 = cA + (ptrdiff_t)(t + 1) * kstepA;
;             const char* a2 = last ? nA : cA + (ptrdiff_t)(t + 2) * kstepA; const char* b2 = last ? nB : cB + (ptrdiff_t)(t + 2) * kstep;
;             const char* a3 = a2 + kstepA; const char* b3 = b2 + kstep;
;             if (last && has_next) S.a_ready(nxt);
;             if constexpr (SP2) {
;             PG8_LDB(B0, 0, 0); PG8_LDB(B1, 0, 1); PG8_SCHED; PG8_LDA(At, 0, 0); PG8_STAGE(PG8_SA(1, 1), a1 + hstepA, voffA);
;             PG8_WAIT_V(8); PG8_WAIT_L(0); PG8_BAR; PG8_MMA(0, 0, At, B0); PG8_MMA(0, 1, At, B1); PG8_BAR; PG8_SCHED;
;             PG8_LDA(At, 0, 1); PG8_STAGE(PG8_SB(0, 0), b2, voffB); PG8_STAGE(PG8_SB(0, 1), b2 + hstepB, voffB); PG8_STAGE(PG8_SA(0, 0), a2, voffA);
;             PG8_WAIT_V(8); PG8_WAIT_L(0); PG8_BAR; PG8_MMA(1, 0, At, B0); PG8_MMA(1, 1, At, B1); PG8_BAR; PG8_SCHED;
;             PG8_LDB(B0, 1, 0); PG8_LDB(B1, 1, 1); PG8_SCHED; PG8_LDA(At, 1, 0); PG8_STAGE(PG8_SA(0, 1), a2 + hstepA, voffA);
;             PG8_WAIT_V(8); PG8_WAIT_L(0); PG8_BAR; PG8_MMA(0, 0, At, B0); PG8_MMA(0, 1, At, B1); PG8_BAR; PG8_SCHED;
;             PG8_LDA(At, 1, 1); PG8_STAGE(PG8_SB(1, 0), b3, voffB); PG8_STAGE(PG8_SB(1, 1), b3 + hstepB, voffB); PG8_STAGE(PG8_SA(1, 0), a3, voffA);
;             PG8_WAIT_V(8); PG8_WAIT_L(0); PG8_BAR; PG8_MMA(1, 0, At, B0); PG8_MMA(1, 1, At, B1); PG8_BAR; PG8_SCHED;
.Lout_nostg:
	s_add_u32 s36, s34, 0x4000
	s_addc_u32 s37, s35, 0
	s_cmp_eq_u32 s57, 28
	s_cselect_b32 s86, s29, s36
	s_cselect_b32 s87, s23, s37
	s_cselect_b32 s46, s31, s44
	s_cselect_b32 s47, s21, s56
	s_add_u32 s36, s86, 0x8000
	s_addc_u32 s37, s87, 0
	s_add_i32 s65, 0, 0x10000
	v_add_u32_e32 v0, s65, v242
	s_add_i32 s66, 0, 0x14000
	s_waitcnt lgkmcnt(0)
	ds_read_b128 v[130:133], v0
	ds_read_b128 v[134:137], v0 offset:1024
	ds_read_b128 v[138:141], v0 offset:2048
	ds_read_b128 v[142:145], v0 offset:3072
	v_add_u32_e32 v0, s66, v242
	ds_read_b128 v[146:149], v0
	ds_read_b128 v[150:153], v0 offset:1024
	ds_read_b128 v[154:157], v0 offset:2048
	ds_read_b128 v[158:161], v0 offset:3072
	s_add_i32 m0, s51, 0xc000
	ds_read_b128 v[162:165], v243
	ds_read_b128 v[166:169], v243 offset:1024
	ds_read_b128 v[170:173], v243 offset:2048
	ds_read_b128 v[174:177], v243 offset:3072
	ds_read_b128 v[178:181], v243 offset:4096
	ds_read_b128 v[182:185], v243 offset:5120
	ds_read_b128 v[198:201], v243 offset:6144
	ds_read_b128 v[202:205], v243 offset:7168
	global_load_lds_dwordx4 v194, s[34:35]
	s_add_i32 m0, s51, 0xe000
	s_nop 0
	global_load_lds_dwordx4 v196, s[34:35]
	s_waitcnt vmcnt(8)
	s_waitcnt lgkmcnt(0)
	s_barrier
	s_setprio 1
	v_mfma_f32_16x16x32_bf16 v[126:129], v[130:133], v[162:165], 0
	v_mfma_f32_16x16x32_bf16 v[126:129], v[134:137], v[166:169], v[126:129]
	v_mfma_f32_16x16x32_bf16 v[122:125], v[142:145], v[166:169], 0
	v_mfma_f32_16x16x32_bf16 v[122:125], v[138:141], v[162:165], v[122:125]
	v_mfma_f32_16x16x32_bf16 v[106:109], v[138:141], v[170:173], 0
	v_mfma_f32_16x16x32_bf16 v[106:109], v[142:145], v[174:177], v[106:109]
	v_mfma_f32_16x16x32_bf16 v[110:113], v[134:137], v[174:177], 0
	v_mfma_f32_16x16x32_bf16 v[110:113], v[130:133], v[170:173], v[110:113]
	v_mfma_f32_16x16x32_bf16 v[94:97], v[130:133], v[178:181], 0
	v_mfma_f32_16x16x32_bf16 v[94:97], v[134:137], v[182:185], v[94:97]
	v_mfma_f32_16x16x32_bf16 v[90:93], v[142:145], v[182:185], 0
	v_mfma_f32_16x16x32_bf16 v[90:93], v[138:141], v[178:181], v[90:93]
	v_mfma_f32_16x16x32_bf16 v[74:77], v[138:141], v[198:201], 0
	v_mfma_f32_16x16x32_bf16 v[74:77], v[142:145], v[202:205], v[74:77]
	v_mfma_f32_16x16x32_bf16 v[78:81], v[134:137], v[202:205], 0
	v_mfma_f32_16x16x32_bf16 v[78:81], v[130:133], v[198:201], v[78:81]
	s_setprio 0
	s_setprio 1
	v_mfma_f32_16x16x32_bf16 v[118:121], v[146:149], v[162:165], 0
	v_mfma_f32_16x16x32_bf16 v[118:121], v[150:153], v[166:169], v[118:121]
	v_mfma_f32_16x16x32_bf16 v[114:117], v[158:161], v[166:169], 0
	v_mfma_f32_16x16x32_bf16 v[114:117], v[154:157], v[162:165], v[114:117]
	v_mfma_f32_16x16x32_bf16 v[98:101], v[154:157], v[170:173], 0
	v_mfma_f32_16x16x32_bf16 v[98:101], v[158:161], v[174:177], v[98:101]
	v_mfma_f32_16x16x32_bf16 v[102:105], v[150:153], v[174:177], 0
	v_mfma_f32_16x16x32_bf16 v[102:105], v[146:149], v[170:173], v[102:105]
	v_mfma_f32_16x16x32_bf16 v[86:89], v[146:149], v[178:181], 0
	v_mfma_f32_16x16x32_bf16 v[86:89], v[150:153], v[182:185], v[86:89]
	v_mfma_f32_16x16x32_bf16 v[82:85], v[158:161], v[182:185], 0
	v_mfma_f32_16x16x32_bf16 v[82:85], v[154:157], v[178:181], v[82:85]
	v_mfma_f32_16x16x32_bf16 v[66:69], v[154:157], v[198:201], 0
	v_mfma_f32_16x16x32_bf16 v[66:69], v[158:161], v[202:205], v[66:69]
	v_mfma_f32_16x16x32_bf16 v[70:73], v[150:153], v[202:205], 0
	v_mfma_f32_16x16x32_bf16 v[70:73], v[146:149], v[198:201], v[70:73]
	s_setprio 0
	s_barrier
	s_add_i32 s65, s65, s49
	s_mov_b32 m0, s65
	ds_read_b128 v[162:165], v243 offset:16384
	ds_read_b128 v[166:169], v243 offset:17408
	ds_read_b128 v[170:173], v243 offset:18432
	ds_read_b128 v[174:177], v243 offset:19456
	ds_read_b128 v[178:181], v243 offset:20480
	ds_read_b128 v[182:185], v243 offset:21504
	ds_read_b128 v[198:201], v243 offset:22528
	ds_read_b128 v[202:205], v243 offset:23552
	global_load_lds_dwordx4 v188, s[46:47]
	s_add_i32 m0, s65, 0x2000
	s_add_u32 s90, s46, 0x4000
	s_addc_u32 s91, s47, 0
	s_add_i32 s65, s66, s49
	global_load_lds_dwordx4 v192, s[46:47]
	s_mov_b32 m0, s65
	s_nop 0
	global_load_lds_dwordx4 v188, s[90:91]
	s_add_i32 m0, s65, 0x2000
	s_nop 0
	global_load_lds_dwordx4 v192, s[90:91]
	s_mov_b32 m0, s51
	s_nop 0
	global_load_lds_dwordx4 v186, s[86:87]
	s_mov_b32 m0, s54
	s_nop 0
	global_load_lds_dwordx4 v190, s[86:87]
	s_waitcnt vmcnt(8)
	s_waitcnt lgkmcnt(0)
	s_barrier
	s_setprio 1
	v_mfma_f32_16x16x32_bf16 v[62:65], v[130:133], v[162:165], 0
	v_mfma_f32_16x16x32_bf16 v[62:65], v[134:137], v[166:169], v[62:65]
	v_mfma_f32_16x16x32_bf16 v[58:61], v[142:145], v[166:169], 0
	v_mfma_f32_16x16x32_bf16 v[58:61], v[138:141], v[162:165], v[58:61]
	v_mfma_f32_16x16x32_bf16 v[42:45], v[138:141], v[170:173], 0
	v_mfma_f32_16x16x32_bf16 v[42:45], v[142:145], v[174:177], v[42:45]
	v_mfma_f32_16x16x32_bf16 v[46:49], v[134:137], v[174:177], 0
	v_mfma_f32_16x16x32_bf16 v[46:49], v[130:133], v[170:173], v[46:49]
	v_mfma_f32_16x16x32_bf16 v[30:33], v[130:133], v[178:181], 0
	v_mfma_f32_16x16x32_bf16 v[30:33], v[134:137], v[182:185], v[30:33]
	v_mfma_f32_16x16x32_bf16 v[26:29], v[142:145], v[182:185], 0
	v_mfma_f32_16x16x32_bf16 v[26:29], v[138:141], v[178:181], v[26:29]
	v_mfma_f32_16x16x32_bf16 v[10:13], v[138:141], v[198:201], 0
	v_mfma_f32_16x16x32_bf16 v[10:13], v[142:145], v[202:205], v[10:13]
	v_mfma_f32_16x16x32_bf16 v[14:17], v[134:137], v[202:205], 0
	v_mfma_f32_16x16x32_bf16 v[14:17], v[130:133], v[198:201], v[14:17]
	s_setprio 0
	s_setprio 1
	v_mfma_f32_16x16x32_bf16 v[54:57], v[146:149], v[162:165], 0
	v_mfma_f32_16x16x32_bf16 v[54:57], v[150:153], v[166:169], v[54:57]
	v_mfma_f32_16x16x32_bf16 v[50:53], v[158:161], v[166:169], 0
	v_mfma_f32_16x16x32_bf16 v[50:53], v[154:157], v[162:165], v[50:53]
	v_mfma_f32_16x16x32_bf16 v[34:37], v[154:157], v[170:173], 0
	v_mfma_f32_16x16x32_bf16 v[34:37], v[158:161], v[174:177], v[34:37]
	v_mfma_f32_16x16x32_bf16 v[38:41], v[150:153], v[174:177], 0
	v_mfma_f32_16x16x32_bf16 v[38:41], v[146:149], v[170:173], v[38:41]
	v_mfma_f32_16x16x32_bf16 v[22:25], v[146:149], v[178:181], 0
	v_mfma_f32_16x16x32_bf16 v[22:25], v[150:153], v[182:185], v[22:25]
	v_mfma_f32_16x16x32_bf16 v[18:21], v[158:161], v[182:185], 0
	v_mfma_f32_16x16x32_bf16 v[18:21], v[154:157], v[178:181], v[18:21]
	v_mfma_f32_16x16x32_bf16 v[2:5], v[154:157], v[198:201], 0
	v_mfma_f32_16x16x32_bf16 v[2:5], v[158:161], v[202:205], v[2:5]
	v_mfma_f32_16x16x32_bf16 v[6:9], v[150:153], v[202:205], 0
	v_mfma_f32_16x16x32_bf16 v[6:9], v[146:149], v[198:201], v[6:9]
	s_setprio 0
	s_barrier
	s_branch .Lout_mid

; #define PG8_STAGE(bufoff, gbase, voff) do { _Pragma("unroll") for (int _i = 0; _i < 2; ++_i) \
;         __builtin_amdgcn_global_load_lds((const unsigned*)((const char*)(gbase) + (voff)[_i]), (PG8_LAS unsigned*)(lds + (bufoff) + ldsw + _i * 8192), 16, 0, 0); } while (0)
; #define PG8_LDA(dst, b, h) do { _Pragma("unroll") for (int m = 0; m < 4; ++m) _Pragma("unroll") for (int k = 0; k < 2; ++k) dst[m][k] = *(const PG8_LAS bf16x8*)(lds + PG8_SA(b, h) + aoff + m * 2048 + k * 1024); } while (0)
; #define PG8_LDB(dst, b, h) do { _Pragma("unroll") for (int n = 0; n < 2; ++n) _Pragma("unroll") for (int k = 0; k < 2; ++k) dst[n][k] = *(const PG8_LAS bf16x8*)(lds + PG8_SB(b, h) + boff + n * 2048 + k * 1024); } while (0)
; #define PG8_WAIT_V(n) asm volatile("s_waitcnt vmcnt(" #n ")" ::: "memory")
; #define PG8_WAIT_L(n) asm volatile("s_waitcnt lgkmcnt(" #n ")" ::: "memory")
;     ...
;         for (int t = 0; t < nt; t += 2) {
;             const bool last = (t == nt - 2);
;             const char* a1 = cA + (ptrdiff_t)(t + 1) * kstepA;
;             const char* a2 = last ? nA : cA + (ptrdiff_t)(t + 2) * kstepA; const char* b2 = last ? nB : cB + (ptrdiff_t)(t + 2) * kstep;
;             const char* a3 = a2 + kstepA; const char* b3 = b2 + kstep;
;             if (last && has_next) S.a_ready(nxt);
;             if constexpr (SP2) {
;             PG8_LDB(B0, 0, 0); PG8_LDB(B1, 0, 1); PG8_SCHED; PG8_LDA(At, 0, 0); PG8_STAGE(PG8_SA(1, 1), a1 + hstepA, voffA);
;             PG8_WAIT_V(8); PG8_WAIT_L(0); PG8_BAR; PG8_MMA(0, 0, At, B0); PG8_MMA(0, 1, At, B1); PG8_BAR; PG8_SCHED;
;             PG8_LDA(At, 0, 1); PG8_STAGE(PG8_SB(0, 0), b2, voffB); PG8_STAGE(PG8_SB(0, 1), b2 + hstepB, voffB); PG8_STAGE(PG8_SA(0, 0), a2, voffA);
;             PG8_WAIT_V(8); PG8_WAIT_L(0); PG8_BAR; PG8_MMA(1, 0, At, B0); PG8_MMA(1, 1, At, B1); PG8_BAR; PG8_SCHED;
;             PG8_LDB(B0, 1, 0); PG8_LDB(B1, 1, 1); PG8_SCHED; PG8_LDA(At, 1, 0); PG8_STAGE(PG8_SA(0, 1), a2 + hstepA, voffA);
;             PG8_WAIT_V(8); PG8_WAIT_L(0); PG8_BAR; PG8_MMA(0, 0, At, B0); PG8_MMA(0, 1, At, B1); PG8_BAR; PG8_SCHED;
;             PG8_LDA(At, 1, 1); PG8_STAGE(PG8_SB(1, 0), b3, voffB); PG8_STAGE(PG8_SB(1, 1), b3 + hstepB, voffB); PG8_STAGE(PG8_SA(1, 0), a3, voffA);
;             PG8_WAIT_V(8); PG8_WAIT_L(0); PG8_BAR; PG8_MMA(1, 0, At, B0); PG8_MMA(1, 1, At, B1); PG8_BAR; PG8_SCHED;
.LBB0_1128:
	s_add_u32 s36, s34, 0x4000
	s_addc_u32 s37, s35, 0
	s_cmp_eq_u32 s57, 28
	s_cselect_b32 s86, s29, s36
	s_cselect_b32 s87, s23, s37
	s_cselect_b32 s46, s31, s44
	s_cselect_b32 s47, s21, s56
	s_add_u32 s36, s86, 0x8000
	s_addc_u32 s37, s87, 0
	s_add_i32 s65, 0, 0x10000
	v_add_u32_e32 v0, s65, v242
	s_add_i32 s66, 0, 0x14000
	s_waitcnt lgkmcnt(0)
	ds_read_b128 v[130:133], v0
	ds_read_b128 v[134:137], v0 offset:1024
	ds_read_b128 v[138:141], v0 offset:2048
	ds_read_b128 v[142:145], v0 offset:3072
	v_add_u32_e32 v0, s66, v242
	ds_read_b128 v[146:149], v0
	ds_read_b128 v[150:153], v0 offset:1024
	ds_read_b128 v[154:157], v0 offset:2048
	ds_read_b128 v[158:161], v0 offset:3072
	s_add_i32 m0, s51, 0xc000
	ds_read_b128 v[162:165], v243
	ds_read_b128 v[166:169], v243 offset:1024
	ds_read_b128 v[170:173], v243 offset:2048
	ds_read_b128 v[174:177], v243 offset:3072
	ds_read_b128 v[178:181], v243 offset:4096
	ds_read_b128 v[182:185], v243 offset:5120
	ds_read_b128 v[198:201], v243 offset:6144
	ds_read_b128 v[202:205], v243 offset:7168
	global_load_lds_dwordx4 v194, s[34:35]
	s_add_i32 m0, s51, 0xe000
	s_nop 0
	global_load_lds_dwordx4 v196, s[34:35]
	s_waitcnt vmcnt(8)
	s_waitcnt lgkmcnt(0)
	s_barrier
	s_setprio 1
	v_mfma_f32_16x16x32_bf16 v[126:129], v[130:133], v[162:165], v[126:129]
	v_mfma_f32_16x16x32_bf16 v[126:129], v[134:137], v[166:169], v[126:129]
	v_mfma_f32_16x16x32_bf16 v[122:125], v[142:145], v[166:169], v[122:125]
	v_mfma_f32_16x16x32_bf16 v[122:125], v[138:141], v[162:165], v[122:125]
	v_mfma_f32_16x16x32_bf16 v[106:109], v[138:141], v[170:173], v[106:109]
	v_mfma_f32_16x16x32_bf16 v[106:109], v[142:145], v[174:177], v[106:109]
	v_mfma_f32_16x16x32_bf16 v[110:113], v[134:137], v[174:177], v[110:113]
	v_mfma_f32_16x16x32_bf16 v[110:113], v[130:133], v[170:173], v[110:113]
	v_mfma_f32_16x16x32_bf16 v[94:97], v[130:133], v[178:181], v[94:97]
	v_mfma_f32_16x16x32_bf16 v[94:97], v[134:137], v[182:185], v[94:97]
	v_mfma_f32_16x16x32_bf16 v[90:93], v[142:145], v[182:185], v[90:93]
	v_mfma_f32_16x16x32_bf16 v[90:93], v[138:141], v[178:181], v[90:93]
	v_mfma_f32_16x16x32_bf16 v[74:77], v[138:141], v[198:201], v[74:77]
	v_mfma_f32_16x16x32_bf16 v[74:77], v[142:145], v[202:205], v[74:77]
	v_mfma_f32_16x16x32_bf16 v[78:81], v[134:137], v[202:205], v[78:81]
	v_mfma_f32_16x16x32_bf16 v[78:81], v[130:133], v[198:201], v[78:81]
	s_setprio 0
	s_setprio 1
	v_mfma_f32_16x16x32_bf16 v[118:121], v[146:149], v[162:165], v[118:121]
	v_mfma_f32_16x16x32_bf16 v[118:121], v[150:153], v[166:169], v[118:121]
	v_mfma_f32_16x16x32_bf16 v[114:117], v[158:161], v[166:169], v[114:117]
	v_mfma_f32_16x16x32_bf16 v[114:117], v[154:157], v[162:165], v[114:117]
	v_mfma_f32_16x16x32_bf16 v[98:101], v[154:157], v[170:173], v[98:101]
	v_mfma_f32_16x16x32_bf16 v[98:101], v[158:161], v[174:177], v[98:101]
	v_mfma_f32_16x16x32_bf16 v[102:105], v[150:153], v[174:177], v[102:105]
	v_mfma_f32_16x16x32_bf16 v[102:105], v[146:149], v[170:173], v[102:105]
	v_mfma_f32_16x16x32_bf16 v[86:89], v[146:149], v[178:181], v[86:89]
	v_mfma_f32_16x16x32_bf16 v[86:89], v[150:153], v[182:185], v[86:89]
	v_mfma_f32_16x16x32_bf16 v[82:85], v[158:161], v[182:185], v[82:85]
	v_mfma_f32_16x16x32_bf16 v[82:85], v[154:157], v[178:181], v[82:85]
	v_mfma_f32_16x16x32_bf16 v[66:69], v[154:157], v[198:201], v[66:69]
	v_mfma_f32_16x16x32_bf16 v[66:69], v[158:161], v[202:205], v[66:69]
	v_mfma_f32_16x16x32_bf16 v[70:73], v[150:153], v[202:205], v[70:73]
	v_mfma_f32_16x16x32_bf16 v[70:73], v[146:149], v[198:201], v[70:73]
	s_setprio 0
	s_barrier
	s_add_i32 s65, s65, s49
	s_mov_b32 m0, s65
	ds_read_b128 v[162:165], v243 offset:16384
	ds_read_b128 v[166:169], v243 offset:17408
	ds_read_b128 v[170:173], v243 offset:18432
	ds_read_b128 v[174:177], v243 offset:19456
	ds_read_b128 v[178:181], v243 offset:20480
	ds_read_b128 v[182:185], v243 offset:21504
	ds_read_b128 v[198:201], v243 offset:22528
	ds_read_b128 v[202:205], v243 offset:23552
	global_load_lds_dwordx4 v188, s[46:47]
	s_add_i32 m0, s65, 0x2000
	s_add_u32 s90, s46, 0x4000
	s_addc_u32 s91, s47, 0
	s_add_i32 s65, s66, s49
	global_load_lds_dwordx4 v192, s[46:47]
	s_mov_b32 m0, s65
	s_nop 0
	global_load_lds_dwordx4 v188, s[90:91]
	s_add_i32 m0, s65, 0x2000
	s_nop 0
	global_load_lds_dwordx4 v192, s[90:91]
	s_mov_b32 m0, s51
	s_nop 0
	global_load_lds_dwordx4 v186, s[86:87]
	s_mov_b32 m0, s54
	s_nop 0
	global_load_lds_dwordx4 v190, s[86:87]
	s_waitcnt vmcnt(8)
	s_waitcnt lgkmcnt(0)
	s_barrier
	s_setprio 1
	v_mfma_f32_16x16x32_bf16 v[62:65], v[130:133], v[162:165], v[62:65]
	v_mfma_f32_16x16x32_bf16 v[62:65], v[134:137], v[166:169], v[62:65]
	v_mfma_f32_16x16x32_bf16 v[58:61], v[142:145], v[166:169], v[58:61]
	v_mfma_f32_16x16x32_bf16 v[58:61], v[138:141], v[162:165], v[58:61]
	v_mfma_f32_16x16x32_bf16 v[42:45], v[138:141], v[170:173], v[42:45]
	v_mfma_f32_16x16x32_bf16 v[42:45], v[142:145], v[174:177], v[42:45]
	v_mfma_f32_16x16x32_bf16 v[46:49], v[134:137], v[174:177], v[46:49]
	v_mfma_f32_16x16x32_bf16 v[46:49], v[130:133], v[170:173], v[46:49]
	v_mfma_f32_16x16x32_bf16 v[30:33], v[130:133], v[178:181], v[30:33]
	v_mfma_f32_16x16x32_bf16 v[30:33], v[134:137], v[182:185], v[30:33]
	v_mfma_f32_16x16x32_bf16 v[26:29], v[142:145], v[182:185], v[26:29]
	v_mfma_f32_16x16x32_bf16 v[26:29], v[138:141], v[178:181], v[26:29]
	v_mfma_f32_16x16x32_bf16 v[10:13], v[138:141], v[198:201], v[10:13]
	v_mfma_f32_16x16x32_bf16 v[10:13], v[142:145], v[202:205], v[10:13]
	v_mfma_f32_16x16x32_bf16 v[14:17], v[134:137], v[202:205], v[14:17]
	v_mfma_f32_16x16x32_bf16 v[14:17], v[130:133], v[198:201], v[14:17]
	s_setprio 0
	s_setprio 1
	v_mfma_f32_16x16x32_bf16 v[54:57], v[146:149], v[162:165], v[54:57]
	v_mfma_f32_16x16x32_bf16 v[54:57], v[150:153], v[166:169], v[54:57]
	v_mfma_f32_16x16x32_bf16 v[50:53], v[158:161], v[166:169], v[50:53]
	v_mfma_f32_16x16x32_bf16 v[50:53], v[154:157], v[162:165], v[50:53]
	v_mfma_f32_16x16x32_bf16 v[34:37], v[154:157], v[170:173], v[34:37]
	v_mfma_f32_16x16x32_bf16 v[34:37], v[158:161], v[174:177], v[34:37]
	v_mfma_f32_16x16x32_bf16 v[38:41], v[150:153], v[174:177], v[38:41]
	v_mfma_f32_16x16x32_bf16 v[38:41], v[146:149], v[170:173], v[38:41]
	v_mfma_f32_16x16x32_bf16 v[22:25], v[146:149], v[178:181], v[22:25]
	v_mfma_f32_16x16x32_bf16 v[22:25], v[150:153], v[182:185], v[22:25]
	v_mfma_f32_16x16x32_bf16 v[18:21], v[158:161], v[182:185], v[18:21]
	v_mfma_f32_16x16x32_bf16 v[18:21], v[154:157], v[178:181], v[18:21]
	v_mfma_f32_16x16x32_bf16 v[2:5], v[154:157], v[198:201], v[2:5]
	v_mfma_f32_16x16x32_bf16 v[2:5], v[158:161], v[202:205], v[2:5]
	v_mfma_f32_16x16x32_bf16 v[6:9], v[150:153], v[202:205], v[6:9]
	v_mfma_f32_16x16x32_bf16 v[6:9], v[146:149], v[198:201], v[6:9]
	s_setprio 0
	s_barrier
; #define PG8_STAGE(bufoff, gbase, voff) do { _Pragma("unroll") for (int _i = 0; _i < 2; ++_i) \
;         __builtin_amdgcn_global_load_lds((const unsigned*)((const char*)(gbase) + (voff)[_i]), (PG8_LAS unsigned*)(lds + (bufoff) + ldsw + _i * 8192), 16, 0, 0); } while (0)
; #define PG8_LDA(dst, b, h) do { _Pragma("unroll") for (int m = 0; m < 4; ++m) _Pragma("unroll") for (int k = 0; k < 2; ++k) dst[m][k] = *(const PG8_LAS bf16x8*)(lds + PG8_SA(b, h) + aoff + m * 2048 + k * 1024); } while (0)
; #define PG8_LDB(dst, b, h) do { _Pragma("unroll") for (int n = 0; n < 2; ++n) _Pragma("unroll") for (int k = 0; k < 2; ++k) dst[n][k] = *(const PG8_LAS bf16x8*)(lds + PG8_SB(b, h) + boff + n * 2048 + k * 1024); } while (0)
; #define PG8_WAIT_V(n) asm volatile("s_waitcnt vmcnt(" #n ")" ::: "memory")
; #define PG8_WAIT_L(n) asm volatile("s_waitcnt lgkmcnt(" #n ")" ::: "memory")
;     ...
;         for (int t = 0; t < nt; t += 2) {
;             const bool last = (t == nt - 2);
;             const char* a1 = cA + (ptrdiff_t)(t + 1) * kstepA;
;             const char* a2 = last ? nA : cA + (ptrdiff_t)(t + 2) * kstepA; const char* b2 = last ? nB : cB + (ptrdiff_t)(t + 2) * kstep;
;             const char* a3 = a2 + kstepA; const char* b3 = b2 + kstep;
;             if (last && has_next) S.a_ready(nxt);
;             if constexpr (SP2) {
;             PG8_LDB(B0, 0, 0); PG8_LDB(B1, 0, 1); PG8_SCHED; PG8_LDA(At, 0, 0); PG8_STAGE(PG8_SA(1, 1), a1 + hstepA, voffA);
;             PG8_WAIT_V(8); PG8_WAIT_L(0); PG8_BAR; PG8_MMA(0, 0, At, B0); PG8_MMA(0, 1, At, B1); PG8_BAR; PG8_SCHED;
;             PG8_LDA(At, 0, 1); PG8_STAGE(PG8_SB(0, 0), b2, voffB); PG8_STAGE(PG8_SB(0, 1), b2 + hstepB, voffB); PG8_STAGE(PG8_SA(0, 0), a2, voffA);
;             PG8_WAIT_V(8); PG8_WAIT_L(0); PG8_BAR; PG8_MMA(1, 0, At, B0); PG8_MMA(1, 1, At, B1); PG8_BAR; PG8_SCHED;
;             PG8_LDB(B0, 1, 0); PG8_LDB(B1, 1, 1); PG8_SCHED; PG8_LDA(At, 1, 0); PG8_STAGE(PG8_SA(0, 1), a2 + hstepA, voffA);
;             PG8_WAIT_V(8); PG8_WAIT_L(0); PG8_BAR; PG8_MMA(0, 0, At, B0); PG8_MMA(0, 1, At, B1); PG8_BAR; PG8_SCHED;
;             PG8_LDA(At, 1, 1); PG8_STAGE(PG8_SB(1, 0), b3, voffB); PG8_STAGE(PG8_SB(1, 1), b3 + hstepB, voffB); PG8_STAGE(PG8_SA(1, 0), a3, voffA);
;             PG8_WAIT_V(8); PG8_WAIT_L(0); PG8_BAR; PG8_MMA(1, 0, At, B0); PG8_MMA(1, 1, At, B1); PG8_BAR; PG8_SCHED;
.Lout_mid:
	s_add_i32 s65, 0, 0x18000
	v_add_u32_e32 v0, s65, v242
	s_add_i32 s66, 0, 0x1c000
	ds_read_b128 v[130:133], v0
	ds_read_b128 v[134:137], v0 offset:1024
	ds_read_b128 v[138:141], v0 offset:2048
	ds_read_b128 v[142:145], v0 offset:3072
	v_add_u32_e32 v0, s66, v242
	ds_read_b128 v[146:149], v0
	ds_read_b128 v[150:153], v0 offset:1024
	ds_read_b128 v[154:157], v0 offset:2048
	ds_read_b128 v[158:161], v0 offset:3072
	s_add_u32 s86, s86, 0x4000
	s_addc_u32 s87, s87, 0
	s_mov_b32 m0, s55
	ds_read_b128 v[162:165], v243 offset:32768
	ds_read_b128 v[166:169], v243 offset:33792
	ds_read_b128 v[170:173], v243 offset:34816
	ds_read_b128 v[174:177], v243 offset:35840
	ds_read_b128 v[178:181], v243 offset:36864
	ds_read_b128 v[182:185], v243 offset:37888
	ds_read_b128 v[198:201], v243 offset:38912
	ds_read_b128 v[202:205], v243 offset:39936
	global_load_lds_dwordx4 v186, s[86:87]
	s_mov_b32 m0, s61
	s_nop 0
	global_load_lds_dwordx4 v190, s[86:87]
	s_waitcnt vmcnt(8)
	s_waitcnt lgkmcnt(0)
	s_barrier
	s_setprio 1
	v_mfma_f32_16x16x32_bf16 v[126:129], v[130:133], v[162:165], v[126:129]
	v_mfma_f32_16x16x32_bf16 v[126:129], v[134:137], v[166:169], v[126:129]
	v_mfma_f32_16x16x32_bf16 v[122:125], v[142:145], v[166:169], v[122:125]
	v_mfma_f32_16x16x32_bf16 v[122:125], v[138:141], v[162:165], v[122:125]
	v_mfma_f32_16x16x32_bf16 v[106:109], v[138:141], v[170:173], v[106:109]
	v_mfma_f32_16x16x32_bf16 v[106:109], v[142:145], v[174:177], v[106:109]
	v_mfma_f32_16x16x32_bf16 v[110:113], v[134:137], v[174:177], v[110:113]
	v_mfma_f32_16x16x32_bf16 v[110:113], v[130:133], v[170:173], v[110:113]
	v_mfma_f32_16x16x32_bf16 v[94:97], v[130:133], v[178:181], v[94:97]
	v_mfma_f32_16x16x32_bf16 v[94:97], v[134:137], v[182:185], v[94:97]
	v_mfma_f32_16x16x32_bf16 v[90:93], v[142:145], v[182:185], v[90:93]
	v_mfma_f32_16x16x32_bf16 v[90:93], v[138:141], v[178:181], v[90:93]
	v_mfma_f32_16x16x32_bf16 v[74:77], v[138:141], v[198:201], v[74:77]
	v_mfma_f32_16x16x32_bf16 v[74:77], v[142:145], v[202:205], v[74:77]
	v_mfma_f32_16x16x32_bf16 v[78:81], v[134:137], v[202:205], v[78:81]
	v_mfma_f32_16x16x32_bf16 v[78:81], v[130:133], v[198:201], v[78:81]
	s_setprio 0
	s_setprio 1
	v_mfma_f32_16x16x32_bf16 v[118:121], v[146:149], v[162:165], v[118:121]
	v_mfma_f32_16x16x32_bf16 v[118:121], v[150:153], v[166:169], v[118:121]
	v_mfma_f32_16x16x32_bf16 v[114:117], v[158:161], v[166:169], v[114:117]
	v_mfma_f32_16x16x32_bf16 v[114:117], v[154:157], v[162:165], v[114:117]
	v_mfma_f32_16x16x32_bf16 v[98:101], v[154:157], v[170:173], v[98:101]
	v_mfma_f32_16x16x32_bf16 v[98:101], v[158:161], v[174:177], v[98:101]
	v_mfma_f32_16x16x32_bf16 v[102:105], v[150:153], v[174:177], v[102:105]
	v_mfma_f32_16x16x32_bf16 v[102:105], v[146:149], v[170:173], v[102:105]
	v_mfma_f32_16x16x32_bf16 v[86:89], v[146:149], v[178:181], v[86:89]
	v_mfma_f32_16x16x32_bf16 v[86:89], v[150:153], v[182:185], v[86:89]
	v_mfma_f32_16x16x32_bf16 v[82:85], v[158:161], v[182:185], v[82:85]
	v_mfma_f32_16x16x32_bf16 v[82:85], v[154:157], v[178:181], v[82:85]
	v_mfma_f32_16x16x32_bf16 v[66:69], v[154:157], v[198:201], v[66:69]
	v_mfma_f32_16x16x32_bf16 v[66:69], v[158:161], v[202:205], v[66:69]
	v_mfma_f32_16x16x32_bf16 v[70:73], v[150:153], v[202:205], v[70:73]
	v_mfma_f32_16x16x32_bf16 v[70:73], v[146:149], v[198:201], v[70:73]
	s_setprio 0
	s_barrier
	s_add_u32 s86, s46, 0x8000
	s_addc_u32 s87, s47, 0
	s_add_i32 s65, s65, s49
	s_mov_b32 m0, s65
	ds_read_b128 v[162:165], v243 offset:49152
	ds_read_b128 v[166:169], v243 offset:50176
	ds_read_b128 v[170:173], v243 offset:51200
	ds_read_b128 v[174:177], v243 offset:52224
	ds_read_b128 v[178:181], v243 offset:53248
	ds_read_b128 v[182:185], v243 offset:54272
	ds_read_b128 v[198:201], v243 offset:55296
	ds_read_b128 v[202:205], v243 offset:56320
	global_load_lds_dwordx4 v188, s[86:87]
	s_add_i32 m0, s65, 0x2000
	s_add_u32 s46, s46, 0xc000
	s_addc_u32 s47, s47, 0
	s_add_i32 s65, s66, s49
	global_load_lds_dwordx4 v192, s[86:87]
	s_mov_b32 m0, s65
	s_nop 0
	global_load_lds_dwordx4 v188, s[46:47]
	s_add_i32 m0, s65, 0x2000
	s_nop 0
	global_load_lds_dwordx4 v192, s[46:47]
	s_mov_b32 m0, s83
	s_nop 0
	global_load_lds_dwordx4 v186, s[36:37]
	v_lshl_add_u64 v[206:207], s[36:37], 0, v[190:191]
	s_mov_b32 m0, s85
	s_nop 0
	global_load_lds_dwordx4 v[206:207], off
	s_waitcnt vmcnt(8)
	s_waitcnt lgkmcnt(0)
	s_barrier
	s_setprio 1
	v_mfma_f32_16x16x32_bf16 v[62:65], v[130:133], v[162:165], v[62:65]
	v_mfma_f32_16x16x32_bf16 v[62:65], v[134:137], v[166:169], v[62:65]
	v_mfma_f32_16x16x32_bf16 v[58:61], v[142:145], v[166:169], v[58:61]
	v_mfma_f32_16x16x32_bf16 v[58:61], v[138:141], v[162:165], v[58:61]
	v_mfma_f32_16x16x32_bf16 v[42:45], v[138:141], v[170:173], v[42:45]
	v_mfma_f32_16x16x32_bf16 v[42:45], v[142:145], v[174:177], v[42:45]
	v_mfma_f32_16x16x32_bf16 v[46:49], v[134:137], v[174:177], v[46:49]
	v_mfma_f32_16x16x32_bf16 v[46:49], v[130:133], v[170:173], v[46:49]
	v_mfma_f32_16x16x32_bf16 v[30:33], v[130:133], v[178:181], v[30:33]
	v_mfma_f32_16x16x32_bf16 v[30:33], v[134:137], v[182:185], v[30:33]
	v_mfma_f32_16x16x32_bf16 v[26:29], v[142:145], v[182:185], v[26:29]
	v_mfma_f32_16x16x32_bf16 v[26:29], v[138:141], v[178:181], v[26:29]
	v_mfma_f32_16x16x32_bf16 v[10:13], v[138:141], v[198:201], v[10:13]
	v_mfma_f32_16x16x32_bf16 v[10:13], v[142:145], v[202:205], v[10:13]
	v_mfma_f32_16x16x32_bf16 v[14:17], v[134:137], v[202:205], v[14:17]
	v_mfma_f32_16x16x32_bf16 v[14:17], v[130:133], v[198:201], v[14:17]
	s_setprio 0
	s_setprio 1
	v_mfma_f32_16x16x32_bf16 v[54:57], v[146:149], v[162:165], v[54:57]
	v_mfma_f32_16x16x32_bf16 v[54:57], v[150:153], v[166:169], v[54:57]
	v_mfma_f32_16x16x32_bf16 v[50:53], v[158:161], v[166:169], v[50:53]
	v_mfma_f32_16x16x32_bf16 v[50:53], v[154:157], v[162:165], v[50:53]
	v_mfma_f32_16x16x32_bf16 v[34:37], v[154:157], v[170:173], v[34:37]
	v_mfma_f32_16x16x32_bf16 v[34:37], v[158:161], v[174:177], v[34:37]
	v_mfma_f32_16x16x32_bf16 v[38:41], v[150:153], v[174:177], v[38:41]
	v_mfma_f32_16x16x32_bf16 v[38:41], v[146:149], v[170:173], v[38:41]
	v_mfma_f32_16x16x32_bf16 v[22:25], v[146:149], v[178:181], v[22:25]
	v_mfma_f32_16x16x32_bf16 v[22:25], v[150:153], v[182:185], v[22:25]
	v_mfma_f32_16x16x32_bf16 v[18:21], v[158:161], v[182:185], v[18:21]
	v_mfma_f32_16x16x32_bf16 v[18:21], v[154:157], v[178:181], v[18:21]
	v_mfma_f32_16x16x32_bf16 v[2:5], v[154:157], v[198:201], v[2:5]
	v_mfma_f32_16x16x32_bf16 v[2:5], v[158:161], v[202:205], v[2:5]
	v_mfma_f32_16x16x32_bf16 v[6:9], v[150:153], v[202:205], v[6:9]
	v_mfma_f32_16x16x32_bf16 v[6:9], v[146:149], v[198:201], v[6:9]
	s_setprio 0
	s_barrier
	s_add_i32 s57, s57, 2
	s_add_u32 s34, s34, 0x10000
	s_addc_u32 s35, s35, 0
	s_add_u32 s44, s44, 0x10000
	s_addc_u32 s56, s56, 0
	s_cmp_gt_u32 s57, 29
	s_cbranch_scc0 .LBB0_1128
	s_and_b64 vcc, exec, s[92:93]
	s_cbranch_vccz .LBB0_1131
	s_barrier

; #define PG8_STAGE(bufoff, gbase, voff) do { _Pragma("unroll") for (int _i = 0; _i < 2; ++_i) \
;         __builtin_amdgcn_global_load_lds((const unsigned*)((const char*)(gbase) + (voff)[_i]), (PG8_LAS unsigned*)(lds + (bufoff) + ldsw + _i * 8192), 16, 0, 0); } while (0)
; #define PG8_LDA(dst, b, h) do { _Pragma("unroll") for (int m = 0; m < 4; ++m) _Pragma("unroll") for (int k = 0; k < 2; ++k) dst[m][k] = *(const PG8_LAS bf16x8*)(lds + PG8_SA(b, h) + aoff + m * 2048 + k * 1024); } while (0)
; #define PG8_LDB(dst, b, h) do { _Pragma("unroll") for (int n = 0; n < 2; ++n) _Pragma("unroll") for (int k = 0; k < 2; ++k) dst[n][k] = *(const PG8_LAS bf16x8*)(lds + PG8_SB(b, h) + boff + n * 2048 + k * 1024); } while (0)
; #define PG8_MMA(ai, bj, At, Bt) do { __builtin_amdgcn_s_setprio(1); _Pragma("unroll") for (int m = 0; m < 4; ++m) _Pragma("unroll") for (int n = 0; n < 2; ++n) _Pragma("unroll") for (int k = 0; k < 2; ++k) \
;         acc[ai][bj][m][n] = __builtin_amdgcn_mfma_f32_16x16x32_bf16(Bt[n][k], At[m][k], acc[ai][bj][m][n], 0, 0, 0); __builtin_amdgcn_s_setprio(0); } while (0)
; #define PG8_WAIT_V(n) asm volatile("s_waitcnt vmcnt(" #n ")" ::: "memory")
; #define PG8_WAIT_L(n) asm volatile("s_waitcnt lgkmcnt(" #n ")" ::: "memory")
; #define PG8_BAR __builtin_amdgcn_s_barrier()
; #define PG8_SCHED __builtin_amdgcn_sched_barrier(0)
;     ...
;         for (int t = 0; t < nt; t += 2) {
;             const bool last = (t == nt - 2);
;             const char* a1 = cA + (ptrdiff_t)(t + 1) * kstepA;
;             const char* a2 = last ? nA : cA + (ptrdiff_t)(t + 2) * kstepA; const char* b2 = last ? nB : cB + (ptrdiff_t)(t + 2) * kstep;
;             const char* a3 = a2 + kstepA; const char* b3 = b2 + kstep;
;             if (last && has_next) S.a_ready(nxt);
;             if constexpr (SP2) {
;             PG8_LDB(B0, 0, 0); PG8_LDB(B1, 0, 1); PG8_SCHED; PG8_LDA(At, 0, 0); PG8_STAGE(PG8_SA(1, 1), a1 + hstepA, voffA);
;             PG8_WAIT_V(8); PG8_WAIT_L(0); PG8_BAR; PG8_MMA(0, 0, At, B0); PG8_MMA(0, 1, At, B1); PG8_BAR; PG8_SCHED;
;             PG8_LDA(At, 0, 1); PG8_STAGE(PG8_SB(0, 0), b2, voffB); PG8_STAGE(PG8_SB(0, 1), b2 + hstepB, voffB); PG8_STAGE(PG8_SA(0, 0), a2, voffA);
;             PG8_WAIT_V(8); PG8_WAIT_L(0); PG8_BAR; PG8_MMA(1, 0, At, B0); PG8_MMA(1, 1, At, B1); PG8_BAR; PG8_SCHED;
.Lup_nostg:
	s_add_u32 s36, s34, 0x10000
	s_addc_u32 s37, s35, 0
	s_cmp_eq_u32 s66, 28
	s_cselect_b32 s88, s57, s36
	s_cselect_b32 s89, s27, s37
	s_cselect_b32 s86, vcc_lo, vcc_hi
	s_cselect_b32 s87, s25, s65
	s_add_u32 s46, s88, 0x8000
	s_addc_u32 s47, s89, 0
	s_add_i32 s96, 0, 0x10000
	v_add_u32_e32 v0, s96, v192
	s_add_i32 s97, 0, 0x14000
	ds_read_b128 v[130:133], v0
	ds_read_b128 v[134:137], v0 offset:1024
	ds_read_b128 v[138:141], v0 offset:2048
	ds_read_b128 v[142:145], v0 offset:3072
	v_add_u32_e32 v0, s97, v192
	ds_read_b128 v[146:149], v0
	ds_read_b128 v[150:153], v0 offset:1024
	ds_read_b128 v[154:157], v0 offset:2048
	ds_read_b128 v[170:173], v0 offset:3072
	s_add_i32 m0, s48, 0xc000
	ds_read_b128 v[174:177], v193
	ds_read_b128 v[178:181], v193 offset:1024
	ds_read_b128 v[182:185], v193 offset:2048
	ds_read_b128 v[186:189], v193 offset:3072
	ds_read_b128 v[194:197], v193 offset:4096
	ds_read_b128 v[198:201], v193 offset:5120
	ds_read_b128 v[202:205], v193 offset:6144
	ds_read_b128 v[206:209], v193 offset:7168
	global_load_lds_dwordx4 v166, s[34:35]
	s_add_i32 m0, s48, 0xe000
	s_nop 0
	global_load_lds_dwordx4 v168, s[34:35]
	s_waitcnt vmcnt(8)
	s_waitcnt lgkmcnt(0)
	s_barrier
	s_setprio 1
	v_mfma_f32_16x16x32_bf16 v[126:129], v[130:133], v[174:177], 0
	v_mfma_f32_16x16x32_bf16 v[126:129], v[134:137], v[178:181], v[126:129]
	v_mfma_f32_16x16x32_bf16 v[122:125], v[142:145], v[178:181], 0
	v_mfma_f32_16x16x32_bf16 v[122:125], v[138:141], v[174:177], v[122:125]
	v_mfma_f32_16x16x32_bf16 v[114:117], v[138:141], v[182:185], 0
	v_mfma_f32_16x16x32_bf16 v[114:117], v[142:145], v[186:189], v[114:117]
	v_mfma_f32_16x16x32_bf16 v[118:121], v[134:137], v[186:189], 0
	v_mfma_f32_16x16x32_bf16 v[118:121], v[130:133], v[182:185], v[118:121]
	v_mfma_f32_16x16x32_bf16 v[110:113], v[130:133], v[194:197], 0
	v_mfma_f32_16x16x32_bf16 v[110:113], v[134:137], v[198:201], v[110:113]
	v_mfma_f32_16x16x32_bf16 v[106:109], v[142:145], v[198:201], 0
	v_mfma_f32_16x16x32_bf16 v[106:109], v[138:141], v[194:197], v[106:109]
	v_mfma_f32_16x16x32_bf16 v[98:101], v[138:141], v[202:205], 0
	v_mfma_f32_16x16x32_bf16 v[98:101], v[142:145], v[206:209], v[98:101]
	v_mfma_f32_16x16x32_bf16 v[102:105], v[134:137], v[206:209], 0
	v_mfma_f32_16x16x32_bf16 v[102:105], v[130:133], v[202:205], v[102:105]
	s_setprio 0
	s_setprio 1
	v_mfma_f32_16x16x32_bf16 v[30:33], v[146:149], v[174:177], 0
	v_mfma_f32_16x16x32_bf16 v[30:33], v[150:153], v[178:181], v[30:33]
	v_mfma_f32_16x16x32_bf16 v[46:49], v[170:173], v[178:181], 0
	v_mfma_f32_16x16x32_bf16 v[46:49], v[154:157], v[174:177], v[46:49]
	v_mfma_f32_16x16x32_bf16 v[34:37], v[154:157], v[182:185], 0
	v_mfma_f32_16x16x32_bf16 v[34:37], v[170:173], v[186:189], v[34:37]
	v_mfma_f32_16x16x32_bf16 v[26:29], v[150:153], v[186:189], 0
	v_mfma_f32_16x16x32_bf16 v[26:29], v[146:149], v[182:185], v[26:29]
	v_mfma_f32_16x16x32_bf16 v[94:97], v[146:149], v[194:197], 0
	v_mfma_f32_16x16x32_bf16 v[94:97], v[150:153], v[198:201], v[94:97]
	v_mfma_f32_16x16x32_bf16 v[90:93], v[170:173], v[198:201], 0
	v_mfma_f32_16x16x32_bf16 v[90:93], v[154:157], v[194:197], v[90:93]
	v_mfma_f32_16x16x32_bf16 v[82:85], v[154:157], v[202:205], 0
	v_mfma_f32_16x16x32_bf16 v[82:85], v[170:173], v[206:209], v[82:85]
	v_mfma_f32_16x16x32_bf16 v[86:89], v[150:153], v[206:209], 0
	v_mfma_f32_16x16x32_bf16 v[86:89], v[146:149], v[202:205], v[86:89]
	s_setprio 0
	s_barrier
	s_add_i32 s34, s96, s44
	s_mov_b32 m0, s34
	ds_read_b128 v[174:177], v193 offset:16384
	ds_read_b128 v[178:181], v193 offset:17408
	ds_read_b128 v[182:185], v193 offset:18432
	ds_read_b128 v[186:189], v193 offset:19456
	ds_read_b128 v[194:197], v193 offset:20480
	ds_read_b128 v[198:201], v193 offset:21504
	ds_read_b128 v[202:205], v193 offset:22528
	ds_read_b128 v[206:209], v193 offset:23552
	global_load_lds_dwordx4 v162, s[86:87]
	s_add_i32 m0, s34, 0x2000
	s_add_u32 s34, s86, 0x4000
	s_addc_u32 s35, s87, 0
	s_add_i32 s96, s97, s44
	global_load_lds_dwordx4 v158, s[86:87]
	s_mov_b32 m0, s96
	v_lshl_add_u64 v[210:211], s[88:89], 0, v[160:161]
	global_load_lds_dwordx4 v162, s[34:35]
	s_add_i32 m0, s96, 0x2000
	s_nop 0
	global_load_lds_dwordx4 v158, s[34:35]
	v_lshl_add_u64 v[190:191], s[88:89], 0, v[164:165]
	s_mov_b32 m0, s48
	s_nop 0
	global_load_lds_dwordx4 v[190:191], off
	s_mov_b32 m0, s49
	s_nop 0
	global_load_lds_dwordx4 v[210:211], off
	s_waitcnt vmcnt(8)
	s_waitcnt lgkmcnt(0)
	s_barrier
	s_setprio 1
	v_mfma_f32_16x16x32_bf16 v[78:81], v[130:133], v[174:177], 0
	v_mfma_f32_16x16x32_bf16 v[78:81], v[134:137], v[178:181], v[78:81]
	v_mfma_f32_16x16x32_bf16 v[74:77], v[142:145], v[178:181], 0
	v_mfma_f32_16x16x32_bf16 v[74:77], v[138:141], v[174:177], v[74:77]
	v_mfma_f32_16x16x32_bf16 v[66:69], v[138:141], v[182:185], 0
	v_mfma_f32_16x16x32_bf16 v[66:69], v[142:145], v[186:189], v[66:69]
	v_mfma_f32_16x16x32_bf16 v[70:73], v[134:137], v[186:189], 0
	v_mfma_f32_16x16x32_bf16 v[70:73], v[130:133], v[182:185], v[70:73]
	v_mfma_f32_16x16x32_bf16 v[42:45], v[130:133], v[194:197], 0
	v_mfma_f32_16x16x32_bf16 v[42:45], v[134:137], v[198:201], v[42:45]
	v_mfma_f32_16x16x32_bf16 v[6:9], v[142:145], v[198:201], 0
	v_mfma_f32_16x16x32_bf16 v[6:9], v[138:141], v[194:197], v[6:9]
	v_mfma_f32_16x16x32_bf16 v[2:5], v[138:141], v[202:205], 0
	v_mfma_f32_16x16x32_bf16 v[2:5], v[142:145], v[206:209], v[2:5]
	v_mfma_f32_16x16x32_bf16 v[38:41], v[134:137], v[206:209], 0
	v_mfma_f32_16x16x32_bf16 v[38:41], v[130:133], v[202:205], v[38:41]
	s_setprio 0
	s_setprio 1
	v_mfma_f32_16x16x32_bf16 v[62:65], v[146:149], v[174:177], 0
	v_mfma_f32_16x16x32_bf16 v[62:65], v[150:153], v[178:181], v[62:65]
	v_mfma_f32_16x16x32_bf16 v[58:61], v[170:173], v[178:181], 0
	v_mfma_f32_16x16x32_bf16 v[58:61], v[154:157], v[174:177], v[58:61]
	v_mfma_f32_16x16x32_bf16 v[50:53], v[154:157], v[182:185], 0
	v_mfma_f32_16x16x32_bf16 v[50:53], v[170:173], v[186:189], v[50:53]
	v_mfma_f32_16x16x32_bf16 v[54:57], v[150:153], v[186:189], 0
	v_mfma_f32_16x16x32_bf16 v[54:57], v[146:149], v[182:185], v[54:57]
	v_mfma_f32_16x16x32_bf16 v[22:25], v[146:149], v[194:197], 0
	v_mfma_f32_16x16x32_bf16 v[22:25], v[150:153], v[198:201], v[22:25]
	v_mfma_f32_16x16x32_bf16 v[18:21], v[170:173], v[198:201], 0
	v_mfma_f32_16x16x32_bf16 v[18:21], v[154:157], v[194:197], v[18:21]
	v_mfma_f32_16x16x32_bf16 v[10:13], v[154:157], v[202:205], 0
	v_mfma_f32_16x16x32_bf16 v[10:13], v[170:173], v[206:209], v[10:13]
	v_mfma_f32_16x16x32_bf16 v[14:17], v[150:153], v[206:209], 0
	v_mfma_f32_16x16x32_bf16 v[14:17], v[146:149], v[202:205], v[14:17]
	s_setprio 0
	s_barrier
	s_branch .Lup_mid

; #define PG8_STAGE(bufoff, gbase, voff) do { _Pragma("unroll") for (int _i = 0; _i < 2; ++_i) \
;         __builtin_amdgcn_global_load_lds((const unsigned*)((const char*)(gbase) + (voff)[_i]), (PG8_LAS unsigned*)(lds + (bufoff) + ldsw + _i * 8192), 16, 0, 0); } while (0)
; #define PG8_LDA(dst, b, h) do { _Pragma("unroll") for (int m = 0; m < 4; ++m) _Pragma("unroll") for (int k = 0; k < 2; ++k) dst[m][k] = *(const PG8_LAS bf16x8*)(lds + PG8_SA(b, h) + aoff + m * 2048 + k * 1024); } while (0)
; #define PG8_LDB(dst, b, h) do { _Pragma("unroll") for (int n = 0; n < 2; ++n) _Pragma("unroll") for (int k = 0; k < 2; ++k) dst[n][k] = *(const PG8_LAS bf16x8*)(lds + PG8_SB(b, h) + boff + n * 2048 + k * 1024); } while (0)
; #define PG8_MMA(ai, bj, At, Bt) do { __builtin_amdgcn_s_setprio(1); _Pragma("unroll") for (int m = 0; m < 4; ++m) _Pragma("unroll") for (int n = 0; n < 2; ++n) _Pragma("unroll") for (int k = 0; k < 2; ++k) \
;         acc[ai][bj][m][n] = __builtin_amdgcn_mfma_f32_16x16x32_bf16(Bt[n][k], At[m][k], acc[ai][bj][m][n], 0, 0, 0); __builtin_amdgcn_s_setprio(0); } while (0)
; #define PG8_WAIT_V(n) asm volatile("s_waitcnt vmcnt(" #n ")" ::: "memory")
; #define PG8_WAIT_L(n) asm volatile("s_waitcnt lgkmcnt(" #n ")" ::: "memory")
; #define PG8_BAR __builtin_amdgcn_s_barrier()
; #define PG8_SCHED __builtin_amdgcn_sched_barrier(0)
;     ...
;         for (int t = 0; t < nt; t += 2) {
;             const bool last = (t == nt - 2);
;             const char* a1 = cA + (ptrdiff_t)(t + 1) * kstepA;
;             const char* a2 = last ? nA : cA + (ptrdiff_t)(t + 2) * kstepA; const char* b2 = last ? nB : cB + (ptrdiff_t)(t + 2) * kstep;
;             const char* a3 = a2 + kstepA; const char* b3 = b2 + kstep;
;             if (last && has_next) S.a_ready(nxt);
;             if constexpr (SP2) {
;             PG8_LDB(B0, 0, 0); PG8_LDB(B1, 0, 1); PG8_SCHED; PG8_LDA(At, 0, 0); PG8_STAGE(PG8_SA(1, 1), a1 + hstepA, voffA);
;             PG8_WAIT_V(8); PG8_WAIT_L(0); PG8_BAR; PG8_MMA(0, 0, At, B0); PG8_MMA(0, 1, At, B1); PG8_BAR; PG8_SCHED;
;             PG8_LDA(At, 0, 1); PG8_STAGE(PG8_SB(0, 0), b2, voffB); PG8_STAGE(PG8_SB(0, 1), b2 + hstepB, voffB); PG8_STAGE(PG8_SA(0, 0), a2, voffA);
;             PG8_WAIT_V(8); PG8_WAIT_L(0); PG8_BAR; PG8_MMA(1, 0, At, B0); PG8_MMA(1, 1, At, B1); PG8_BAR; PG8_SCHED;
.LBB0_1256:
	s_add_u32 s36, s34, 0x10000
	s_addc_u32 s37, s35, 0
	s_cmp_eq_u32 s66, 28
	s_cselect_b32 s88, s57, s36
	s_cselect_b32 s89, s27, s37
	s_cselect_b32 s86, vcc_lo, vcc_hi
	s_cselect_b32 s87, s25, s65
	s_add_u32 s46, s88, 0x8000
	s_addc_u32 s47, s89, 0
	s_add_i32 s96, 0, 0x10000
	v_add_u32_e32 v0, s96, v192
	s_add_i32 s97, 0, 0x14000
	ds_read_b128 v[130:133], v0
	ds_read_b128 v[134:137], v0 offset:1024
	ds_read_b128 v[138:141], v0 offset:2048
	ds_read_b128 v[142:145], v0 offset:3072
	v_add_u32_e32 v0, s97, v192
	ds_read_b128 v[146:149], v0
	ds_read_b128 v[150:153], v0 offset:1024
	ds_read_b128 v[154:157], v0 offset:2048
	ds_read_b128 v[170:173], v0 offset:3072
	s_add_i32 m0, s48, 0xc000
	ds_read_b128 v[174:177], v193
	ds_read_b128 v[178:181], v193 offset:1024
	ds_read_b128 v[182:185], v193 offset:2048
	ds_read_b128 v[186:189], v193 offset:3072
	ds_read_b128 v[194:197], v193 offset:4096
	ds_read_b128 v[198:201], v193 offset:5120
	ds_read_b128 v[202:205], v193 offset:6144
	ds_read_b128 v[206:209], v193 offset:7168
	global_load_lds_dwordx4 v166, s[34:35]
	s_add_i32 m0, s48, 0xe000
	s_nop 0
	global_load_lds_dwordx4 v168, s[34:35]
	s_waitcnt vmcnt(8)
	s_waitcnt lgkmcnt(0)
	s_barrier
	s_setprio 1
	v_mfma_f32_16x16x32_bf16 v[126:129], v[130:133], v[174:177], v[126:129]
	v_mfma_f32_16x16x32_bf16 v[126:129], v[134:137], v[178:181], v[126:129]
	v_mfma_f32_16x16x32_bf16 v[122:125], v[142:145], v[178:181], v[122:125]
	v_mfma_f32_16x16x32_bf16 v[122:125], v[138:141], v[174:177], v[122:125]
	v_mfma_f32_16x16x32_bf16 v[114:117], v[138:141], v[182:185], v[114:117]
	v_mfma_f32_16x16x32_bf16 v[114:117], v[142:145], v[186:189], v[114:117]
	v_mfma_f32_16x16x32_bf16 v[118:121], v[134:137], v[186:189], v[118:121]
	v_mfma_f32_16x16x32_bf16 v[118:121], v[130:133], v[182:185], v[118:121]
	v_mfma_f32_16x16x32_bf16 v[110:113], v[130:133], v[194:197], v[110:113]
	v_mfma_f32_16x16x32_bf16 v[110:113], v[134:137], v[198:201], v[110:113]
	v_mfma_f32_16x16x32_bf16 v[106:109], v[142:145], v[198:201], v[106:109]
	v_mfma_f32_16x16x32_bf16 v[106:109], v[138:141], v[194:197], v[106:109]
	v_mfma_f32_16x16x32_bf16 v[98:101], v[138:141], v[202:205], v[98:101]
	v_mfma_f32_16x16x32_bf16 v[98:101], v[142:145], v[206:209], v[98:101]
	v_mfma_f32_16x16x32_bf16 v[102:105], v[134:137], v[206:209], v[102:105]
	v_mfma_f32_16x16x32_bf16 v[102:105], v[130:133], v[202:205], v[102:105]
	s_setprio 0
	s_setprio 1
	v_mfma_f32_16x16x32_bf16 v[30:33], v[146:149], v[174:177], v[30:33]
	v_mfma_f32_16x16x32_bf16 v[30:33], v[150:153], v[178:181], v[30:33]
	v_mfma_f32_16x16x32_bf16 v[46:49], v[170:173], v[178:181], v[46:49]
	v_mfma_f32_16x16x32_bf16 v[46:49], v[154:157], v[174:177], v[46:49]
	v_mfma_f32_16x16x32_bf16 v[34:37], v[154:157], v[182:185], v[34:37]
	v_mfma_f32_16x16x32_bf16 v[34:37], v[170:173], v[186:189], v[34:37]
	v_mfma_f32_16x16x32_bf16 v[26:29], v[150:153], v[186:189], v[26:29]
	v_mfma_f32_16x16x32_bf16 v[26:29], v[146:149], v[182:185], v[26:29]
	v_mfma_f32_16x16x32_bf16 v[94:97], v[146:149], v[194:197], v[94:97]
	v_mfma_f32_16x16x32_bf16 v[94:97], v[150:153], v[198:201], v[94:97]
	v_mfma_f32_16x16x32_bf16 v[90:93], v[170:173], v[198:201], v[90:93]
	v_mfma_f32_16x16x32_bf16 v[90:93], v[154:157], v[194:197], v[90:93]
	v_mfma_f32_16x16x32_bf16 v[82:85], v[154:157], v[202:205], v[82:85]
	v_mfma_f32_16x16x32_bf16 v[82:85], v[170:173], v[206:209], v[82:85]
	v_mfma_f32_16x16x32_bf16 v[86:89], v[150:153], v[206:209], v[86:89]
	v_mfma_f32_16x16x32_bf16 v[86:89], v[146:149], v[202:205], v[86:89]
	s_setprio 0
	s_barrier
	s_add_i32 s34, s96, s44
	s_mov_b32 m0, s34
	ds_read_b128 v[174:177], v193 offset:16384
	ds_read_b128 v[178:181], v193 offset:17408
	ds_read_b128 v[182:185], v193 offset:18432
	ds_read_b128 v[186:189], v193 offset:19456
	ds_read_b128 v[194:197], v193 offset:20480
	ds_read_b128 v[198:201], v193 offset:21504
	ds_read_b128 v[202:205], v193 offset:22528
	ds_read_b128 v[206:209], v193 offset:23552
	global_load_lds_dwordx4 v162, s[86:87]
	s_add_i32 m0, s34, 0x2000
	s_add_u32 s34, s86, 0x4000
	s_addc_u32 s35, s87, 0
	s_add_i32 s96, s97, s44
	global_load_lds_dwordx4 v158, s[86:87]
	s_mov_b32 m0, s96
	v_lshl_add_u64 v[210:211], s[88:89], 0, v[160:161]
	global_load_lds_dwordx4 v162, s[34:35]
	s_add_i32 m0, s96, 0x2000
	s_nop 0
	global_load_lds_dwordx4 v158, s[34:35]
	v_lshl_add_u64 v[190:191], s[88:89], 0, v[164:165]
	s_mov_b32 m0, s48
	s_nop 0
	global_load_lds_dwordx4 v[190:191], off
	s_mov_b32 m0, s49
	s_nop 0
	global_load_lds_dwordx4 v[210:211], off
	s_waitcnt vmcnt(8)
	s_waitcnt lgkmcnt(0)
	s_barrier
	s_setprio 1
	v_mfma_f32_16x16x32_bf16 v[78:81], v[130:133], v[174:177], v[78:81]
	v_mfma_f32_16x16x32_bf16 v[78:81], v[134:137], v[178:181], v[78:81]
	v_mfma_f32_16x16x32_bf16 v[74:77], v[142:145], v[178:181], v[74:77]
	v_mfma_f32_16x16x32_bf16 v[74:77], v[138:141], v[174:177], v[74:77]
	v_mfma_f32_16x16x32_bf16 v[66:69], v[138:141], v[182:185], v[66:69]
	v_mfma_f32_16x16x32_bf16 v[66:69], v[142:145], v[186:189], v[66:69]
	v_mfma_f32_16x16x32_bf16 v[70:73], v[134:137], v[186:189], v[70:73]
	v_mfma_f32_16x16x32_bf16 v[70:73], v[130:133], v[182:185], v[70:73]
	v_mfma_f32_16x16x32_bf16 v[42:45], v[130:133], v[194:197], v[42:45]
	v_mfma_f32_16x16x32_bf16 v[42:45], v[134:137], v[198:201], v[42:45]
	v_mfma_f32_16x16x32_bf16 v[6:9], v[142:145], v[198:201], v[6:9]
	v_mfma_f32_16x16x32_bf16 v[6:9], v[138:141], v[194:197], v[6:9]
	v_mfma_f32_16x16x32_bf16 v[2:5], v[138:141], v[202:205], v[2:5]
	v_mfma_f32_16x16x32_bf16 v[2:5], v[142:145], v[206:209], v[2:5]
	v_mfma_f32_16x16x32_bf16 v[38:41], v[134:137], v[206:209], v[38:41]
	v_mfma_f32_16x16x32_bf16 v[38:41], v[130:133], v[202:205], v[38:41]
	s_setprio 0
	s_setprio 1
	v_mfma_f32_16x16x32_bf16 v[62:65], v[146:149], v[174:177], v[62:65]
	v_mfma_f32_16x16x32_bf16 v[62:65], v[150:153], v[178:181], v[62:65]
	v_mfma_f32_16x16x32_bf16 v[58:61], v[170:173], v[178:181], v[58:61]
	v_mfma_f32_16x16x32_bf16 v[58:61], v[154:157], v[174:177], v[58:61]
	v_mfma_f32_16x16x32_bf16 v[50:53], v[154:157], v[182:185], v[50:53]
	v_mfma_f32_16x16x32_bf16 v[50:53], v[170:173], v[186:189], v[50:53]
	v_mfma_f32_16x16x32_bf16 v[54:57], v[150:153], v[186:189], v[54:57]
	v_mfma_f32_16x16x32_bf16 v[54:57], v[146:149], v[182:185], v[54:57]
	v_mfma_f32_16x16x32_bf16 v[22:25], v[146:149], v[194:197], v[22:25]
	v_mfma_f32_16x16x32_bf16 v[22:25], v[150:153], v[198:201], v[22:25]
	v_mfma_f32_16x16x32_bf16 v[18:21], v[170:173], v[198:201], v[18:21]
	v_mfma_f32_16x16x32_bf16 v[18:21], v[154:157], v[194:197], v[18:21]
	v_mfma_f32_16x16x32_bf16 v[10:13], v[154:157], v[202:205], v[10:13]
	v_mfma_f32_16x16x32_bf16 v[10:13], v[170:173], v[206:209], v[10:13]
	v_mfma_f32_16x16x32_bf16 v[14:17], v[150:153], v[206:209], v[14:17]
	v_mfma_f32_16x16x32_bf16 v[14:17], v[146:149], v[202:205], v[14:17]
	s_setprio 0
	s_barrier
; #define PG8_STAGE(bufoff, gbase, voff) do { _Pragma("unroll") for (int _i = 0; _i < 2; ++_i) \
;         __builtin_amdgcn_global_load_lds((const unsigned*)((const char*)(gbase) + (voff)[_i]), (PG8_LAS unsigned*)(lds + (bufoff) + ldsw + _i * 8192), 16, 0, 0); } while (0)
; #define PG8_LDA(dst, b, h) do { _Pragma("unroll") for (int m = 0; m < 4; ++m) _Pragma("unroll") for (int k = 0; k < 2; ++k) dst[m][k] = *(const PG8_LAS bf16x8*)(lds + PG8_SA(b, h) + aoff + m * 2048 + k * 1024); } while (0)
; #define PG8_LDB(dst, b, h) do { _Pragma("unroll") for (int n = 0; n < 2; ++n) _Pragma("unroll") for (int k = 0; k < 2; ++k) dst[n][k] = *(const PG8_LAS bf16x8*)(lds + PG8_SB(b, h) + boff + n * 2048 + k * 1024); } while (0)
; #define PG8_MMA(ai, bj, At, Bt) do { __builtin_amdgcn_s_setprio(1); _Pragma("unroll") for (int m = 0; m < 4; ++m) _Pragma("unroll") for (int n = 0; n < 2; ++n) _Pragma("unroll") for (int k = 0; k < 2; ++k) \
;         acc[ai][bj][m][n] = __builtin_amdgcn_mfma_f32_16x16x32_bf16(Bt[n][k], At[m][k], acc[ai][bj][m][n], 0, 0, 0); __builtin_amdgcn_s_setprio(0); } while (0)
; #define PG8_WAIT_V(n) asm volatile("s_waitcnt vmcnt(" #n ")" ::: "memory")
; #define PG8_WAIT_L(n) asm volatile("s_waitcnt lgkmcnt(" #n ")" ::: "memory")
; #define PG8_BAR __builtin_amdgcn_s_barrier()
; #define PG8_SCHED __builtin_amdgcn_sched_barrier(0)
;     ...
;             PG8_LDB(B0, 1, 0); PG8_LDB(B1, 1, 1); PG8_SCHED; PG8_LDA(At, 1, 0); PG8_STAGE(PG8_SA(0, 1), a2 + hstepA, voffA);
;             PG8_WAIT_V(8); PG8_WAIT_L(0); PG8_BAR; PG8_MMA(0, 0, At, B0); PG8_MMA(0, 1, At, B1); PG8_BAR; PG8_SCHED;
;             PG8_LDA(At, 1, 1); PG8_STAGE(PG8_SB(1, 0), b3, voffB); PG8_STAGE(PG8_SB(1, 1), b3 + hstepB, voffB); PG8_STAGE(PG8_SA(1, 0), a3, voffA);
;             PG8_WAIT_V(8); PG8_WAIT_L(0); PG8_BAR; PG8_MMA(1, 0, At, B0); PG8_MMA(1, 1, At, B1); PG8_BAR; PG8_SCHED;
;     ...
;         if constexpr (ALIGN_EPI) { if (wr == 0) PG8_BAR; }
.Lup_mid:
	s_add_i32 s88, 0, 0x18000
	v_add_u32_e32 v0, s88, v192
	s_add_i32 s89, 0, 0x1c000
	ds_read_b128 v[130:133], v0
	ds_read_b128 v[134:137], v0 offset:1024
	ds_read_b128 v[138:141], v0 offset:2048
	ds_read_b128 v[142:145], v0 offset:3072
	v_add_u32_e32 v0, s89, v192
	ds_read_b128 v[146:149], v0
	ds_read_b128 v[150:153], v0 offset:1024
	ds_read_b128 v[154:157], v0 offset:2048
	ds_read_b128 v[170:173], v0 offset:3072
	s_mov_b32 m0, s51
	v_lshl_add_u64 v[190:191], v[190:191], 0, s[58:59]
	ds_read_b128 v[174:177], v193 offset:32768
	ds_read_b128 v[178:181], v193 offset:33792
	ds_read_b128 v[182:185], v193 offset:34816
	ds_read_b128 v[186:189], v193 offset:35840
	ds_read_b128 v[194:197], v193 offset:36864
	ds_read_b128 v[198:201], v193 offset:37888
	ds_read_b128 v[202:205], v193 offset:38912
	ds_read_b128 v[206:209], v193 offset:39936
	global_load_lds_dwordx4 v[190:191], off
	v_lshl_add_u64 v[190:191], v[210:211], 0, s[58:59]
	s_mov_b32 m0, s54
	s_nop 0
	global_load_lds_dwordx4 v[190:191], off
	s_waitcnt vmcnt(8)
	s_waitcnt lgkmcnt(0)
	s_barrier
	s_setprio 1
	v_mfma_f32_16x16x32_bf16 v[126:129], v[130:133], v[174:177], v[126:129]
	v_mfma_f32_16x16x32_bf16 v[126:129], v[134:137], v[178:181], v[126:129]
	v_mfma_f32_16x16x32_bf16 v[122:125], v[142:145], v[178:181], v[122:125]
	v_mfma_f32_16x16x32_bf16 v[122:125], v[138:141], v[174:177], v[122:125]
	v_mfma_f32_16x16x32_bf16 v[114:117], v[138:141], v[182:185], v[114:117]
	v_mfma_f32_16x16x32_bf16 v[114:117], v[142:145], v[186:189], v[114:117]
	v_mfma_f32_16x16x32_bf16 v[118:121], v[134:137], v[186:189], v[118:121]
	v_mfma_f32_16x16x32_bf16 v[118:121], v[130:133], v[182:185], v[118:121]
	v_mfma_f32_16x16x32_bf16 v[110:113], v[130:133], v[194:197], v[110:113]
	v_mfma_f32_16x16x32_bf16 v[110:113], v[134:137], v[198:201], v[110:113]
	v_mfma_f32_16x16x32_bf16 v[106:109], v[142:145], v[198:201], v[106:109]
	v_mfma_f32_16x16x32_bf16 v[106:109], v[138:141], v[194:197], v[106:109]
	v_mfma_f32_16x16x32_bf16 v[98:101], v[138:141], v[202:205], v[98:101]
	v_mfma_f32_16x16x32_bf16 v[98:101], v[142:145], v[206:209], v[98:101]
	v_mfma_f32_16x16x32_bf16 v[102:105], v[134:137], v[206:209], v[102:105]
	v_mfma_f32_16x16x32_bf16 v[102:105], v[130:133], v[202:205], v[102:105]
	s_setprio 0
	s_setprio 1
	v_mfma_f32_16x16x32_bf16 v[30:33], v[146:149], v[174:177], v[30:33]
	v_mfma_f32_16x16x32_bf16 v[30:33], v[150:153], v[178:181], v[30:33]
	v_mfma_f32_16x16x32_bf16 v[46:49], v[170:173], v[178:181], v[46:49]
	v_mfma_f32_16x16x32_bf16 v[46:49], v[154:157], v[174:177], v[46:49]
	v_mfma_f32_16x16x32_bf16 v[34:37], v[154:157], v[182:185], v[34:37]
	v_mfma_f32_16x16x32_bf16 v[34:37], v[170:173], v[186:189], v[34:37]
	v_mfma_f32_16x16x32_bf16 v[26:29], v[150:153], v[186:189], v[26:29]
	v_mfma_f32_16x16x32_bf16 v[26:29], v[146:149], v[182:185], v[26:29]
	v_mfma_f32_16x16x32_bf16 v[94:97], v[146:149], v[194:197], v[94:97]
	v_mfma_f32_16x16x32_bf16 v[94:97], v[150:153], v[198:201], v[94:97]
	v_mfma_f32_16x16x32_bf16 v[90:93], v[170:173], v[198:201], v[90:93]
	v_mfma_f32_16x16x32_bf16 v[90:93], v[154:157], v[194:197], v[90:93]
	v_mfma_f32_16x16x32_bf16 v[82:85], v[154:157], v[202:205], v[82:85]
	v_mfma_f32_16x16x32_bf16 v[82:85], v[170:173], v[206:209], v[82:85]
	v_mfma_f32_16x16x32_bf16 v[86:89], v[150:153], v[206:209], v[86:89]
	v_mfma_f32_16x16x32_bf16 v[86:89], v[146:149], v[202:205], v[86:89]
	s_setprio 0
	s_barrier
	s_add_u32 s34, s86, 0x8000
	s_addc_u32 s35, s87, 0
	s_add_i32 s88, s88, s44
	s_mov_b32 m0, s88
	ds_read_b128 v[174:177], v193 offset:49152
	ds_read_b128 v[178:181], v193 offset:50176
	ds_read_b128 v[182:185], v193 offset:51200
	ds_read_b128 v[186:189], v193 offset:52224
	ds_read_b128 v[194:197], v193 offset:53248
	ds_read_b128 v[198:201], v193 offset:54272
	ds_read_b128 v[202:205], v193 offset:55296
	ds_read_b128 v[206:209], v193 offset:56320
	global_load_lds_dwordx4 v162, s[34:35]
	s_add_i32 m0, s88, 0x2000
	v_lshl_add_u64 v[190:191], s[34:35], 0, v[158:159]
	s_add_u32 s34, s86, 0xc000
	s_addc_u32 s35, s87, 0
	s_add_i32 s86, s89, s44
	global_load_lds_dwordx4 v[190:191], off
	s_mov_b32 m0, s86
	s_nop 0
	global_load_lds_dwordx4 v162, s[34:35]
	s_add_i32 m0, s86, 0x2000
	s_nop 0
	global_load_lds_dwordx4 v158, s[34:35]
	s_mov_b32 m0, s85
	s_nop 0
	global_load_lds_dwordx4 v164, s[46:47]
	v_lshl_add_u64 v[190:191], s[46:47], 0, v[160:161]
	s_mov_b32 m0, s90
	s_nop 0
	global_load_lds_dwordx4 v[190:191], off
	s_waitcnt vmcnt(8)
	s_waitcnt lgkmcnt(0)
	s_barrier
	s_setprio 1
	v_mfma_f32_16x16x32_bf16 v[78:81], v[130:133], v[174:177], v[78:81]
	v_mfma_f32_16x16x32_bf16 v[78:81], v[134:137], v[178:181], v[78:81]
	v_mfma_f32_16x16x32_bf16 v[74:77], v[142:145], v[178:181], v[74:77]
	v_mfma_f32_16x16x32_bf16 v[74:77], v[138:141], v[174:177], v[74:77]
	v_mfma_f32_16x16x32_bf16 v[66:69], v[138:141], v[182:185], v[66:69]
	v_mfma_f32_16x16x32_bf16 v[66:69], v[142:145], v[186:189], v[66:69]
	v_mfma_f32_16x16x32_bf16 v[70:73], v[134:137], v[186:189], v[70:73]
	v_mfma_f32_16x16x32_bf16 v[70:73], v[130:133], v[182:185], v[70:73]
	v_mfma_f32_16x16x32_bf16 v[42:45], v[130:133], v[194:197], v[42:45]
	v_mfma_f32_16x16x32_bf16 v[42:45], v[134:137], v[198:201], v[42:45]
	v_mfma_f32_16x16x32_bf16 v[6:9], v[142:145], v[198:201], v[6:9]
	v_mfma_f32_16x16x32_bf16 v[6:9], v[138:141], v[194:197], v[6:9]
	v_mfma_f32_16x16x32_bf16 v[2:5], v[138:141], v[202:205], v[2:5]
	v_mfma_f32_16x16x32_bf16 v[2:5], v[142:145], v[206:209], v[2:5]
	v_mfma_f32_16x16x32_bf16 v[38:41], v[134:137], v[206:209], v[38:41]
	v_mfma_f32_16x16x32_bf16 v[38:41], v[130:133], v[202:205], v[38:41]
	s_setprio 0
	s_setprio 1
	v_mfma_f32_16x16x32_bf16 v[62:65], v[146:149], v[174:177], v[62:65]
	v_mfma_f32_16x16x32_bf16 v[62:65], v[150:153], v[178:181], v[62:65]
	v_mfma_f32_16x16x32_bf16 v[58:61], v[170:173], v[178:181], v[58:61]
	v_mfma_f32_16x16x32_bf16 v[58:61], v[154:157], v[174:177], v[58:61]
	v_mfma_f32_16x16x32_bf16 v[50:53], v[154:157], v[182:185], v[50:53]
	v_mfma_f32_16x16x32_bf16 v[50:53], v[170:173], v[186:189], v[50:53]
	v_mfma_f32_16x16x32_bf16 v[54:57], v[150:153], v[186:189], v[54:57]
	v_mfma_f32_16x16x32_bf16 v[54:57], v[146:149], v[182:185], v[54:57]
	v_mfma_f32_16x16x32_bf16 v[22:25], v[146:149], v[194:197], v[22:25]
	v_mfma_f32_16x16x32_bf16 v[22:25], v[150:153], v[198:201], v[22:25]
	v_mfma_f32_16x16x32_bf16 v[18:21], v[170:173], v[198:201], v[18:21]
	v_mfma_f32_16x16x32_bf16 v[18:21], v[154:157], v[194:197], v[18:21]
	v_mfma_f32_16x16x32_bf16 v[10:13], v[154:157], v[202:205], v[10:13]
	v_mfma_f32_16x16x32_bf16 v[10:13], v[170:173], v[206:209], v[10:13]
	v_mfma_f32_16x16x32_bf16 v[14:17], v[150:153], v[206:209], v[14:17]
	v_mfma_f32_16x16x32_bf16 v[14:17], v[146:149], v[202:205], v[14:17]
	s_setprio 0
	s_barrier
	s_add_i32 s66, s66, 2
	s_add_u32 vcc_hi, vcc_hi, 0x10000
	s_addc_u32 s65, s65, 0
	s_cmp_gt_u32 s66, 29
	s_mov_b64 s[34:35], s[36:37]
	s_cbranch_scc0 .LBB0_1256
	s_and_b64 vcc, exec, s[18:19]
	s_cbranch_vccz .LBB0_1259
	s_barrier

; #define PG8_STAGE(bufoff, gbase, voff) do { _Pragma("unroll") for (int _i = 0; _i < 2; ++_i) \
;         __builtin_amdgcn_global_load_lds((const unsigned*)((const char*)(gbase) + (voff)[_i]), (PG8_LAS unsigned*)(lds + (bufoff) + ldsw + _i * 8192), 16, 0, 0); } while (0)
; #define PG8_LDA(dst, b, h) do { _Pragma("unroll") for (int m = 0; m < 4; ++m) _Pragma("unroll") for (int k = 0; k < 2; ++k) dst[m][k] = *(const PG8_LAS bf16x8*)(lds + PG8_SA(b, h) + aoff + m * 2048 + k * 1024); } while (0)
; #define PG8_LDB(dst, b, h) do { _Pragma("unroll") for (int n = 0; n < 2; ++n) _Pragma("unroll") for (int k = 0; k < 2; ++k) dst[n][k] = *(const PG8_LAS bf16x8*)(lds + PG8_SB(b, h) + boff + n * 2048 + k * 1024); } while (0)
; #define PG8_MMA(ai, bj, At, Bt) do { __builtin_amdgcn_s_setprio(1); _Pragma("unroll") for (int m = 0; m < 4; ++m) _Pragma("unroll") for (int n = 0; n < 2; ++n) _Pragma("unroll") for (int k = 0; k < 2; ++k) \
;         acc[ai][bj][m][n] = __builtin_amdgcn_mfma_f32_16x16x32_bf16(Bt[n][k], At[m][k], acc[ai][bj][m][n], 0, 0, 0); __builtin_amdgcn_s_setprio(0); } while (0)
; #define PG8_WAIT_V(n) asm volatile("s_waitcnt vmcnt(" #n ")" ::: "memory")
; #define PG8_WAIT_L(n) asm volatile("s_waitcnt lgkmcnt(" #n ")" ::: "memory")
; #define PG8_BAR __builtin_amdgcn_s_barrier()
; #define PG8_SCHED __builtin_amdgcn_sched_barrier(0)
;     ...
;         for (int t = 0; t < nt; t += 2) {
;             const bool last = (t == nt - 2);
;             const char* a1 = cA + (ptrdiff_t)(t + 1) * kstepA;
;             const char* a2 = last ? nA : cA + (ptrdiff_t)(t + 2) * kstepA; const char* b2 = last ? nB : cB + (ptrdiff_t)(t + 2) * kstep;
;             const char* a3 = a2 + kstepA; const char* b3 = b2 + kstep;
;             if (last && has_next) S.a_ready(nxt);
;             if constexpr (SP2) {
;             PG8_LDB(B0, 0, 0); PG8_LDB(B1, 0, 1); PG8_SCHED; PG8_LDA(At, 0, 0); PG8_STAGE(PG8_SA(1, 1), a1 + hstepA, voffA);
;             PG8_WAIT_V(8); PG8_WAIT_L(0); PG8_BAR; PG8_MMA(0, 0, At, B0); PG8_MMA(0, 1, At, B1); PG8_BAR; PG8_SCHED;
;             PG8_LDA(At, 0, 1); PG8_STAGE(PG8_SB(0, 0), b2, voffB); PG8_STAGE(PG8_SB(0, 1), b2 + hstepB, voffB); PG8_STAGE(PG8_SA(0, 0), a2, voffA);
;             PG8_WAIT_V(8); PG8_WAIT_L(0); PG8_BAR; PG8_MMA(1, 0, At, B0); PG8_MMA(1, 1, At, B1); PG8_BAR; PG8_SCHED;
.Ldn_nostg:
	s_or_b32 s44, s56, 1
	s_lshl_b64 s[34:35], s[44:45], 15
	s_sub_u32 s34, 0, s34
	s_subb_u32 s35, 0, s35
	s_add_u32 s44, s28, s34
	s_addc_u32 s65, s29, s35
	s_add_u32 s34, s30, 0xffff8000
	s_addc_u32 s35, s31, -1
	s_add_i32 s66, 0, 0x10000
	v_add_u32_e32 v0, s66, v230
	s_add_i32 s90, 0, 0x14000
	s_waitcnt lgkmcnt(0)
	ds_read_b128 v[130:133], v0
	ds_read_b128 v[134:137], v0 offset:1024
	ds_read_b128 v[138:141], v0 offset:2048
	ds_read_b128 v[142:145], v0 offset:3072
	v_add_u32_e32 v0, s90, v230
	ds_read_b128 v[146:149], v0
	ds_read_b128 v[150:153], v0 offset:1024
	ds_read_b128 v[154:157], v0 offset:2048
	ds_read_b128 v[158:161], v0 offset:3072
	s_add_u32 s88, s44, 0x4000
	s_addc_u32 s89, s65, 0
	s_add_i32 m0, s46, 0xc000
	ds_read_b128 v[162:165], v231
	ds_read_b128 v[166:169], v231 offset:1024
	ds_read_b128 v[170:173], v231 offset:2048
	ds_read_b128 v[174:177], v231 offset:3072
	ds_read_b128 v[178:181], v231 offset:4096
	ds_read_b128 v[182:185], v231 offset:5120
	ds_read_b128 v[186:189], v231 offset:6144
	ds_read_b128 v[190:193], v231 offset:7168
	global_load_lds_dwordx4 v194, s[88:89]
	s_add_i32 m0, s46, 0xe000
	s_nop 0
	global_load_lds_dwordx4 v198, s[88:89]
	s_waitcnt vmcnt(8)
	s_waitcnt lgkmcnt(0)
	s_barrier
	s_setprio 1
	v_mfma_f32_16x16x32_bf16 v[126:129], v[130:133], v[162:165], 0
	v_mfma_f32_16x16x32_bf16 v[126:129], v[134:137], v[166:169], v[126:129]
	v_mfma_f32_16x16x32_bf16 v[122:125], v[142:145], v[166:169], 0
	v_mfma_f32_16x16x32_bf16 v[122:125], v[138:141], v[162:165], v[122:125]
	v_mfma_f32_16x16x32_bf16 v[106:109], v[138:141], v[170:173], 0
	v_mfma_f32_16x16x32_bf16 v[106:109], v[142:145], v[174:177], v[106:109]
	v_mfma_f32_16x16x32_bf16 v[110:113], v[134:137], v[174:177], 0
	v_mfma_f32_16x16x32_bf16 v[110:113], v[130:133], v[170:173], v[110:113]
	v_mfma_f32_16x16x32_bf16 v[94:97], v[130:133], v[178:181], 0
	v_mfma_f32_16x16x32_bf16 v[94:97], v[134:137], v[182:185], v[94:97]
	v_mfma_f32_16x16x32_bf16 v[90:93], v[142:145], v[182:185], 0
	v_mfma_f32_16x16x32_bf16 v[90:93], v[138:141], v[178:181], v[90:93]
	v_mfma_f32_16x16x32_bf16 v[74:77], v[138:141], v[186:189], 0
	v_mfma_f32_16x16x32_bf16 v[74:77], v[142:145], v[190:193], v[74:77]
	v_mfma_f32_16x16x32_bf16 v[78:81], v[134:137], v[190:193], 0
	v_mfma_f32_16x16x32_bf16 v[78:81], v[130:133], v[186:189], v[78:81]
	s_setprio 0
	s_setprio 1
	v_mfma_f32_16x16x32_bf16 v[118:121], v[146:149], v[162:165], 0
	v_mfma_f32_16x16x32_bf16 v[118:121], v[150:153], v[166:169], v[118:121]
	v_mfma_f32_16x16x32_bf16 v[114:117], v[158:161], v[166:169], 0
	v_mfma_f32_16x16x32_bf16 v[114:117], v[154:157], v[162:165], v[114:117]
	v_mfma_f32_16x16x32_bf16 v[98:101], v[154:157], v[170:173], 0
	v_mfma_f32_16x16x32_bf16 v[98:101], v[158:161], v[174:177], v[98:101]
	v_mfma_f32_16x16x32_bf16 v[102:105], v[150:153], v[174:177], 0
	v_mfma_f32_16x16x32_bf16 v[102:105], v[146:149], v[170:173], v[102:105]
	v_mfma_f32_16x16x32_bf16 v[86:89], v[146:149], v[178:181], 0
	v_mfma_f32_16x16x32_bf16 v[86:89], v[150:153], v[182:185], v[86:89]
	v_mfma_f32_16x16x32_bf16 v[82:85], v[158:161], v[182:185], 0
	v_mfma_f32_16x16x32_bf16 v[82:85], v[154:157], v[178:181], v[82:85]
	v_mfma_f32_16x16x32_bf16 v[66:69], v[154:157], v[186:189], 0
	v_mfma_f32_16x16x32_bf16 v[66:69], v[158:161], v[190:193], v[66:69]
	v_mfma_f32_16x16x32_bf16 v[70:73], v[150:153], v[190:193], 0
	v_mfma_f32_16x16x32_bf16 v[70:73], v[146:149], v[186:189], v[70:73]
	s_setprio 0
	s_barrier
	s_add_i32 s44, s66, s41
	s_mov_b32 m0, s44
	ds_read_b128 v[162:165], v231 offset:16384
	ds_read_b128 v[166:169], v231 offset:17408
	ds_read_b128 v[170:173], v231 offset:18432
	ds_read_b128 v[174:177], v231 offset:19456
	ds_read_b128 v[178:181], v231 offset:20480
	ds_read_b128 v[182:185], v231 offset:21504
	ds_read_b128 v[186:189], v231 offset:22528
	ds_read_b128 v[190:193], v231 offset:23552
	global_load_lds_dwordx4 v196, s[8:9]
	s_add_i32 m0, s44, 0x2000
	s_add_u32 s88, s8, 0x4000
	s_addc_u32 s89, s9, 0
	s_add_i32 s44, s90, s41
	global_load_lds_dwordx4 v200, s[8:9]
	s_mov_b32 m0, s44
	s_nop 0
	global_load_lds_dwordx4 v196, s[88:89]
	s_add_i32 m0, s44, 0x2000
	s_nop 0
	global_load_lds_dwordx4 v200, s[88:89]
	s_mov_b32 m0, s46
	s_nop 0
	global_load_lds_dwordx4 v194, s[30:31]
	s_mov_b32 m0, s47
	s_nop 0
	global_load_lds_dwordx4 v198, s[30:31]
	s_waitcnt vmcnt(8)
	s_waitcnt lgkmcnt(0)
	s_barrier
	s_setprio 1
	v_mfma_f32_16x16x32_bf16 v[62:65], v[130:133], v[162:165], 0
	v_mfma_f32_16x16x32_bf16 v[62:65], v[134:137], v[166:169], v[62:65]
	v_mfma_f32_16x16x32_bf16 v[58:61], v[142:145], v[166:169], 0
	v_mfma_f32_16x16x32_bf16 v[58:61], v[138:141], v[162:165], v[58:61]
	v_mfma_f32_16x16x32_bf16 v[42:45], v[138:141], v[170:173], 0
	v_mfma_f32_16x16x32_bf16 v[42:45], v[142:145], v[174:177], v[42:45]
	v_mfma_f32_16x16x32_bf16 v[46:49], v[134:137], v[174:177], 0
	v_mfma_f32_16x16x32_bf16 v[46:49], v[130:133], v[170:173], v[46:49]
	v_mfma_f32_16x16x32_bf16 v[30:33], v[130:133], v[178:181], 0
	v_mfma_f32_16x16x32_bf16 v[30:33], v[134:137], v[182:185], v[30:33]
	v_mfma_f32_16x16x32_bf16 v[26:29], v[142:145], v[182:185], 0
	v_mfma_f32_16x16x32_bf16 v[26:29], v[138:141], v[178:181], v[26:29]
	v_mfma_f32_16x16x32_bf16 v[10:13], v[138:141], v[186:189], 0
	v_mfma_f32_16x16x32_bf16 v[10:13], v[142:145], v[190:193], v[10:13]
	v_mfma_f32_16x16x32_bf16 v[14:17], v[134:137], v[190:193], 0
	v_mfma_f32_16x16x32_bf16 v[14:17], v[130:133], v[186:189], v[14:17]
	s_setprio 0
	s_setprio 1
	v_mfma_f32_16x16x32_bf16 v[54:57], v[146:149], v[162:165], 0
	v_mfma_f32_16x16x32_bf16 v[54:57], v[150:153], v[166:169], v[54:57]
	v_mfma_f32_16x16x32_bf16 v[50:53], v[158:161], v[166:169], 0
	v_mfma_f32_16x16x32_bf16 v[50:53], v[154:157], v[162:165], v[50:53]
	v_mfma_f32_16x16x32_bf16 v[34:37], v[154:157], v[170:173], 0
	v_mfma_f32_16x16x32_bf16 v[34:37], v[158:161], v[174:177], v[34:37]
	v_mfma_f32_16x16x32_bf16 v[38:41], v[150:153], v[174:177], 0
	v_mfma_f32_16x16x32_bf16 v[38:41], v[146:149], v[170:173], v[38:41]
	v_mfma_f32_16x16x32_bf16 v[22:25], v[146:149], v[178:181], 0
	v_mfma_f32_16x16x32_bf16 v[22:25], v[150:153], v[182:185], v[22:25]
	v_mfma_f32_16x16x32_bf16 v[18:21], v[158:161], v[182:185], 0
	v_mfma_f32_16x16x32_bf16 v[18:21], v[154:157], v[178:181], v[18:21]
	v_mfma_f32_16x16x32_bf16 v[2:5], v[154:157], v[186:189], 0
	v_mfma_f32_16x16x32_bf16 v[2:5], v[158:161], v[190:193], v[2:5]
	v_mfma_f32_16x16x32_bf16 v[6:9], v[150:153], v[190:193], 0
	v_mfma_f32_16x16x32_bf16 v[6:9], v[146:149], v[186:189], v[6:9]
	s_setprio 0
	s_barrier
	s_branch .Ldn_mid

; #define PG8_STAGE(bufoff, gbase, voff) do { _Pragma("unroll") for (int _i = 0; _i < 2; ++_i) \
;         __builtin_amdgcn_global_load_lds((const unsigned*)((const char*)(gbase) + (voff)[_i]), (PG8_LAS unsigned*)(lds + (bufoff) + ldsw + _i * 8192), 16, 0, 0); } while (0)
; #define PG8_LDA(dst, b, h) do { _Pragma("unroll") for (int m = 0; m < 4; ++m) _Pragma("unroll") for (int k = 0; k < 2; ++k) dst[m][k] = *(const PG8_LAS bf16x8*)(lds + PG8_SA(b, h) + aoff + m * 2048 + k * 1024); } while (0)
; #define PG8_LDB(dst, b, h) do { _Pragma("unroll") for (int n = 0; n < 2; ++n) _Pragma("unroll") for (int k = 0; k < 2; ++k) dst[n][k] = *(const PG8_LAS bf16x8*)(lds + PG8_SB(b, h) + boff + n * 2048 + k * 1024); } while (0)
; #define PG8_MMA(ai, bj, At, Bt) do { __builtin_amdgcn_s_setprio(1); _Pragma("unroll") for (int m = 0; m < 4; ++m) _Pragma("unroll") for (int n = 0; n < 2; ++n) _Pragma("unroll") for (int k = 0; k < 2; ++k) \
;         acc[ai][bj][m][n] = __builtin_amdgcn_mfma_f32_16x16x32_bf16(Bt[n][k], At[m][k], acc[ai][bj][m][n], 0, 0, 0); __builtin_amdgcn_s_setprio(0); } while (0)
; #define PG8_WAIT_V(n) asm volatile("s_waitcnt vmcnt(" #n ")" ::: "memory")
; #define PG8_WAIT_L(n) asm volatile("s_waitcnt lgkmcnt(" #n ")" ::: "memory")
; #define PG8_BAR __builtin_amdgcn_s_barrier()
; #define PG8_SCHED __builtin_amdgcn_sched_barrier(0)
;     ...
;         for (int t = 0; t < nt; t += 2) {
;             const bool last = (t == nt - 2);
;             const char* a1 = cA + (ptrdiff_t)(t + 1) * kstepA;
;             const char* a2 = last ? nA : cA + (ptrdiff_t)(t + 2) * kstepA; const char* b2 = last ? nB : cB + (ptrdiff_t)(t + 2) * kstep;
;             const char* a3 = a2 + kstepA; const char* b3 = b2 + kstep;
;             if (last && has_next) S.a_ready(nxt);
;             if constexpr (SP2) {
;             PG8_LDB(B0, 0, 0); PG8_LDB(B1, 0, 1); PG8_SCHED; PG8_LDA(At, 0, 0); PG8_STAGE(PG8_SA(1, 1), a1 + hstepA, voffA);
;             PG8_WAIT_V(8); PG8_WAIT_L(0); PG8_BAR; PG8_MMA(0, 0, At, B0); PG8_MMA(0, 1, At, B1); PG8_BAR; PG8_SCHED;
;             PG8_LDA(At, 0, 1); PG8_STAGE(PG8_SB(0, 0), b2, voffB); PG8_STAGE(PG8_SB(0, 1), b2 + hstepB, voffB); PG8_STAGE(PG8_SA(0, 0), a2, voffA);
;             PG8_WAIT_V(8); PG8_WAIT_L(0); PG8_BAR; PG8_MMA(1, 0, At, B0); PG8_MMA(1, 1, At, B1); PG8_BAR; PG8_SCHED;
.LBB0_1444:
	s_or_b32 s44, s56, 1
	s_lshl_b64 s[34:35], s[44:45], 15
	s_sub_u32 s34, 0, s34
	s_subb_u32 s35, 0, s35
	s_add_u32 s44, s28, s34
	s_addc_u32 s65, s29, s35
	s_add_u32 s34, s30, 0xffff8000
	s_addc_u32 s35, s31, -1
	s_add_i32 s66, 0, 0x10000
	v_add_u32_e32 v0, s66, v230
	s_add_i32 s90, 0, 0x14000
	s_waitcnt lgkmcnt(0)
	ds_read_b128 v[130:133], v0
	ds_read_b128 v[134:137], v0 offset:1024
	ds_read_b128 v[138:141], v0 offset:2048
	ds_read_b128 v[142:145], v0 offset:3072
	v_add_u32_e32 v0, s90, v230
	ds_read_b128 v[146:149], v0
	ds_read_b128 v[150:153], v0 offset:1024
	ds_read_b128 v[154:157], v0 offset:2048
	ds_read_b128 v[158:161], v0 offset:3072
	s_add_u32 s88, s44, 0x4000
	s_addc_u32 s89, s65, 0
	s_add_i32 m0, s46, 0xc000
	ds_read_b128 v[162:165], v231
	ds_read_b128 v[166:169], v231 offset:1024
	ds_read_b128 v[170:173], v231 offset:2048
	ds_read_b128 v[174:177], v231 offset:3072
	ds_read_b128 v[178:181], v231 offset:4096
	ds_read_b128 v[182:185], v231 offset:5120
	ds_read_b128 v[186:189], v231 offset:6144
	ds_read_b128 v[190:193], v231 offset:7168
	global_load_lds_dwordx4 v194, s[88:89]
	s_add_i32 m0, s46, 0xe000
	s_nop 0
	global_load_lds_dwordx4 v198, s[88:89]
	s_waitcnt vmcnt(8)
	s_waitcnt lgkmcnt(0)
	s_barrier
	s_setprio 1
	v_mfma_f32_16x16x32_bf16 v[126:129], v[130:133], v[162:165], v[126:129]
	v_mfma_f32_16x16x32_bf16 v[126:129], v[134:137], v[166:169], v[126:129]
	v_mfma_f32_16x16x32_bf16 v[122:125], v[142:145], v[166:169], v[122:125]
	v_mfma_f32_16x16x32_bf16 v[122:125], v[138:141], v[162:165], v[122:125]
	v_mfma_f32_16x16x32_bf16 v[106:109], v[138:141], v[170:173], v[106:109]
	v_mfma_f32_16x16x32_bf16 v[106:109], v[142:145], v[174:177], v[106:109]
	v_mfma_f32_16x16x32_bf16 v[110:113], v[134:137], v[174:177], v[110:113]
	v_mfma_f32_16x16x32_bf16 v[110:113], v[130:133], v[170:173], v[110:113]
	v_mfma_f32_16x16x32_bf16 v[94:97], v[130:133], v[178:181], v[94:97]
	v_mfma_f32_16x16x32_bf16 v[94:97], v[134:137], v[182:185], v[94:97]
	v_mfma_f32_16x16x32_bf16 v[90:93], v[142:145], v[182:185], v[90:93]
	v_mfma_f32_16x16x32_bf16 v[90:93], v[138:141], v[178:181], v[90:93]
	v_mfma_f32_16x16x32_bf16 v[74:77], v[138:141], v[186:189], v[74:77]
	v_mfma_f32_16x16x32_bf16 v[74:77], v[142:145], v[190:193], v[74:77]
	v_mfma_f32_16x16x32_bf16 v[78:81], v[134:137], v[190:193], v[78:81]
	v_mfma_f32_16x16x32_bf16 v[78:81], v[130:133], v[186:189], v[78:81]
	s_setprio 0
	s_setprio 1
	v_mfma_f32_16x16x32_bf16 v[118:121], v[146:149], v[162:165], v[118:121]
	v_mfma_f32_16x16x32_bf16 v[118:121], v[150:153], v[166:169], v[118:121]
	v_mfma_f32_16x16x32_bf16 v[114:117], v[158:161], v[166:169], v[114:117]
	v_mfma_f32_16x16x32_bf16 v[114:117], v[154:157], v[162:165], v[114:117]
	v_mfma_f32_16x16x32_bf16 v[98:101], v[154:157], v[170:173], v[98:101]
	v_mfma_f32_16x16x32_bf16 v[98:101], v[158:161], v[174:177], v[98:101]
	v_mfma_f32_16x16x32_bf16 v[102:105], v[150:153], v[174:177], v[102:105]
	v_mfma_f32_16x16x32_bf16 v[102:105], v[146:149], v[170:173], v[102:105]
	v_mfma_f32_16x16x32_bf16 v[86:89], v[146:149], v[178:181], v[86:89]
	v_mfma_f32_16x16x32_bf16 v[86:89], v[150:153], v[182:185], v[86:89]
	v_mfma_f32_16x16x32_bf16 v[82:85], v[158:161], v[182:185], v[82:85]
	v_mfma_f32_16x16x32_bf16 v[82:85], v[154:157], v[178:181], v[82:85]
	v_mfma_f32_16x16x32_bf16 v[66:69], v[154:157], v[186:189], v[66:69]
	v_mfma_f32_16x16x32_bf16 v[66:69], v[158:161], v[190:193], v[66:69]
	v_mfma_f32_16x16x32_bf16 v[70:73], v[150:153], v[190:193], v[70:73]
	v_mfma_f32_16x16x32_bf16 v[70:73], v[146:149], v[186:189], v[70:73]
	s_setprio 0
	s_barrier
	s_add_i32 s44, s66, s41
	s_mov_b32 m0, s44
	ds_read_b128 v[162:165], v231 offset:16384
	ds_read_b128 v[166:169], v231 offset:17408
	ds_read_b128 v[170:173], v231 offset:18432
	ds_read_b128 v[174:177], v231 offset:19456
	ds_read_b128 v[178:181], v231 offset:20480
	ds_read_b128 v[182:185], v231 offset:21504
	ds_read_b128 v[186:189], v231 offset:22528
	ds_read_b128 v[190:193], v231 offset:23552
	global_load_lds_dwordx4 v196, s[8:9]
	s_add_i32 m0, s44, 0x2000
	s_add_u32 s88, s8, 0x4000
	s_addc_u32 s89, s9, 0
	s_add_i32 s44, s90, s41
	global_load_lds_dwordx4 v200, s[8:9]
	s_mov_b32 m0, s44
	s_nop 0
	global_load_lds_dwordx4 v196, s[88:89]
	s_add_i32 m0, s44, 0x2000
	s_nop 0
	global_load_lds_dwordx4 v200, s[88:89]
	s_mov_b32 m0, s46
	s_nop 0
	global_load_lds_dwordx4 v194, s[30:31]
	s_mov_b32 m0, s47
	s_nop 0
	global_load_lds_dwordx4 v198, s[30:31]
	s_waitcnt vmcnt(8)
	s_waitcnt lgkmcnt(0)
	s_barrier
	s_setprio 1
	v_mfma_f32_16x16x32_bf16 v[62:65], v[130:133], v[162:165], v[62:65]
	v_mfma_f32_16x16x32_bf16 v[62:65], v[134:137], v[166:169], v[62:65]
	v_mfma_f32_16x16x32_bf16 v[58:61], v[142:145], v[166:169], v[58:61]
	v_mfma_f32_16x16x32_bf16 v[58:61], v[138:141], v[162:165], v[58:61]
	v_mfma_f32_16x16x32_bf16 v[42:45], v[138:141], v[170:173], v[42:45]
	v_mfma_f32_16x16x32_bf16 v[42:45], v[142:145], v[174:177], v[42:45]
	v_mfma_f32_16x16x32_bf16 v[46:49], v[134:137], v[174:177], v[46:49]
	v_mfma_f32_16x16x32_bf16 v[46:49], v[130:133], v[170:173], v[46:49]
	v_mfma_f32_16x16x32_bf16 v[30:33], v[130:133], v[178:181], v[30:33]
	v_mfma_f32_16x16x32_bf16 v[30:33], v[134:137], v[182:185], v[30:33]
	v_mfma_f32_16x16x32_bf16 v[26:29], v[142:145], v[182:185], v[26:29]
	v_mfma_f32_16x16x32_bf16 v[26:29], v[138:141], v[178:181], v[26:29]
	v_mfma_f32_16x16x32_bf16 v[10:13], v[138:141], v[186:189], v[10:13]
	v_mfma_f32_16x16x32_bf16 v[10:13], v[142:145], v[190:193], v[10:13]
	v_mfma_f32_16x16x32_bf16 v[14:17], v[134:137], v[190:193], v[14:17]
	v_mfma_f32_16x16x32_bf16 v[14:17], v[130:133], v[186:189], v[14:17]
	s_setprio 0
	s_setprio 1
	v_mfma_f32_16x16x32_bf16 v[54:57], v[146:149], v[162:165], v[54:57]
	v_mfma_f32_16x16x32_bf16 v[54:57], v[150:153], v[166:169], v[54:57]
	v_mfma_f32_16x16x32_bf16 v[50:53], v[158:161], v[166:169], v[50:53]
	v_mfma_f32_16x16x32_bf16 v[50:53], v[154:157], v[162:165], v[50:53]
	v_mfma_f32_16x16x32_bf16 v[34:37], v[154:157], v[170:173], v[34:37]
	v_mfma_f32_16x16x32_bf16 v[34:37], v[158:161], v[174:177], v[34:37]
	v_mfma_f32_16x16x32_bf16 v[38:41], v[150:153], v[174:177], v[38:41]
	v_mfma_f32_16x16x32_bf16 v[38:41], v[146:149], v[170:173], v[38:41]
	v_mfma_f32_16x16x32_bf16 v[22:25], v[146:149], v[178:181], v[22:25]
	v_mfma_f32_16x16x32_bf16 v[22:25], v[150:153], v[182:185], v[22:25]
	v_mfma_f32_16x16x32_bf16 v[18:21], v[158:161], v[182:185], v[18:21]
	v_mfma_f32_16x16x32_bf16 v[18:21], v[154:157], v[178:181], v[18:21]
	v_mfma_f32_16x16x32_bf16 v[2:5], v[154:157], v[186:189], v[2:5]
	v_mfma_f32_16x16x32_bf16 v[2:5], v[158:161], v[190:193], v[2:5]
	v_mfma_f32_16x16x32_bf16 v[6:9], v[150:153], v[190:193], v[6:9]
	v_mfma_f32_16x16x32_bf16 v[6:9], v[146:149], v[186:189], v[6:9]
	s_setprio 0
	s_barrier
; #define PG8_STAGE(bufoff, gbase, voff) do { _Pragma("unroll") for (int _i = 0; _i < 2; ++_i) \
;         __builtin_amdgcn_global_load_lds((const unsigned*)((const char*)(gbase) + (voff)[_i]), (PG8_LAS unsigned*)(lds + (bufoff) + ldsw + _i * 8192), 16, 0, 0); } while (0)
; #define PG8_LDA(dst, b, h) do { _Pragma("unroll") for (int m = 0; m < 4; ++m) _Pragma("unroll") for (int k = 0; k < 2; ++k) dst[m][k] = *(const PG8_LAS bf16x8*)(lds + PG8_SA(b, h) + aoff + m * 2048 + k * 1024); } while (0)
; #define PG8_LDB(dst, b, h) do { _Pragma("unroll") for (int n = 0; n < 2; ++n) _Pragma("unroll") for (int k = 0; k < 2; ++k) dst[n][k] = *(const PG8_LAS bf16x8*)(lds + PG8_SB(b, h) + boff + n * 2048 + k * 1024); } while (0)
; #define PG8_MMA(ai, bj, At, Bt) do { __builtin_amdgcn_s_setprio(1); _Pragma("unroll") for (int m = 0; m < 4; ++m) _Pragma("unroll") for (int n = 0; n < 2; ++n) _Pragma("unroll") for (int k = 0; k < 2; ++k) \
;         acc[ai][bj][m][n] = __builtin_amdgcn_mfma_f32_16x16x32_bf16(Bt[n][k], At[m][k], acc[ai][bj][m][n], 0, 0, 0); __builtin_amdgcn_s_setprio(0); } while (0)
; #define PG8_WAIT_V(n) asm volatile("s_waitcnt vmcnt(" #n ")" ::: "memory")
; #define PG8_WAIT_L(n) asm volatile("s_waitcnt lgkmcnt(" #n ")" ::: "memory")
; #define PG8_BAR __builtin_amdgcn_s_barrier()
; #define PG8_SCHED __builtin_amdgcn_sched_barrier(0)
;     ...
;             PG8_LDB(B0, 1, 0); PG8_LDB(B1, 1, 1); PG8_SCHED; PG8_LDA(At, 1, 0); PG8_STAGE(PG8_SA(0, 1), a2 + hstepA, voffA);
;             PG8_WAIT_V(8); PG8_WAIT_L(0); PG8_BAR; PG8_MMA(0, 0, At, B0); PG8_MMA(0, 1, At, B1); PG8_BAR; PG8_SCHED;
;             PG8_LDA(At, 1, 1); PG8_STAGE(PG8_SB(1, 0), b3, voffB); PG8_STAGE(PG8_SB(1, 1), b3 + hstepB, voffB); PG8_STAGE(PG8_SA(1, 0), a3, voffA);
;             PG8_WAIT_V(8); PG8_WAIT_L(0); PG8_BAR; PG8_MMA(1, 0, At, B0); PG8_MMA(1, 1, At, B1); PG8_BAR; PG8_SCHED;
.Ldn_mid:
	s_add_i32 s44, 0, 0x18000
	v_add_u32_e32 v0, s44, v230
	s_add_i32 s65, 0, 0x1c000
	ds_read_b128 v[130:133], v0
	ds_read_b128 v[134:137], v0 offset:1024
	ds_read_b128 v[138:141], v0 offset:2048
	ds_read_b128 v[142:145], v0 offset:3072
	v_add_u32_e32 v0, s65, v230
	ds_read_b128 v[146:149], v0
	ds_read_b128 v[150:153], v0 offset:1024
	ds_read_b128 v[154:157], v0 offset:2048
	ds_read_b128 v[158:161], v0 offset:3072
	s_add_u32 s30, s30, 0x4000
	s_addc_u32 s31, s31, 0
	s_mov_b32 m0, s48
	ds_read_b128 v[162:165], v231 offset:32768
	ds_read_b128 v[166:169], v231 offset:33792
	ds_read_b128 v[170:173], v231 offset:34816
	ds_read_b128 v[174:177], v231 offset:35840
	ds_read_b128 v[178:181], v231 offset:36864
	ds_read_b128 v[182:185], v231 offset:37888
	ds_read_b128 v[186:189], v231 offset:38912
	ds_read_b128 v[190:193], v231 offset:39936
	global_load_lds_dwordx4 v194, s[30:31]
	s_mov_b32 m0, s49
	s_nop 0
	global_load_lds_dwordx4 v198, s[30:31]
	s_waitcnt vmcnt(8)
	s_waitcnt lgkmcnt(0)
	s_barrier
	s_setprio 1
	v_mfma_f32_16x16x32_bf16 v[126:129], v[130:133], v[162:165], v[126:129]
	v_mfma_f32_16x16x32_bf16 v[126:129], v[134:137], v[166:169], v[126:129]
	v_mfma_f32_16x16x32_bf16 v[122:125], v[142:145], v[166:169], v[122:125]
	v_mfma_f32_16x16x32_bf16 v[122:125], v[138:141], v[162:165], v[122:125]
	v_mfma_f32_16x16x32_bf16 v[106:109], v[138:141], v[170:173], v[106:109]
	v_mfma_f32_16x16x32_bf16 v[106:109], v[142:145], v[174:177], v[106:109]
	v_mfma_f32_16x16x32_bf16 v[110:113], v[134:137], v[174:177], v[110:113]
	v_mfma_f32_16x16x32_bf16 v[110:113], v[130:133], v[170:173], v[110:113]
	v_mfma_f32_16x16x32_bf16 v[94:97], v[130:133], v[178:181], v[94:97]
	v_mfma_f32_16x16x32_bf16 v[94:97], v[134:137], v[182:185], v[94:97]
	v_mfma_f32_16x16x32_bf16 v[90:93], v[142:145], v[182:185], v[90:93]
	v_mfma_f32_16x16x32_bf16 v[90:93], v[138:141], v[178:181], v[90:93]
	v_mfma_f32_16x16x32_bf16 v[74:77], v[138:141], v[186:189], v[74:77]
	v_mfma_f32_16x16x32_bf16 v[74:77], v[142:145], v[190:193], v[74:77]
	v_mfma_f32_16x16x32_bf16 v[78:81], v[134:137], v[190:193], v[78:81]
	v_mfma_f32_16x16x32_bf16 v[78:81], v[130:133], v[186:189], v[78:81]
	s_setprio 0
	s_setprio 1
	v_mfma_f32_16x16x32_bf16 v[118:121], v[146:149], v[162:165], v[118:121]
	v_mfma_f32_16x16x32_bf16 v[118:121], v[150:153], v[166:169], v[118:121]
	v_mfma_f32_16x16x32_bf16 v[114:117], v[158:161], v[166:169], v[114:117]
	v_mfma_f32_16x16x32_bf16 v[114:117], v[154:157], v[162:165], v[114:117]
	v_mfma_f32_16x16x32_bf16 v[98:101], v[154:157], v[170:173], v[98:101]
	v_mfma_f32_16x16x32_bf16 v[98:101], v[158:161], v[174:177], v[98:101]
	v_mfma_f32_16x16x32_bf16 v[102:105], v[150:153], v[174:177], v[102:105]
	v_mfma_f32_16x16x32_bf16 v[102:105], v[146:149], v[170:173], v[102:105]
	v_mfma_f32_16x16x32_bf16 v[86:89], v[146:149], v[178:181], v[86:89]
	v_mfma_f32_16x16x32_bf16 v[86:89], v[150:153], v[182:185], v[86:89]
	v_mfma_f32_16x16x32_bf16 v[82:85], v[158:161], v[182:185], v[82:85]
	v_mfma_f32_16x16x32_bf16 v[82:85], v[154:157], v[178:181], v[82:85]
	v_mfma_f32_16x16x32_bf16 v[66:69], v[154:157], v[186:189], v[66:69]
	v_mfma_f32_16x16x32_bf16 v[66:69], v[158:161], v[190:193], v[66:69]
	v_mfma_f32_16x16x32_bf16 v[70:73], v[150:153], v[190:193], v[70:73]
	v_mfma_f32_16x16x32_bf16 v[70:73], v[146:149], v[186:189], v[70:73]
	s_setprio 0
	s_barrier
	s_add_u32 s30, s8, 0xffff8000
	s_addc_u32 s31, s9, -1
	s_add_i32 s44, s44, s41
	s_mov_b32 m0, s44
	ds_read_b128 v[162:165], v231 offset:49152
	ds_read_b128 v[166:169], v231 offset:50176
	ds_read_b128 v[170:173], v231 offset:51200
	ds_read_b128 v[174:177], v231 offset:52224
	ds_read_b128 v[178:181], v231 offset:53248
	ds_read_b128 v[182:185], v231 offset:54272
	ds_read_b128 v[186:189], v231 offset:55296
	ds_read_b128 v[190:193], v231 offset:56320
	global_load_lds_dwordx4 v196, s[30:31]
	s_add_i32 m0, s44, 0x2000
	s_add_u32 s8, s8, 0xffffc000
	v_lshl_add_u64 v[202:203], s[30:31], 0, v[200:201]
	s_addc_u32 s9, s9, -1
	s_add_i32 s30, s65, s41
	global_load_lds_dwordx4 v[202:203], off
	s_mov_b32 m0, s30
	s_nop 0
	global_load_lds_dwordx4 v196, s[8:9]
	s_add_i32 m0, s30, 0x2000
	s_nop 0
	global_load_lds_dwordx4 v200, s[8:9]
	s_mov_b32 m0, s71
	s_nop 0
	global_load_lds_dwordx4 v194, s[34:35]
	v_lshl_add_u64 v[202:203], s[34:35], 0, v[198:199]
	s_mov_b32 m0, s80
	s_nop 0
	global_load_lds_dwordx4 v[202:203], off
	s_waitcnt vmcnt(8)
	s_waitcnt lgkmcnt(0)
	s_barrier
	s_setprio 1
	v_mfma_f32_16x16x32_bf16 v[62:65], v[130:133], v[162:165], v[62:65]
	v_mfma_f32_16x16x32_bf16 v[62:65], v[134:137], v[166:169], v[62:65]
	v_mfma_f32_16x16x32_bf16 v[58:61], v[142:145], v[166:169], v[58:61]
	v_mfma_f32_16x16x32_bf16 v[58:61], v[138:141], v[162:165], v[58:61]
	v_mfma_f32_16x16x32_bf16 v[42:45], v[138:141], v[170:173], v[42:45]
	v_mfma_f32_16x16x32_bf16 v[42:45], v[142:145], v[174:177], v[42:45]
	v_mfma_f32_16x16x32_bf16 v[46:49], v[134:137], v[174:177], v[46:49]
	v_mfma_f32_16x16x32_bf16 v[46:49], v[130:133], v[170:173], v[46:49]
	v_mfma_f32_16x16x32_bf16 v[30:33], v[130:133], v[178:181], v[30:33]
	v_mfma_f32_16x16x32_bf16 v[30:33], v[134:137], v[182:185], v[30:33]
	v_mfma_f32_16x16x32_bf16 v[26:29], v[142:145], v[182:185], v[26:29]
	v_mfma_f32_16x16x32_bf16 v[26:29], v[138:141], v[178:181], v[26:29]
	v_mfma_f32_16x16x32_bf16 v[10:13], v[138:141], v[186:189], v[10:13]
	v_mfma_f32_16x16x32_bf16 v[10:13], v[142:145], v[190:193], v[10:13]
	v_mfma_f32_16x16x32_bf16 v[14:17], v[134:137], v[190:193], v[14:17]
	v_mfma_f32_16x16x32_bf16 v[14:17], v[130:133], v[186:189], v[14:17]
	s_setprio 0
	s_setprio 1
	v_mfma_f32_16x16x32_bf16 v[54:57], v[146:149], v[162:165], v[54:57]
	v_mfma_f32_16x16x32_bf16 v[54:57], v[150:153], v[166:169], v[54:57]
	v_mfma_f32_16x16x32_bf16 v[50:53], v[158:161], v[166:169], v[50:53]
	v_mfma_f32_16x16x32_bf16 v[50:53], v[154:157], v[162:165], v[50:53]
	v_mfma_f32_16x16x32_bf16 v[34:37], v[154:157], v[170:173], v[34:37]
	v_mfma_f32_16x16x32_bf16 v[34:37], v[158:161], v[174:177], v[34:37]
	v_mfma_f32_16x16x32_bf16 v[38:41], v[150:153], v[174:177], v[38:41]
	v_mfma_f32_16x16x32_bf16 v[38:41], v[146:149], v[170:173], v[38:41]
	v_mfma_f32_16x16x32_bf16 v[22:25], v[146:149], v[178:181], v[22:25]
	v_mfma_f32_16x16x32_bf16 v[22:25], v[150:153], v[182:185], v[22:25]
	v_mfma_f32_16x16x32_bf16 v[18:21], v[158:161], v[182:185], v[18:21]
	v_mfma_f32_16x16x32_bf16 v[18:21], v[154:157], v[178:181], v[18:21]
	v_mfma_f32_16x16x32_bf16 v[2:5], v[154:157], v[186:189], v[2:5]
	v_mfma_f32_16x16x32_bf16 v[2:5], v[158:161], v[190:193], v[2:5]
	v_mfma_f32_16x16x32_bf16 v[6:9], v[150:153], v[190:193], v[6:9]
	v_mfma_f32_16x16x32_bf16 v[6:9], v[146:149], v[186:189], v[6:9]
	s_setprio 0
	s_barrier
	s_cmpk_gt_u32 s56, 0x55
	s_mov_b32 s56, s57
	s_cbranch_scc1 .LBB0_1449
